# GEMM K-loops: all 176 per-segment s_setprio flips removed (one static priority through the loops)
# speedup vs baseline: 1.0070x; 1.0070x over previous
; #define PG8_STAGE(bufoff, gbase, voff) do { _Pragma("unroll") for (int _i = 0; _i < 2; ++_i) \
;         __builtin_amdgcn_global_load_lds((const unsigned*)((const char*)(gbase) + (voff)[_i]), (PG8_LAS unsigned*)(lds + (bufoff) + ldsw + _i * 8192), 16, 0, 0); } while (0)
; #define PG8_LDA(dst, b, h) do { _Pragma("unroll") for (int m = 0; m < 4; ++m) _Pragma("unroll") for (int k = 0; k < 2; ++k) dst[m][k] = *(const PG8_LAS bf16x8*)(lds + PG8_SA(b, h) + aoff + m * 2048 + k * 1024); } while (0)
; #define PG8_LDB(dst, b, h) do { _Pragma("unroll") for (int n = 0; n < 2; ++n) _Pragma("unroll") for (int k = 0; k < 2; ++k) dst[n][k] = *(const PG8_LAS bf16x8*)(lds + PG8_SB(b, h) + boff + n * 2048 + k * 1024); } while (0)
; #define PG8_MMA(ai, bj, At, Bt) do { __builtin_amdgcn_s_setprio(1); _Pragma("unroll") for (int m = 0; m < 4; ++m) _Pragma("unroll") for (int n = 0; n < 2; ++n) _Pragma("unroll") for (int k = 0; k < 2; ++k) \
;         acc[ai][bj][m][n] = __builtin_amdgcn_mfma_f32_16x16x32_bf16(Bt[n][k], At[m][k], acc[ai][bj][m][n], 0, 0, 0); __builtin_amdgcn_s_setprio(0); } while (0)
; #define PG8_WAIT_V(n) asm volatile("s_waitcnt vmcnt(" #n ")" ::: "memory")
; #define PG8_WAIT_L(n) asm volatile("s_waitcnt lgkmcnt(" #n ")" ::: "memory")
; #define PG8_BAR __builtin_amdgcn_s_barrier()
; #define PG8_SCHED __builtin_amdgcn_sched_barrier(0)
; template <class Epi, class Sched, bool ALIGN_EPI = false, bool SP2 = false>
; __device__ __forceinline__ void gemm_phase(PG8_LAS unsigned char* lds, const Gemm g, const Sched& S, const Epi& E) {
;     ...
;             PG8_LDB(B0, 0, 0); PG8_LDB(B1, 0, 1); PG8_SCHED; PG8_LDA(At, 0, 0); PG8_STAGE(PG8_SA(1, 1), a1 + hstepA, voffA);
;             PG8_WAIT_V(8); PG8_WAIT_L(0); PG8_BAR; PG8_MMA(0, 0, At, B0); PG8_MMA(0, 1, At, B1); PG8_BAR; PG8_SCHED;
;             PG8_LDA(At, 0, 1); PG8_STAGE(PG8_SB(0, 0), b2, voffB); PG8_STAGE(PG8_SB(0, 1), b2 + hstepB, voffB); PG8_STAGE(PG8_SA(0, 0), a2, voffA);
;             PG8_WAIT_V(8); PG8_WAIT_L(0); PG8_BAR; PG8_MMA(1, 0, At, B0); PG8_MMA(1, 1, At, B1); PG8_BAR; PG8_SCHED;
.LBB0_318:
	ds_read_b128 v[156:159], v153
	ds_read_b128 v[160:163], v153 offset:1024
	ds_read_b128 v[164:167], v153 offset:2048
	ds_read_b128 v[168:171], v153 offset:3072
	ds_read_b128 v[172:175], v154
	ds_read_b128 v[176:179], v154 offset:1024
	ds_read_b128 v[180:183], v154 offset:2048
	ds_read_b128 v[184:187], v154 offset:3072
	s_add_u32 s8, s6, 0xfffc0080
	s_addc_u32 s9, s7, -1
	s_cmp_eq_u32 s36, 12
	s_cselect_b32 s31, s1, s9
	s_cselect_b32 s30, s5, s8
	s_cselect_b32 s9, s23, s35
	s_cselect_b32 s8, s25, s34
	s_add_i32 m0, s42, 0xc000
	ds_read_b128 v[188:191], v155
	ds_read_b128 v[192:195], v155 offset:1024
	ds_read_b128 v[196:199], v155 offset:2048
	ds_read_b128 v[200:203], v155 offset:3072
	ds_read_b128 v[204:207], v155 offset:4096
	ds_read_b128 v[208:211], v155 offset:5120
	ds_read_b128 v[212:215], v155 offset:6144
	ds_read_b128 v[216:219], v155 offset:7168
	global_load_lds_dwordx4 v140, s[6:7]
	s_add_i32 m0, s42, 0xe000
	s_nop 0
	global_load_lds_dwordx4 v142, s[6:7]
	s_waitcnt vmcnt(8)
	s_waitcnt lgkmcnt(0)
	s_barrier
	s_waitcnt lgkmcnt(0)
	v_mfma_f32_16x16x32_bf16 v[126:129], v[156:159], v[188:191], v[126:129]
	v_mfma_f32_16x16x32_bf16 v[122:125], v[164:167], v[188:191], v[122:125]
	v_mfma_f32_16x16x32_bf16 v[110:113], v[156:159], v[196:199], v[110:113]
	v_mfma_f32_16x16x32_bf16 v[106:109], v[164:167], v[196:199], v[106:109]
	v_mfma_f32_16x16x32_bf16 v[94:97], v[156:159], v[204:207], v[94:97]
	v_mfma_f32_16x16x32_bf16 v[90:93], v[164:167], v[204:207], v[90:93]
	v_mfma_f32_16x16x32_bf16 v[78:81], v[156:159], v[212:215], v[78:81]
	v_mfma_f32_16x16x32_bf16 v[74:77], v[164:167], v[212:215], v[74:77]
	v_mfma_f32_16x16x32_bf16 v[126:129], v[160:163], v[192:195], v[126:129]
	v_mfma_f32_16x16x32_bf16 v[122:125], v[168:171], v[192:195], v[122:125]
	v_mfma_f32_16x16x32_bf16 v[110:113], v[160:163], v[200:203], v[110:113]
	v_mfma_f32_16x16x32_bf16 v[106:109], v[168:171], v[200:203], v[106:109]
	v_mfma_f32_16x16x32_bf16 v[94:97], v[160:163], v[208:211], v[94:97]
	v_mfma_f32_16x16x32_bf16 v[90:93], v[168:171], v[208:211], v[90:93]
	v_mfma_f32_16x16x32_bf16 v[78:81], v[160:163], v[216:219], v[78:81]
	v_mfma_f32_16x16x32_bf16 v[74:77], v[168:171], v[216:219], v[74:77]
	v_mfma_f32_16x16x32_bf16 v[118:121], v[172:175], v[188:191], v[118:121]
	v_mfma_f32_16x16x32_bf16 v[114:117], v[180:183], v[188:191], v[114:117]
	v_mfma_f32_16x16x32_bf16 v[102:105], v[172:175], v[196:199], v[102:105]
	v_mfma_f32_16x16x32_bf16 v[98:101], v[180:183], v[196:199], v[98:101]
	v_mfma_f32_16x16x32_bf16 v[86:89], v[172:175], v[204:207], v[86:89]
	v_mfma_f32_16x16x32_bf16 v[82:85], v[180:183], v[204:207], v[82:85]
	v_mfma_f32_16x16x32_bf16 v[70:73], v[172:175], v[212:215], v[70:73]
	v_mfma_f32_16x16x32_bf16 v[66:69], v[180:183], v[212:215], v[66:69]
	v_mfma_f32_16x16x32_bf16 v[118:121], v[176:179], v[192:195], v[118:121]
	v_mfma_f32_16x16x32_bf16 v[114:117], v[184:187], v[192:195], v[114:117]
	v_mfma_f32_16x16x32_bf16 v[102:105], v[176:179], v[200:203], v[102:105]
	v_mfma_f32_16x16x32_bf16 v[98:101], v[184:187], v[200:203], v[98:101]
	v_mfma_f32_16x16x32_bf16 v[86:89], v[176:179], v[208:211], v[86:89]
	v_mfma_f32_16x16x32_bf16 v[82:85], v[184:187], v[208:211], v[82:85]
	v_mfma_f32_16x16x32_bf16 v[70:73], v[176:179], v[216:219], v[70:73]
	v_mfma_f32_16x16x32_bf16 v[66:69], v[184:187], v[216:219], v[66:69]
	s_barrier
	s_add_i32 s37, s59, s41
	s_add_u32 s98, s8, 0x80
	s_addc_u32 s99, s9, 0
	s_mov_b32 m0, s37
	ds_read_b128 v[188:191], v155 offset:16384
	ds_read_b128 v[192:195], v155 offset:17408
	ds_read_b128 v[196:199], v155 offset:18432
	ds_read_b128 v[200:203], v155 offset:19456
	ds_read_b128 v[204:207], v155 offset:20480
	ds_read_b128 v[208:211], v155 offset:21504
	ds_read_b128 v[212:215], v155 offset:22528
	ds_read_b128 v[216:219], v155 offset:23552
	global_load_lds_dwordx4 v132, s[8:9]
	s_add_i32 m0, s37, 0x2000
	s_add_u32 s72, s8, 0x40000
	s_addc_u32 s73, s9, 0
	s_add_i32 s37, s60, s41
	global_load_lds_dwordx4 v136, s[8:9]
	s_mov_b32 m0, s37
	s_nop 0
	global_load_lds_dwordx4 v132, s[72:73]
	s_add_i32 m0, s37, 0x2000
	s_nop 0
	global_load_lds_dwordx4 v136, s[72:73]
	s_add_u32 s100, s30, 0x80
	s_addc_u32 s101, s31, 0
	s_mov_b32 m0, s42
	s_nop 0
	global_load_lds_dwordx4 v130, s[30:31]
	s_mov_b32 m0, s43
	s_nop 0
	global_load_lds_dwordx4 v134, s[30:31]
	s_waitcnt vmcnt(8)
	s_waitcnt lgkmcnt(0)
	s_barrier
	s_waitcnt lgkmcnt(0)
	v_mfma_f32_16x16x32_bf16 v[62:65], v[156:159], v[188:191], v[62:65]
	v_mfma_f32_16x16x32_bf16 v[58:61], v[164:167], v[188:191], v[58:61]
	v_mfma_f32_16x16x32_bf16 v[46:49], v[156:159], v[196:199], v[46:49]
	v_mfma_f32_16x16x32_bf16 v[42:45], v[164:167], v[196:199], v[42:45]
	v_mfma_f32_16x16x32_bf16 v[30:33], v[156:159], v[204:207], v[30:33]
	v_mfma_f32_16x16x32_bf16 v[26:29], v[164:167], v[204:207], v[26:29]
	v_mfma_f32_16x16x32_bf16 v[14:17], v[156:159], v[212:215], v[14:17]
	v_mfma_f32_16x16x32_bf16 v[10:13], v[164:167], v[212:215], v[10:13]
	v_mfma_f32_16x16x32_bf16 v[62:65], v[160:163], v[192:195], v[62:65]
	v_mfma_f32_16x16x32_bf16 v[58:61], v[168:171], v[192:195], v[58:61]
	v_mfma_f32_16x16x32_bf16 v[46:49], v[160:163], v[200:203], v[46:49]
	v_mfma_f32_16x16x32_bf16 v[42:45], v[168:171], v[200:203], v[42:45]
	v_mfma_f32_16x16x32_bf16 v[30:33], v[160:163], v[208:211], v[30:33]
	v_mfma_f32_16x16x32_bf16 v[26:29], v[168:171], v[208:211], v[26:29]
	v_mfma_f32_16x16x32_bf16 v[14:17], v[160:163], v[216:219], v[14:17]
	v_mfma_f32_16x16x32_bf16 v[10:13], v[168:171], v[216:219], v[10:13]
	v_mfma_f32_16x16x32_bf16 v[54:57], v[172:175], v[188:191], v[54:57]
	v_mfma_f32_16x16x32_bf16 v[50:53], v[180:183], v[188:191], v[50:53]
	v_mfma_f32_16x16x32_bf16 v[38:41], v[172:175], v[196:199], v[38:41]
	v_mfma_f32_16x16x32_bf16 v[34:37], v[180:183], v[196:199], v[34:37]
	v_mfma_f32_16x16x32_bf16 v[22:25], v[172:175], v[204:207], v[22:25]
	v_mfma_f32_16x16x32_bf16 v[18:21], v[180:183], v[204:207], v[18:21]
	v_mfma_f32_16x16x32_bf16 v[6:9], v[172:175], v[212:215], v[6:9]
	v_mfma_f32_16x16x32_bf16 v[2:5], v[180:183], v[212:215], v[2:5]
	v_mfma_f32_16x16x32_bf16 v[54:57], v[176:179], v[192:195], v[54:57]
	v_mfma_f32_16x16x32_bf16 v[50:53], v[184:187], v[192:195], v[50:53]
	v_mfma_f32_16x16x32_bf16 v[38:41], v[176:179], v[200:203], v[38:41]
	v_mfma_f32_16x16x32_bf16 v[34:37], v[184:187], v[200:203], v[34:37]
	v_mfma_f32_16x16x32_bf16 v[22:25], v[176:179], v[208:211], v[22:25]
	v_mfma_f32_16x16x32_bf16 v[18:21], v[184:187], v[208:211], v[18:21]
	v_mfma_f32_16x16x32_bf16 v[6:9], v[176:179], v[216:219], v[6:9]
	v_mfma_f32_16x16x32_bf16 v[2:5], v[184:187], v[216:219], v[2:5]
	s_barrier
; #define PG8_STAGE(bufoff, gbase, voff) do { _Pragma("unroll") for (int _i = 0; _i < 2; ++_i) \
;         __builtin_amdgcn_global_load_lds((const unsigned*)((const char*)(gbase) + (voff)[_i]), (PG8_LAS unsigned*)(lds + (bufoff) + ldsw + _i * 8192), 16, 0, 0); } while (0)
; #define PG8_LDA(dst, b, h) do { _Pragma("unroll") for (int m = 0; m < 4; ++m) _Pragma("unroll") for (int k = 0; k < 2; ++k) dst[m][k] = *(const PG8_LAS bf16x8*)(lds + PG8_SA(b, h) + aoff + m * 2048 + k * 1024); } while (0)
; #define PG8_LDB(dst, b, h) do { _Pragma("unroll") for (int n = 0; n < 2; ++n) _Pragma("unroll") for (int k = 0; k < 2; ++k) dst[n][k] = *(const PG8_LAS bf16x8*)(lds + PG8_SB(b, h) + boff + n * 2048 + k * 1024); } while (0)
; #define PG8_MMA(ai, bj, At, Bt) do { __builtin_amdgcn_s_setprio(1); _Pragma("unroll") for (int m = 0; m < 4; ++m) _Pragma("unroll") for (int n = 0; n < 2; ++n) _Pragma("unroll") for (int k = 0; k < 2; ++k) \
;         acc[ai][bj][m][n] = __builtin_amdgcn_mfma_f32_16x16x32_bf16(Bt[n][k], At[m][k], acc[ai][bj][m][n], 0, 0, 0); __builtin_amdgcn_s_setprio(0); } while (0)
; #define PG8_WAIT_V(n) asm volatile("s_waitcnt vmcnt(" #n ")" ::: "memory")
; #define PG8_WAIT_L(n) asm volatile("s_waitcnt lgkmcnt(" #n ")" ::: "memory")
; #define PG8_BAR __builtin_amdgcn_s_barrier()
; #define PG8_SCHED __builtin_amdgcn_sched_barrier(0)
; template <class Epi, class Sched, bool ALIGN_EPI = false, bool SP2 = false>
; __device__ __forceinline__ void gemm_phase(PG8_LAS unsigned char* lds, const Gemm g, const Sched& S, const Epi& E) {
;     ...
;             PG8_LDB(B0, 1, 0); PG8_LDB(B1, 1, 1); PG8_SCHED; PG8_LDA(At, 1, 0); PG8_STAGE(PG8_SA(0, 1), a2 + hstepA, voffA);
;             PG8_WAIT_V(8); PG8_WAIT_L(0); PG8_BAR; PG8_MMA(0, 0, At, B0); PG8_MMA(0, 1, At, B1); PG8_BAR; PG8_SCHED;
;             PG8_LDA(At, 1, 1); PG8_STAGE(PG8_SB(1, 0), b3, voffB); PG8_STAGE(PG8_SB(1, 1), b3 + hstepB, voffB); PG8_STAGE(PG8_SA(1, 0), a3, voffA);
;             PG8_WAIT_V(8); PG8_WAIT_L(0); PG8_BAR; PG8_MMA(1, 0, At, B0); PG8_MMA(1, 1, At, B1); PG8_BAR; PG8_SCHED;
	s_add_i32 s37, 0, 0x18000
	v_add_u32_e32 v138, s37, v152
	s_add_i32 s71, 0, 0x1c000
	ds_read_b128 v[156:159], v138
	ds_read_b128 v[160:163], v138 offset:1024
	ds_read_b128 v[164:167], v138 offset:2048
	ds_read_b128 v[168:171], v138 offset:3072
	v_add_u32_e32 v138, s71, v152
	ds_read_b128 v[172:175], v138
	ds_read_b128 v[176:179], v138 offset:1024
	ds_read_b128 v[180:183], v138 offset:2048
	ds_read_b128 v[184:187], v138 offset:3072
	s_add_u32 s30, s30, 0x40000
	s_addc_u32 s31, s31, 0
	s_mov_b32 m0, s44
	ds_read_b128 v[188:191], v155 offset:32768
	ds_read_b128 v[192:195], v155 offset:33792
	ds_read_b128 v[196:199], v155 offset:34816
	ds_read_b128 v[200:203], v155 offset:35840
	ds_read_b128 v[204:207], v155 offset:36864
	ds_read_b128 v[208:211], v155 offset:37888
	ds_read_b128 v[212:215], v155 offset:38912
	ds_read_b128 v[216:219], v155 offset:39936
	global_load_lds_dwordx4 v130, s[30:31]
	s_mov_b32 m0, s45
	s_nop 0
	global_load_lds_dwordx4 v134, s[30:31]
	s_waitcnt vmcnt(8)
	s_waitcnt lgkmcnt(0)
	s_barrier
	s_waitcnt lgkmcnt(0)
	v_mfma_f32_16x16x32_bf16 v[126:129], v[156:159], v[188:191], v[126:129]
	v_mfma_f32_16x16x32_bf16 v[122:125], v[164:167], v[188:191], v[122:125]
	v_mfma_f32_16x16x32_bf16 v[110:113], v[156:159], v[196:199], v[110:113]
	v_mfma_f32_16x16x32_bf16 v[106:109], v[164:167], v[196:199], v[106:109]
	v_mfma_f32_16x16x32_bf16 v[94:97], v[156:159], v[204:207], v[94:97]
	v_mfma_f32_16x16x32_bf16 v[90:93], v[164:167], v[204:207], v[90:93]
	v_mfma_f32_16x16x32_bf16 v[78:81], v[156:159], v[212:215], v[78:81]
	v_mfma_f32_16x16x32_bf16 v[74:77], v[164:167], v[212:215], v[74:77]
	v_mfma_f32_16x16x32_bf16 v[126:129], v[160:163], v[192:195], v[126:129]
	v_mfma_f32_16x16x32_bf16 v[122:125], v[168:171], v[192:195], v[122:125]
	v_mfma_f32_16x16x32_bf16 v[110:113], v[160:163], v[200:203], v[110:113]
	v_mfma_f32_16x16x32_bf16 v[106:109], v[168:171], v[200:203], v[106:109]
	v_mfma_f32_16x16x32_bf16 v[94:97], v[160:163], v[208:211], v[94:97]
	v_mfma_f32_16x16x32_bf16 v[90:93], v[168:171], v[208:211], v[90:93]
	v_mfma_f32_16x16x32_bf16 v[78:81], v[160:163], v[216:219], v[78:81]
	v_mfma_f32_16x16x32_bf16 v[74:77], v[168:171], v[216:219], v[74:77]
	v_mfma_f32_16x16x32_bf16 v[118:121], v[172:175], v[188:191], v[118:121]
	v_mfma_f32_16x16x32_bf16 v[114:117], v[180:183], v[188:191], v[114:117]
	v_mfma_f32_16x16x32_bf16 v[102:105], v[172:175], v[196:199], v[102:105]
	v_mfma_f32_16x16x32_bf16 v[98:101], v[180:183], v[196:199], v[98:101]
	v_mfma_f32_16x16x32_bf16 v[86:89], v[172:175], v[204:207], v[86:89]
	v_mfma_f32_16x16x32_bf16 v[82:85], v[180:183], v[204:207], v[82:85]
	v_mfma_f32_16x16x32_bf16 v[70:73], v[172:175], v[212:215], v[70:73]
	v_mfma_f32_16x16x32_bf16 v[66:69], v[180:183], v[212:215], v[66:69]
	v_mfma_f32_16x16x32_bf16 v[118:121], v[176:179], v[192:195], v[118:121]
	v_mfma_f32_16x16x32_bf16 v[114:117], v[184:187], v[192:195], v[114:117]
	v_mfma_f32_16x16x32_bf16 v[102:105], v[176:179], v[200:203], v[102:105]
	v_mfma_f32_16x16x32_bf16 v[98:101], v[184:187], v[200:203], v[98:101]
	v_mfma_f32_16x16x32_bf16 v[86:89], v[176:179], v[208:211], v[86:89]
	v_mfma_f32_16x16x32_bf16 v[82:85], v[184:187], v[208:211], v[82:85]
	v_mfma_f32_16x16x32_bf16 v[70:73], v[176:179], v[216:219], v[70:73]
	v_mfma_f32_16x16x32_bf16 v[66:69], v[184:187], v[216:219], v[66:69]
	s_barrier
	s_add_i32 s30, s37, s41
	s_mov_b32 m0, s30
	ds_read_b128 v[188:191], v155 offset:49152
	ds_read_b128 v[192:195], v155 offset:50176
	ds_read_b128 v[196:199], v155 offset:51200
	ds_read_b128 v[200:203], v155 offset:52224
	ds_read_b128 v[204:207], v155 offset:53248
	ds_read_b128 v[208:211], v155 offset:54272
	ds_read_b128 v[212:215], v155 offset:55296
	ds_read_b128 v[216:219], v155 offset:56320
	global_load_lds_dwordx4 v132, s[98:99]
	s_add_i32 m0, s30, 0x2000
	s_add_u32 s8, s8, 0x40080
	s_addc_u32 s9, s9, 0
	s_add_i32 s30, s71, s41
	global_load_lds_dwordx4 v136, s[98:99]
	s_mov_b32 m0, s30
	s_nop 0
	global_load_lds_dwordx4 v132, s[8:9]
	s_add_i32 m0, s30, 0x2000
	s_nop 0
	global_load_lds_dwordx4 v136, s[8:9]
	s_mov_b32 m0, s54
	s_nop 0
	global_load_lds_dwordx4 v130, s[100:101]
	s_mov_b32 m0, s55
	s_nop 0
	global_load_lds_dwordx4 v134, s[100:101]
	s_waitcnt vmcnt(8)
	s_waitcnt lgkmcnt(0)
	s_barrier
	s_waitcnt lgkmcnt(0)
	v_mfma_f32_16x16x32_bf16 v[62:65], v[156:159], v[188:191], v[62:65]
	v_mfma_f32_16x16x32_bf16 v[58:61], v[164:167], v[188:191], v[58:61]
	v_mfma_f32_16x16x32_bf16 v[46:49], v[156:159], v[196:199], v[46:49]
	v_mfma_f32_16x16x32_bf16 v[42:45], v[164:167], v[196:199], v[42:45]
	v_mfma_f32_16x16x32_bf16 v[30:33], v[156:159], v[204:207], v[30:33]
	v_mfma_f32_16x16x32_bf16 v[26:29], v[164:167], v[204:207], v[26:29]
	v_mfma_f32_16x16x32_bf16 v[14:17], v[156:159], v[212:215], v[14:17]
	v_mfma_f32_16x16x32_bf16 v[10:13], v[164:167], v[212:215], v[10:13]
	v_mfma_f32_16x16x32_bf16 v[62:65], v[160:163], v[192:195], v[62:65]
	v_mfma_f32_16x16x32_bf16 v[58:61], v[168:171], v[192:195], v[58:61]
	v_mfma_f32_16x16x32_bf16 v[46:49], v[160:163], v[200:203], v[46:49]
	v_mfma_f32_16x16x32_bf16 v[42:45], v[168:171], v[200:203], v[42:45]
	v_mfma_f32_16x16x32_bf16 v[30:33], v[160:163], v[208:211], v[30:33]
	v_mfma_f32_16x16x32_bf16 v[26:29], v[168:171], v[208:211], v[26:29]
	v_mfma_f32_16x16x32_bf16 v[14:17], v[160:163], v[216:219], v[14:17]
	v_mfma_f32_16x16x32_bf16 v[10:13], v[168:171], v[216:219], v[10:13]
	v_mfma_f32_16x16x32_bf16 v[54:57], v[172:175], v[188:191], v[54:57]
	v_mfma_f32_16x16x32_bf16 v[50:53], v[180:183], v[188:191], v[50:53]
	v_mfma_f32_16x16x32_bf16 v[38:41], v[172:175], v[196:199], v[38:41]
	v_mfma_f32_16x16x32_bf16 v[34:37], v[180:183], v[196:199], v[34:37]
	v_mfma_f32_16x16x32_bf16 v[22:25], v[172:175], v[204:207], v[22:25]
	v_mfma_f32_16x16x32_bf16 v[18:21], v[180:183], v[204:207], v[18:21]
	v_mfma_f32_16x16x32_bf16 v[6:9], v[172:175], v[212:215], v[6:9]
	v_mfma_f32_16x16x32_bf16 v[2:5], v[180:183], v[212:215], v[2:5]
	v_mfma_f32_16x16x32_bf16 v[54:57], v[176:179], v[192:195], v[54:57]
	v_mfma_f32_16x16x32_bf16 v[50:53], v[184:187], v[192:195], v[50:53]
	v_mfma_f32_16x16x32_bf16 v[38:41], v[176:179], v[200:203], v[38:41]
	v_mfma_f32_16x16x32_bf16 v[34:37], v[184:187], v[200:203], v[34:37]
	v_mfma_f32_16x16x32_bf16 v[22:25], v[176:179], v[208:211], v[22:25]
	v_mfma_f32_16x16x32_bf16 v[18:21], v[184:187], v[208:211], v[18:21]
	v_mfma_f32_16x16x32_bf16 v[6:9], v[176:179], v[216:219], v[6:9]
	v_mfma_f32_16x16x32_bf16 v[2:5], v[184:187], v[216:219], v[2:5]
	s_barrier
	s_add_i32 s36, s36, 2
	s_add_u32 s6, s6, 0x100
	s_addc_u32 s7, s7, 0
	s_add_u32 s34, s34, 0x100
	s_addc_u32 s35, s35, 0
	s_cmp_gt_u32 s36, 13
	s_cbranch_scc0 .LBB0_318
	s_and_b64 vcc, exec, s[18:19]
	s_cbranch_vccz .LBB0_321
	s_barrier

; #define PG8_STAGE(bufoff, gbase, voff) do { _Pragma("unroll") for (int _i = 0; _i < 2; ++_i) \
;         __builtin_amdgcn_global_load_lds((const unsigned*)((const char*)(gbase) + (voff)[_i]), (PG8_LAS unsigned*)(lds + (bufoff) + ldsw + _i * 8192), 16, 0, 0); } while (0)
; #define PG8_LDA(dst, b, h) do { _Pragma("unroll") for (int m = 0; m < 4; ++m) _Pragma("unroll") for (int k = 0; k < 2; ++k) dst[m][k] = *(const PG8_LAS bf16x8*)(lds + PG8_SA(b, h) + aoff + m * 2048 + k * 1024); } while (0)
; #define PG8_LDB(dst, b, h) do { _Pragma("unroll") for (int n = 0; n < 2; ++n) _Pragma("unroll") for (int k = 0; k < 2; ++k) dst[n][k] = *(const PG8_LAS bf16x8*)(lds + PG8_SB(b, h) + boff + n * 2048 + k * 1024); } while (0)
; #define PG8_MMA(ai, bj, At, Bt) do { __builtin_amdgcn_s_setprio(1); _Pragma("unroll") for (int m = 0; m < 4; ++m) _Pragma("unroll") for (int n = 0; n < 2; ++n) _Pragma("unroll") for (int k = 0; k < 2; ++k) \
;         acc[ai][bj][m][n] = __builtin_amdgcn_mfma_f32_16x16x32_bf16(Bt[n][k], At[m][k], acc[ai][bj][m][n], 0, 0, 0); __builtin_amdgcn_s_setprio(0); } while (0)
; #define PG8_WAIT_V(n) asm volatile("s_waitcnt vmcnt(" #n ")" ::: "memory")
; #define PG8_WAIT_L(n) asm volatile("s_waitcnt lgkmcnt(" #n ")" ::: "memory")
; #define PG8_BAR __builtin_amdgcn_s_barrier()
; #define PG8_SCHED __builtin_amdgcn_sched_barrier(0)
; template <class Epi, class Sched, bool ALIGN_EPI = false, bool SP2 = false>
; __device__ __forceinline__ void gemm_phase(PG8_LAS unsigned char* lds, const Gemm g, const Sched& S, const Epi& E) {
;     ...
;             PG8_LDB(B0, 0, 0); PG8_LDB(B1, 0, 1); PG8_SCHED; PG8_LDA(At, 0, 0); PG8_STAGE(PG8_SA(1, 1), a1 + hstepA, voffA);
;             PG8_WAIT_V(8); PG8_WAIT_L(0); PG8_BAR; PG8_MMA(0, 0, At, B0); PG8_MMA(0, 1, At, B1); PG8_BAR; PG8_SCHED;
;             PG8_LDA(At, 0, 1); PG8_STAGE(PG8_SB(0, 0), b2, voffB); PG8_STAGE(PG8_SB(0, 1), b2 + hstepB, voffB); PG8_STAGE(PG8_SA(0, 0), a2, voffA);
;             PG8_WAIT_V(8); PG8_WAIT_L(0); PG8_BAR; PG8_MMA(1, 0, At, B0); PG8_MMA(1, 1, At, B1); PG8_BAR; PG8_SCHED;
.LBB0_780:
	ds_read_b128 v[148:151], v165
	ds_read_b128 v[152:155], v165 offset:1024
	ds_read_b128 v[156:159], v165 offset:2048
	ds_read_b128 v[170:173], v165 offset:3072
	ds_read_b128 v[174:177], v166
	ds_read_b128 v[178:181], v166 offset:1024
	ds_read_b128 v[182:185], v166 offset:2048
	ds_read_b128 v[186:189], v166 offset:3072
	s_add_u32 s0, s6, 0x100
	s_addc_u32 s1, s7, 0
	s_cmp_eq_u32 s66, 2
	s_cselect_b32 s29, s25, s1
	s_cselect_b32 s28, s24, s0
	s_cselect_b32 s9, s27, s65
	s_cselect_b32 s8, s26, s64
	v_lshl_add_u64 v[222:223], s[6:7], 0, v[140:141]
	s_add_i32 m0, s36, 0xc000
	ds_read_b128 v[190:193], v167
	ds_read_b128 v[194:197], v167 offset:1024
	ds_read_b128 v[198:201], v167 offset:2048
	ds_read_b128 v[202:205], v167 offset:3072
	ds_read_b128 v[206:209], v167 offset:4096
	ds_read_b128 v[210:213], v167 offset:5120
	ds_read_b128 v[214:217], v167 offset:6144
	ds_read_b128 v[218:221], v167 offset:7168
	global_load_lds_dwordx4 v[222:223], off
	v_lshl_add_u64 v[222:223], s[6:7], 0, v[142:143]
	s_add_i32 m0, s36, 0xe000
	s_nop 0
	global_load_lds_dwordx4 v[222:223], off
	s_waitcnt vmcnt(8)
	s_waitcnt lgkmcnt(0)
	s_barrier
	s_waitcnt lgkmcnt(0)
	v_mfma_f32_16x16x32_bf16 v[126:129], v[148:151], v[190:193], v[126:129]
	v_mfma_f32_16x16x32_bf16 v[122:125], v[156:159], v[190:193], v[122:125]
	v_mfma_f32_16x16x32_bf16 v[110:113], v[148:151], v[198:201], v[110:113]
	v_mfma_f32_16x16x32_bf16 v[106:109], v[156:159], v[198:201], v[106:109]
	v_mfma_f32_16x16x32_bf16 v[94:97], v[148:151], v[206:209], v[94:97]
	v_mfma_f32_16x16x32_bf16 v[90:93], v[156:159], v[206:209], v[90:93]
	v_mfma_f32_16x16x32_bf16 v[78:81], v[148:151], v[214:217], v[78:81]
	v_mfma_f32_16x16x32_bf16 v[74:77], v[156:159], v[214:217], v[74:77]
	v_mfma_f32_16x16x32_bf16 v[126:129], v[152:155], v[194:197], v[126:129]
	v_mfma_f32_16x16x32_bf16 v[122:125], v[170:173], v[194:197], v[122:125]
	v_mfma_f32_16x16x32_bf16 v[110:113], v[152:155], v[202:205], v[110:113]
	v_mfma_f32_16x16x32_bf16 v[106:109], v[170:173], v[202:205], v[106:109]
	v_mfma_f32_16x16x32_bf16 v[94:97], v[152:155], v[210:213], v[94:97]
	v_mfma_f32_16x16x32_bf16 v[90:93], v[170:173], v[210:213], v[90:93]
	v_mfma_f32_16x16x32_bf16 v[78:81], v[152:155], v[218:221], v[78:81]
	v_mfma_f32_16x16x32_bf16 v[74:77], v[170:173], v[218:221], v[74:77]
	v_mfma_f32_16x16x32_bf16 v[118:121], v[174:177], v[190:193], v[118:121]
	v_mfma_f32_16x16x32_bf16 v[114:117], v[182:185], v[190:193], v[114:117]
	v_mfma_f32_16x16x32_bf16 v[102:105], v[174:177], v[198:201], v[102:105]
	v_mfma_f32_16x16x32_bf16 v[98:101], v[182:185], v[198:201], v[98:101]
	v_mfma_f32_16x16x32_bf16 v[86:89], v[174:177], v[206:209], v[86:89]
	v_mfma_f32_16x16x32_bf16 v[82:85], v[182:185], v[206:209], v[82:85]
	v_mfma_f32_16x16x32_bf16 v[70:73], v[174:177], v[214:217], v[70:73]
	v_mfma_f32_16x16x32_bf16 v[66:69], v[182:185], v[214:217], v[66:69]
	v_mfma_f32_16x16x32_bf16 v[118:121], v[178:181], v[194:197], v[118:121]
	v_mfma_f32_16x16x32_bf16 v[114:117], v[186:189], v[194:197], v[114:117]
	v_mfma_f32_16x16x32_bf16 v[102:105], v[178:181], v[202:205], v[102:105]
	v_mfma_f32_16x16x32_bf16 v[98:101], v[186:189], v[202:205], v[98:101]
	v_mfma_f32_16x16x32_bf16 v[86:89], v[178:181], v[210:213], v[86:89]
	v_mfma_f32_16x16x32_bf16 v[82:85], v[186:189], v[210:213], v[82:85]
	v_mfma_f32_16x16x32_bf16 v[70:73], v[178:181], v[218:221], v[70:73]
	v_mfma_f32_16x16x32_bf16 v[66:69], v[186:189], v[218:221], v[66:69]
	s_barrier
	s_add_i32 s6, s48, s35
	s_add_u32 s98, s8, 0x80
	s_addc_u32 s99, s9, 0
	s_mov_b32 m0, s6
	ds_read_b128 v[190:193], v167 offset:16384
	ds_read_b128 v[194:197], v167 offset:17408
	ds_read_b128 v[198:201], v167 offset:18432
	ds_read_b128 v[202:205], v167 offset:19456
	ds_read_b128 v[206:209], v167 offset:20480
	ds_read_b128 v[210:213], v167 offset:21504
	ds_read_b128 v[214:217], v167 offset:22528
	ds_read_b128 v[218:221], v167 offset:23552
	global_load_lds_dwordx4 v132, s[8:9]
	s_add_i32 m0, s6, 0x2000
	s_add_u32 s6, s8, 0x18000
	s_addc_u32 s7, s9, 0
	s_add_i32 s67, s49, s35
	global_load_lds_dwordx4 v136, s[8:9]
	s_mov_b32 m0, s67
	s_nop 0
	global_load_lds_dwordx4 v132, s[6:7]
	s_add_i32 m0, s67, 0x2000
	s_nop 0
	global_load_lds_dwordx4 v136, s[6:7]
	s_add_u32 s100, s28, 0x80
	s_addc_u32 s101, s29, 0
	s_mov_b32 m0, s36
	s_nop 0
	global_load_lds_dwordx4 v130, s[28:29]
	s_mov_b32 m0, s37
	s_nop 0
	global_load_lds_dwordx4 v134, s[28:29]
	s_waitcnt vmcnt(8)
	s_waitcnt lgkmcnt(0)
	s_barrier
	s_waitcnt lgkmcnt(0)
	v_mfma_f32_16x16x32_bf16 v[62:65], v[148:151], v[190:193], v[62:65]
	v_mfma_f32_16x16x32_bf16 v[58:61], v[156:159], v[190:193], v[58:61]
	v_mfma_f32_16x16x32_bf16 v[46:49], v[148:151], v[198:201], v[46:49]
	v_mfma_f32_16x16x32_bf16 v[42:45], v[156:159], v[198:201], v[42:45]
	v_mfma_f32_16x16x32_bf16 v[30:33], v[148:151], v[206:209], v[30:33]
	v_mfma_f32_16x16x32_bf16 v[26:29], v[156:159], v[206:209], v[26:29]
	v_mfma_f32_16x16x32_bf16 v[14:17], v[148:151], v[214:217], v[14:17]
	v_mfma_f32_16x16x32_bf16 v[10:13], v[156:159], v[214:217], v[10:13]
	v_mfma_f32_16x16x32_bf16 v[62:65], v[152:155], v[194:197], v[62:65]
	v_mfma_f32_16x16x32_bf16 v[58:61], v[170:173], v[194:197], v[58:61]
	v_mfma_f32_16x16x32_bf16 v[46:49], v[152:155], v[202:205], v[46:49]
	v_mfma_f32_16x16x32_bf16 v[42:45], v[170:173], v[202:205], v[42:45]
	v_mfma_f32_16x16x32_bf16 v[30:33], v[152:155], v[210:213], v[30:33]
	v_mfma_f32_16x16x32_bf16 v[26:29], v[170:173], v[210:213], v[26:29]
	v_mfma_f32_16x16x32_bf16 v[14:17], v[152:155], v[218:221], v[14:17]
	v_mfma_f32_16x16x32_bf16 v[10:13], v[170:173], v[218:221], v[10:13]
	v_mfma_f32_16x16x32_bf16 v[54:57], v[174:177], v[190:193], v[54:57]
	v_mfma_f32_16x16x32_bf16 v[50:53], v[182:185], v[190:193], v[50:53]
	v_mfma_f32_16x16x32_bf16 v[38:41], v[174:177], v[198:201], v[38:41]
	v_mfma_f32_16x16x32_bf16 v[34:37], v[182:185], v[198:201], v[34:37]
	v_mfma_f32_16x16x32_bf16 v[22:25], v[174:177], v[206:209], v[22:25]
	v_mfma_f32_16x16x32_bf16 v[18:21], v[182:185], v[206:209], v[18:21]
	v_mfma_f32_16x16x32_bf16 v[6:9], v[174:177], v[214:217], v[6:9]
	v_mfma_f32_16x16x32_bf16 v[2:5], v[182:185], v[214:217], v[2:5]
	v_mfma_f32_16x16x32_bf16 v[54:57], v[178:181], v[194:197], v[54:57]
	v_mfma_f32_16x16x32_bf16 v[50:53], v[186:189], v[194:197], v[50:53]
	v_mfma_f32_16x16x32_bf16 v[38:41], v[178:181], v[202:205], v[38:41]
	v_mfma_f32_16x16x32_bf16 v[34:37], v[186:189], v[202:205], v[34:37]
	v_mfma_f32_16x16x32_bf16 v[22:25], v[178:181], v[210:213], v[22:25]
	v_mfma_f32_16x16x32_bf16 v[18:21], v[186:189], v[210:213], v[18:21]
	v_mfma_f32_16x16x32_bf16 v[6:9], v[178:181], v[218:221], v[6:9]
	v_mfma_f32_16x16x32_bf16 v[2:5], v[186:189], v[218:221], v[2:5]
	s_barrier
; #define PG8_STAGE(bufoff, gbase, voff) do { _Pragma("unroll") for (int _i = 0; _i < 2; ++_i) \
;         __builtin_amdgcn_global_load_lds((const unsigned*)((const char*)(gbase) + (voff)[_i]), (PG8_LAS unsigned*)(lds + (bufoff) + ldsw + _i * 8192), 16, 0, 0); } while (0)
; #define PG8_LDA(dst, b, h) do { _Pragma("unroll") for (int m = 0; m < 4; ++m) _Pragma("unroll") for (int k = 0; k < 2; ++k) dst[m][k] = *(const PG8_LAS bf16x8*)(lds + PG8_SA(b, h) + aoff + m * 2048 + k * 1024); } while (0)
; #define PG8_LDB(dst, b, h) do { _Pragma("unroll") for (int n = 0; n < 2; ++n) _Pragma("unroll") for (int k = 0; k < 2; ++k) dst[n][k] = *(const PG8_LAS bf16x8*)(lds + PG8_SB(b, h) + boff + n * 2048 + k * 1024); } while (0)
; #define PG8_MMA(ai, bj, At, Bt) do { __builtin_amdgcn_s_setprio(1); _Pragma("unroll") for (int m = 0; m < 4; ++m) _Pragma("unroll") for (int n = 0; n < 2; ++n) _Pragma("unroll") for (int k = 0; k < 2; ++k) \
;         acc[ai][bj][m][n] = __builtin_amdgcn_mfma_f32_16x16x32_bf16(Bt[n][k], At[m][k], acc[ai][bj][m][n], 0, 0, 0); __builtin_amdgcn_s_setprio(0); } while (0)
; #define PG8_WAIT_V(n) asm volatile("s_waitcnt vmcnt(" #n ")" ::: "memory")
; #define PG8_WAIT_L(n) asm volatile("s_waitcnt lgkmcnt(" #n ")" ::: "memory")
; #define PG8_BAR __builtin_amdgcn_s_barrier()
; #define PG8_SCHED __builtin_amdgcn_sched_barrier(0)
; template <class Epi, class Sched, bool ALIGN_EPI = false, bool SP2 = false>
; __device__ __forceinline__ void gemm_phase(PG8_LAS unsigned char* lds, const Gemm g, const Sched& S, const Epi& E) {
;     ...
;             PG8_LDB(B0, 1, 0); PG8_LDB(B1, 1, 1); PG8_SCHED; PG8_LDA(At, 1, 0); PG8_STAGE(PG8_SA(0, 1), a2 + hstepA, voffA);
;             PG8_WAIT_V(8); PG8_WAIT_L(0); PG8_BAR; PG8_MMA(0, 0, At, B0); PG8_MMA(0, 1, At, B1); PG8_BAR; PG8_SCHED;
;             PG8_LDA(At, 1, 1); PG8_STAGE(PG8_SB(1, 0), b3, voffB); PG8_STAGE(PG8_SB(1, 1), b3 + hstepB, voffB); PG8_STAGE(PG8_SA(1, 0), a3, voffA);
;             PG8_WAIT_V(8); PG8_WAIT_L(0); PG8_BAR; PG8_MMA(1, 0, At, B0); PG8_MMA(1, 1, At, B1); PG8_BAR; PG8_SCHED;
	s_add_i32 s67, 0, 0x18000
	v_add_u32_e32 v138, s67, v160
	s_add_i32 s68, 0, 0x1c000
	ds_read_b128 v[148:151], v138
	ds_read_b128 v[152:155], v138 offset:1024
	ds_read_b128 v[156:159], v138 offset:2048
	ds_read_b128 v[170:173], v138 offset:3072
	v_add_u32_e32 v138, s68, v160
	ds_read_b128 v[174:177], v138
	ds_read_b128 v[178:181], v138 offset:1024
	ds_read_b128 v[182:185], v138 offset:2048
	ds_read_b128 v[186:189], v138 offset:3072
	s_add_u32 s6, s28, 0x2a000
	s_addc_u32 s7, s29, 0
	s_mov_b32 m0, s38
	ds_read_b128 v[190:193], v167 offset:32768
	ds_read_b128 v[194:197], v167 offset:33792
	ds_read_b128 v[198:201], v167 offset:34816
	ds_read_b128 v[202:205], v167 offset:35840
	ds_read_b128 v[206:209], v167 offset:36864
	ds_read_b128 v[210:213], v167 offset:37888
	ds_read_b128 v[214:217], v167 offset:38912
	ds_read_b128 v[218:221], v167 offset:39936
	global_load_lds_dwordx4 v130, s[6:7]
	s_mov_b32 m0, s39
	s_nop 0
	global_load_lds_dwordx4 v134, s[6:7]
	s_waitcnt vmcnt(8)
	s_waitcnt lgkmcnt(0)
	s_barrier
	s_waitcnt lgkmcnt(0)
	v_mfma_f32_16x16x32_bf16 v[126:129], v[148:151], v[190:193], v[126:129]
	v_mfma_f32_16x16x32_bf16 v[122:125], v[156:159], v[190:193], v[122:125]
	v_mfma_f32_16x16x32_bf16 v[110:113], v[148:151], v[198:201], v[110:113]
	v_mfma_f32_16x16x32_bf16 v[106:109], v[156:159], v[198:201], v[106:109]
	v_mfma_f32_16x16x32_bf16 v[94:97], v[148:151], v[206:209], v[94:97]
	v_mfma_f32_16x16x32_bf16 v[90:93], v[156:159], v[206:209], v[90:93]
	v_mfma_f32_16x16x32_bf16 v[78:81], v[148:151], v[214:217], v[78:81]
	v_mfma_f32_16x16x32_bf16 v[74:77], v[156:159], v[214:217], v[74:77]
	v_mfma_f32_16x16x32_bf16 v[126:129], v[152:155], v[194:197], v[126:129]
	v_mfma_f32_16x16x32_bf16 v[122:125], v[170:173], v[194:197], v[122:125]
	v_mfma_f32_16x16x32_bf16 v[110:113], v[152:155], v[202:205], v[110:113]
	v_mfma_f32_16x16x32_bf16 v[106:109], v[170:173], v[202:205], v[106:109]
	v_mfma_f32_16x16x32_bf16 v[94:97], v[152:155], v[210:213], v[94:97]
	v_mfma_f32_16x16x32_bf16 v[90:93], v[170:173], v[210:213], v[90:93]
	v_mfma_f32_16x16x32_bf16 v[78:81], v[152:155], v[218:221], v[78:81]
	v_mfma_f32_16x16x32_bf16 v[74:77], v[170:173], v[218:221], v[74:77]
	v_mfma_f32_16x16x32_bf16 v[118:121], v[174:177], v[190:193], v[118:121]
	v_mfma_f32_16x16x32_bf16 v[114:117], v[182:185], v[190:193], v[114:117]
	v_mfma_f32_16x16x32_bf16 v[102:105], v[174:177], v[198:201], v[102:105]
	v_mfma_f32_16x16x32_bf16 v[98:101], v[182:185], v[198:201], v[98:101]
	v_mfma_f32_16x16x32_bf16 v[86:89], v[174:177], v[206:209], v[86:89]
	v_mfma_f32_16x16x32_bf16 v[82:85], v[182:185], v[206:209], v[82:85]
	v_mfma_f32_16x16x32_bf16 v[70:73], v[174:177], v[214:217], v[70:73]
	v_mfma_f32_16x16x32_bf16 v[66:69], v[182:185], v[214:217], v[66:69]
	v_mfma_f32_16x16x32_bf16 v[118:121], v[178:181], v[194:197], v[118:121]
	v_mfma_f32_16x16x32_bf16 v[114:117], v[186:189], v[194:197], v[114:117]
	v_mfma_f32_16x16x32_bf16 v[102:105], v[178:181], v[202:205], v[102:105]
	v_mfma_f32_16x16x32_bf16 v[98:101], v[186:189], v[202:205], v[98:101]
	v_mfma_f32_16x16x32_bf16 v[86:89], v[178:181], v[210:213], v[86:89]
	v_mfma_f32_16x16x32_bf16 v[82:85], v[186:189], v[210:213], v[82:85]
	v_mfma_f32_16x16x32_bf16 v[70:73], v[178:181], v[218:221], v[70:73]
	v_mfma_f32_16x16x32_bf16 v[66:69], v[186:189], v[218:221], v[66:69]
	s_barrier
	s_add_i32 s6, s67, s35
	s_mov_b32 m0, s6
	ds_read_b128 v[190:193], v167 offset:49152
	ds_read_b128 v[194:197], v167 offset:50176
	ds_read_b128 v[198:201], v167 offset:51200
	ds_read_b128 v[202:205], v167 offset:52224
	ds_read_b128 v[206:209], v167 offset:53248
	ds_read_b128 v[210:213], v167 offset:54272
	ds_read_b128 v[214:217], v167 offset:55296
	ds_read_b128 v[218:221], v167 offset:56320
	global_load_lds_dwordx4 v132, s[98:99]
	s_add_i32 m0, s6, 0x2000
	s_add_u32 s6, s8, 0x18080
	s_addc_u32 s7, s9, 0
	s_add_i32 s8, s68, s35
	global_load_lds_dwordx4 v136, s[98:99]
	s_mov_b32 m0, s8
	s_nop 0
	global_load_lds_dwordx4 v132, s[6:7]
	s_add_i32 m0, s8, 0x2000
	s_nop 0
	global_load_lds_dwordx4 v136, s[6:7]
	s_mov_b32 m0, s45
	s_nop 0
	global_load_lds_dwordx4 v130, s[100:101]
	s_mov_b32 m0, s46
	s_nop 0
	global_load_lds_dwordx4 v134, s[100:101]
	s_waitcnt vmcnt(8)
	s_waitcnt lgkmcnt(0)
	s_barrier
	s_waitcnt lgkmcnt(0)
	v_mfma_f32_16x16x32_bf16 v[62:65], v[148:151], v[190:193], v[62:65]
	v_mfma_f32_16x16x32_bf16 v[58:61], v[156:159], v[190:193], v[58:61]
	v_mfma_f32_16x16x32_bf16 v[46:49], v[148:151], v[198:201], v[46:49]
	v_mfma_f32_16x16x32_bf16 v[42:45], v[156:159], v[198:201], v[42:45]
	v_mfma_f32_16x16x32_bf16 v[30:33], v[148:151], v[206:209], v[30:33]
	v_mfma_f32_16x16x32_bf16 v[26:29], v[156:159], v[206:209], v[26:29]
	v_mfma_f32_16x16x32_bf16 v[14:17], v[148:151], v[214:217], v[14:17]
	v_mfma_f32_16x16x32_bf16 v[10:13], v[156:159], v[214:217], v[10:13]
	v_mfma_f32_16x16x32_bf16 v[62:65], v[152:155], v[194:197], v[62:65]
	v_mfma_f32_16x16x32_bf16 v[58:61], v[170:173], v[194:197], v[58:61]
	v_mfma_f32_16x16x32_bf16 v[46:49], v[152:155], v[202:205], v[46:49]
	v_mfma_f32_16x16x32_bf16 v[42:45], v[170:173], v[202:205], v[42:45]
	v_mfma_f32_16x16x32_bf16 v[30:33], v[152:155], v[210:213], v[30:33]
	v_mfma_f32_16x16x32_bf16 v[26:29], v[170:173], v[210:213], v[26:29]
	v_mfma_f32_16x16x32_bf16 v[14:17], v[152:155], v[218:221], v[14:17]
	v_mfma_f32_16x16x32_bf16 v[10:13], v[170:173], v[218:221], v[10:13]
	v_mfma_f32_16x16x32_bf16 v[54:57], v[174:177], v[190:193], v[54:57]
	v_mfma_f32_16x16x32_bf16 v[50:53], v[182:185], v[190:193], v[50:53]
	v_mfma_f32_16x16x32_bf16 v[38:41], v[174:177], v[198:201], v[38:41]
	v_mfma_f32_16x16x32_bf16 v[34:37], v[182:185], v[198:201], v[34:37]
	v_mfma_f32_16x16x32_bf16 v[22:25], v[174:177], v[206:209], v[22:25]
	v_mfma_f32_16x16x32_bf16 v[18:21], v[182:185], v[206:209], v[18:21]
	v_mfma_f32_16x16x32_bf16 v[6:9], v[174:177], v[214:217], v[6:9]
	v_mfma_f32_16x16x32_bf16 v[2:5], v[182:185], v[214:217], v[2:5]
	v_mfma_f32_16x16x32_bf16 v[54:57], v[178:181], v[194:197], v[54:57]
	v_mfma_f32_16x16x32_bf16 v[50:53], v[186:189], v[194:197], v[50:53]
	v_mfma_f32_16x16x32_bf16 v[38:41], v[178:181], v[202:205], v[38:41]
	v_mfma_f32_16x16x32_bf16 v[34:37], v[186:189], v[202:205], v[34:37]
	v_mfma_f32_16x16x32_bf16 v[22:25], v[178:181], v[210:213], v[22:25]
	v_mfma_f32_16x16x32_bf16 v[18:21], v[186:189], v[210:213], v[18:21]
	v_mfma_f32_16x16x32_bf16 v[6:9], v[178:181], v[218:221], v[6:9]
	v_mfma_f32_16x16x32_bf16 v[2:5], v[186:189], v[218:221], v[2:5]
	s_barrier
	s_add_i32 s66, s66, 2
	s_add_u32 s64, s64, 0x100
	s_addc_u32 s65, s65, 0
	s_cmp_gt_u32 s66, 3
	s_mov_b64 s[6:7], s[0:1]
	s_cbranch_scc0 .LBB0_780
	s_and_b64 vcc, exec, s[20:21]
	s_cbranch_vccz .LBB0_783
	s_barrier

; #define PG8_STAGE(bufoff, gbase, voff) do { _Pragma("unroll") for (int _i = 0; _i < 2; ++_i) \
;         __builtin_amdgcn_global_load_lds((const unsigned*)((const char*)(gbase) + (voff)[_i]), (PG8_LAS unsigned*)(lds + (bufoff) + ldsw + _i * 8192), 16, 0, 0); } while (0)
; #define PG8_LDA(dst, b, h) do { _Pragma("unroll") for (int m = 0; m < 4; ++m) _Pragma("unroll") for (int k = 0; k < 2; ++k) dst[m][k] = *(const PG8_LAS bf16x8*)(lds + PG8_SA(b, h) + aoff + m * 2048 + k * 1024); } while (0)
; #define PG8_LDB(dst, b, h) do { _Pragma("unroll") for (int n = 0; n < 2; ++n) _Pragma("unroll") for (int k = 0; k < 2; ++k) dst[n][k] = *(const PG8_LAS bf16x8*)(lds + PG8_SB(b, h) + boff + n * 2048 + k * 1024); } while (0)
; #define PG8_MMA(ai, bj, At, Bt) do { __builtin_amdgcn_s_setprio(1); _Pragma("unroll") for (int m = 0; m < 4; ++m) _Pragma("unroll") for (int n = 0; n < 2; ++n) _Pragma("unroll") for (int k = 0; k < 2; ++k) \
;         acc[ai][bj][m][n] = __builtin_amdgcn_mfma_f32_16x16x32_bf16(Bt[n][k], At[m][k], acc[ai][bj][m][n], 0, 0, 0); __builtin_amdgcn_s_setprio(0); } while (0)
; #define PG8_WAIT_V(n) asm volatile("s_waitcnt vmcnt(" #n ")" ::: "memory")
; #define PG8_WAIT_L(n) asm volatile("s_waitcnt lgkmcnt(" #n ")" ::: "memory")
; #define PG8_BAR __builtin_amdgcn_s_barrier()
; #define PG8_SCHED __builtin_amdgcn_sched_barrier(0)
; template <class Epi, class Sched, bool ALIGN_EPI = false, bool SP2 = false>
; __device__ __forceinline__ void gemm_phase(PG8_LAS unsigned char* lds, const Gemm g, const Sched& S, const Epi& E) {
;     ...
;             PG8_LDB(B0, 0, 0); PG8_LDB(B1, 0, 1); PG8_SCHED; PG8_LDA(At, 0, 0); PG8_STAGE(PG8_SA(1, 1), a1 + hstepA, voffA);
;             PG8_WAIT_V(8); PG8_WAIT_L(0); PG8_BAR; PG8_MMA(0, 0, At, B0); PG8_MMA(0, 1, At, B1); PG8_BAR; PG8_SCHED;
;             PG8_LDA(At, 0, 1); PG8_STAGE(PG8_SB(0, 0), b2, voffB); PG8_STAGE(PG8_SB(0, 1), b2 + hstepB, voffB); PG8_STAGE(PG8_SA(0, 0), a2, voffA);
;             PG8_WAIT_V(8); PG8_WAIT_L(0); PG8_BAR; PG8_MMA(1, 0, At, B0); PG8_MMA(1, 1, At, B1); PG8_BAR; PG8_SCHED;
.LBB0_1086:
	ds_read_b128 v[130:133], v168
	ds_read_b128 v[134:137], v168 offset:1024
	ds_read_b128 v[138:141], v168 offset:2048
	ds_read_b128 v[158:161], v168 offset:3072
	ds_read_b128 v[162:165], v169
	ds_read_b128 v[172:175], v169 offset:1024
	ds_read_b128 v[176:179], v169 offset:2048
	ds_read_b128 v[180:183], v169 offset:3072
	s_add_u32 s26, s24, 0xfffe0080
	s_addc_u32 s27, s25, -1
	s_cmp_eq_u32 s49, 4
	s_cselect_b32 s29, s17, s27
	s_cselect_b32 s28, s45, s26
	s_cselect_b32 s27, s15, s48
	s_cselect_b32 s26, s46, s47
	s_add_i32 m0, s23, 0xc000
	ds_read_b128 v[184:187], v170
	ds_read_b128 v[188:191], v170 offset:1024
	ds_read_b128 v[192:195], v170 offset:2048
	ds_read_b128 v[196:199], v170 offset:3072
	ds_read_b128 v[200:203], v170 offset:4096
	ds_read_b128 v[204:207], v170 offset:5120
	ds_read_b128 v[208:211], v170 offset:6144
	ds_read_b128 v[212:215], v170 offset:7168
	global_load_lds_dwordx4 v150, s[24:25]
	s_add_i32 m0, s23, 0xe000
	s_nop 0
	global_load_lds_dwordx4 v152, s[24:25]
	s_waitcnt vmcnt(8)
	s_waitcnt lgkmcnt(0)
	s_barrier
	s_waitcnt lgkmcnt(0)
	v_mfma_f32_16x16x32_bf16 v[126:129], v[130:133], v[184:187], v[126:129]
	v_mfma_f32_16x16x32_bf16 v[122:125], v[138:141], v[184:187], v[122:125]
	v_mfma_f32_16x16x32_bf16 v[110:113], v[130:133], v[192:195], v[110:113]
	v_mfma_f32_16x16x32_bf16 v[106:109], v[138:141], v[192:195], v[106:109]
	v_mfma_f32_16x16x32_bf16 v[94:97], v[130:133], v[200:203], v[94:97]
	v_mfma_f32_16x16x32_bf16 v[90:93], v[138:141], v[200:203], v[90:93]
	v_mfma_f32_16x16x32_bf16 v[78:81], v[130:133], v[208:211], v[78:81]
	v_mfma_f32_16x16x32_bf16 v[74:77], v[138:141], v[208:211], v[74:77]
	v_mfma_f32_16x16x32_bf16 v[126:129], v[134:137], v[188:191], v[126:129]
	v_mfma_f32_16x16x32_bf16 v[122:125], v[158:161], v[188:191], v[122:125]
	v_mfma_f32_16x16x32_bf16 v[110:113], v[134:137], v[196:199], v[110:113]
	v_mfma_f32_16x16x32_bf16 v[106:109], v[158:161], v[196:199], v[106:109]
	v_mfma_f32_16x16x32_bf16 v[94:97], v[134:137], v[204:207], v[94:97]
	v_mfma_f32_16x16x32_bf16 v[90:93], v[158:161], v[204:207], v[90:93]
	v_mfma_f32_16x16x32_bf16 v[78:81], v[134:137], v[212:215], v[78:81]
	v_mfma_f32_16x16x32_bf16 v[74:77], v[158:161], v[212:215], v[74:77]
	v_mfma_f32_16x16x32_bf16 v[118:121], v[162:165], v[184:187], v[118:121]
	v_mfma_f32_16x16x32_bf16 v[114:117], v[176:179], v[184:187], v[114:117]
	v_mfma_f32_16x16x32_bf16 v[102:105], v[162:165], v[192:195], v[102:105]
	v_mfma_f32_16x16x32_bf16 v[98:101], v[176:179], v[192:195], v[98:101]
	v_mfma_f32_16x16x32_bf16 v[86:89], v[162:165], v[200:203], v[86:89]
	v_mfma_f32_16x16x32_bf16 v[82:85], v[176:179], v[200:203], v[82:85]
	v_mfma_f32_16x16x32_bf16 v[70:73], v[162:165], v[208:211], v[70:73]
	v_mfma_f32_16x16x32_bf16 v[66:69], v[176:179], v[208:211], v[66:69]
	v_mfma_f32_16x16x32_bf16 v[118:121], v[172:175], v[188:191], v[118:121]
	v_mfma_f32_16x16x32_bf16 v[114:117], v[180:183], v[188:191], v[114:117]
	v_mfma_f32_16x16x32_bf16 v[102:105], v[172:175], v[196:199], v[102:105]
	v_mfma_f32_16x16x32_bf16 v[98:101], v[180:183], v[196:199], v[98:101]
	v_mfma_f32_16x16x32_bf16 v[86:89], v[172:175], v[204:207], v[86:89]
	v_mfma_f32_16x16x32_bf16 v[82:85], v[180:183], v[204:207], v[82:85]
	v_mfma_f32_16x16x32_bf16 v[70:73], v[172:175], v[212:215], v[70:73]
	v_mfma_f32_16x16x32_bf16 v[66:69], v[180:183], v[212:215], v[66:69]
	s_barrier
	s_add_i32 s50, s42, s34
	s_add_u32 s98, s26, 0x80
	s_addc_u32 s99, s27, 0
	s_mov_b32 m0, s50
	ds_read_b128 v[184:187], v170 offset:16384
	ds_read_b128 v[188:191], v170 offset:17408
	ds_read_b128 v[192:195], v170 offset:18432
	ds_read_b128 v[196:199], v170 offset:19456
	ds_read_b128 v[200:203], v170 offset:20480
	ds_read_b128 v[204:207], v170 offset:21504
	ds_read_b128 v[208:211], v170 offset:22528
	ds_read_b128 v[212:215], v170 offset:23552
	global_load_lds_dwordx4 v144, s[26:27]
	s_add_i32 m0, s50, 0x2000
	s_add_u32 s50, s26, 0x20000
	s_addc_u32 s51, s27, 0
	s_add_i32 s52, s43, s34
	global_load_lds_dwordx4 v148, s[26:27]
	s_mov_b32 m0, s52
	s_nop 0
	global_load_lds_dwordx4 v144, s[50:51]
	s_add_i32 m0, s52, 0x2000
	s_nop 0
	global_load_lds_dwordx4 v148, s[50:51]
	s_add_u32 s100, s28, 0x80
	s_addc_u32 s101, s29, 0
	s_mov_b32 m0, s23
	s_nop 0
	global_load_lds_dwordx4 v142, s[28:29]
	s_mov_b32 m0, s35
	s_nop 0
	global_load_lds_dwordx4 v146, s[28:29]
	s_waitcnt vmcnt(8)
	s_waitcnt lgkmcnt(0)
	s_barrier
	s_waitcnt lgkmcnt(0)
	v_mfma_f32_16x16x32_bf16 v[62:65], v[130:133], v[184:187], v[62:65]
	v_mfma_f32_16x16x32_bf16 v[58:61], v[138:141], v[184:187], v[58:61]
	v_mfma_f32_16x16x32_bf16 v[46:49], v[130:133], v[192:195], v[46:49]
	v_mfma_f32_16x16x32_bf16 v[42:45], v[138:141], v[192:195], v[42:45]
	v_mfma_f32_16x16x32_bf16 v[30:33], v[130:133], v[200:203], v[30:33]
	v_mfma_f32_16x16x32_bf16 v[26:29], v[138:141], v[200:203], v[26:29]
	v_mfma_f32_16x16x32_bf16 v[14:17], v[130:133], v[208:211], v[14:17]
	v_mfma_f32_16x16x32_bf16 v[10:13], v[138:141], v[208:211], v[10:13]
	v_mfma_f32_16x16x32_bf16 v[62:65], v[134:137], v[188:191], v[62:65]
	v_mfma_f32_16x16x32_bf16 v[58:61], v[158:161], v[188:191], v[58:61]
	v_mfma_f32_16x16x32_bf16 v[46:49], v[134:137], v[196:199], v[46:49]
	v_mfma_f32_16x16x32_bf16 v[42:45], v[158:161], v[196:199], v[42:45]
	v_mfma_f32_16x16x32_bf16 v[30:33], v[134:137], v[204:207], v[30:33]
	v_mfma_f32_16x16x32_bf16 v[26:29], v[158:161], v[204:207], v[26:29]
	v_mfma_f32_16x16x32_bf16 v[14:17], v[134:137], v[212:215], v[14:17]
	v_mfma_f32_16x16x32_bf16 v[10:13], v[158:161], v[212:215], v[10:13]
	v_mfma_f32_16x16x32_bf16 v[54:57], v[162:165], v[184:187], v[54:57]
	v_mfma_f32_16x16x32_bf16 v[50:53], v[176:179], v[184:187], v[50:53]
	v_mfma_f32_16x16x32_bf16 v[38:41], v[162:165], v[192:195], v[38:41]
	v_mfma_f32_16x16x32_bf16 v[34:37], v[176:179], v[192:195], v[34:37]
	v_mfma_f32_16x16x32_bf16 v[22:25], v[162:165], v[200:203], v[22:25]
	v_mfma_f32_16x16x32_bf16 v[18:21], v[176:179], v[200:203], v[18:21]
	v_mfma_f32_16x16x32_bf16 v[6:9], v[162:165], v[208:211], v[6:9]
	v_mfma_f32_16x16x32_bf16 v[2:5], v[176:179], v[208:211], v[2:5]
	v_mfma_f32_16x16x32_bf16 v[54:57], v[172:175], v[188:191], v[54:57]
	v_mfma_f32_16x16x32_bf16 v[50:53], v[180:183], v[188:191], v[50:53]
	v_mfma_f32_16x16x32_bf16 v[38:41], v[172:175], v[196:199], v[38:41]
	v_mfma_f32_16x16x32_bf16 v[34:37], v[180:183], v[196:199], v[34:37]
	v_mfma_f32_16x16x32_bf16 v[22:25], v[172:175], v[204:207], v[22:25]
	v_mfma_f32_16x16x32_bf16 v[18:21], v[180:183], v[204:207], v[18:21]
	v_mfma_f32_16x16x32_bf16 v[6:9], v[172:175], v[212:215], v[6:9]
	v_mfma_f32_16x16x32_bf16 v[2:5], v[180:183], v[212:215], v[2:5]
	s_barrier
; #define PG8_STAGE(bufoff, gbase, voff) do { _Pragma("unroll") for (int _i = 0; _i < 2; ++_i) \
;         __builtin_amdgcn_global_load_lds((const unsigned*)((const char*)(gbase) + (voff)[_i]), (PG8_LAS unsigned*)(lds + (bufoff) + ldsw + _i * 8192), 16, 0, 0); } while (0)
; #define PG8_LDA(dst, b, h) do { _Pragma("unroll") for (int m = 0; m < 4; ++m) _Pragma("unroll") for (int k = 0; k < 2; ++k) dst[m][k] = *(const PG8_LAS bf16x8*)(lds + PG8_SA(b, h) + aoff + m * 2048 + k * 1024); } while (0)
; #define PG8_LDB(dst, b, h) do { _Pragma("unroll") for (int n = 0; n < 2; ++n) _Pragma("unroll") for (int k = 0; k < 2; ++k) dst[n][k] = *(const PG8_LAS bf16x8*)(lds + PG8_SB(b, h) + boff + n * 2048 + k * 1024); } while (0)
; #define PG8_MMA(ai, bj, At, Bt) do { __builtin_amdgcn_s_setprio(1); _Pragma("unroll") for (int m = 0; m < 4; ++m) _Pragma("unroll") for (int n = 0; n < 2; ++n) _Pragma("unroll") for (int k = 0; k < 2; ++k) \
;         acc[ai][bj][m][n] = __builtin_amdgcn_mfma_f32_16x16x32_bf16(Bt[n][k], At[m][k], acc[ai][bj][m][n], 0, 0, 0); __builtin_amdgcn_s_setprio(0); } while (0)
; #define PG8_WAIT_V(n) asm volatile("s_waitcnt vmcnt(" #n ")" ::: "memory")
; #define PG8_WAIT_L(n) asm volatile("s_waitcnt lgkmcnt(" #n ")" ::: "memory")
; #define PG8_BAR __builtin_amdgcn_s_barrier()
; #define PG8_SCHED __builtin_amdgcn_sched_barrier(0)
; template <class Epi, class Sched, bool ALIGN_EPI = false, bool SP2 = false>
; __device__ __forceinline__ void gemm_phase(PG8_LAS unsigned char* lds, const Gemm g, const Sched& S, const Epi& E) {
;     ...
;             PG8_LDB(B0, 1, 0); PG8_LDB(B1, 1, 1); PG8_SCHED; PG8_LDA(At, 1, 0); PG8_STAGE(PG8_SA(0, 1), a2 + hstepA, voffA);
;             PG8_WAIT_V(8); PG8_WAIT_L(0); PG8_BAR; PG8_MMA(0, 0, At, B0); PG8_MMA(0, 1, At, B1); PG8_BAR; PG8_SCHED;
;             PG8_LDA(At, 1, 1); PG8_STAGE(PG8_SB(1, 0), b3, voffB); PG8_STAGE(PG8_SB(1, 1), b3 + hstepB, voffB); PG8_STAGE(PG8_SA(1, 0), a3, voffA);
;             PG8_WAIT_V(8); PG8_WAIT_L(0); PG8_BAR; PG8_MMA(1, 0, At, B0); PG8_MMA(1, 1, At, B1); PG8_BAR; PG8_SCHED;
	s_add_i32 s50, 0, 0x18000
	s_add_i32 s51, 0, 0x1c000
	v_add_u32_e32 v158, s50, v166
	v_add_u32_e32 v171, s51, v166
	ds_read_b128 v[130:133], v158
	ds_read_b128 v[134:137], v158 offset:1024
	ds_read_b128 v[138:141], v158 offset:2048
	ds_read_b128 v[158:161], v158 offset:3072
	ds_read_b128 v[162:165], v171
	ds_read_b128 v[172:175], v171 offset:1024
	ds_read_b128 v[176:179], v171 offset:2048
	ds_read_b128 v[180:183], v171 offset:3072
	s_add_u32 s28, s28, 0x20000
	s_addc_u32 s29, s29, 0
	s_mov_b32 m0, s36
	ds_read_b128 v[184:187], v170 offset:32768
	ds_read_b128 v[188:191], v170 offset:33792
	ds_read_b128 v[192:195], v170 offset:34816
	ds_read_b128 v[196:199], v170 offset:35840
	ds_read_b128 v[200:203], v170 offset:36864
	ds_read_b128 v[204:207], v170 offset:37888
	ds_read_b128 v[208:211], v170 offset:38912
	ds_read_b128 v[212:215], v170 offset:39936
	global_load_lds_dwordx4 v142, s[28:29]
	s_mov_b32 m0, s37
	s_nop 0
	global_load_lds_dwordx4 v146, s[28:29]
	s_waitcnt vmcnt(8)
	s_waitcnt lgkmcnt(0)
	s_barrier
	s_waitcnt lgkmcnt(0)
	v_mfma_f32_16x16x32_bf16 v[126:129], v[130:133], v[184:187], v[126:129]
	v_mfma_f32_16x16x32_bf16 v[122:125], v[138:141], v[184:187], v[122:125]
	v_mfma_f32_16x16x32_bf16 v[110:113], v[130:133], v[192:195], v[110:113]
	v_mfma_f32_16x16x32_bf16 v[106:109], v[138:141], v[192:195], v[106:109]
	v_mfma_f32_16x16x32_bf16 v[94:97], v[130:133], v[200:203], v[94:97]
	v_mfma_f32_16x16x32_bf16 v[90:93], v[138:141], v[200:203], v[90:93]
	v_mfma_f32_16x16x32_bf16 v[78:81], v[130:133], v[208:211], v[78:81]
	v_mfma_f32_16x16x32_bf16 v[74:77], v[138:141], v[208:211], v[74:77]
	v_mfma_f32_16x16x32_bf16 v[126:129], v[134:137], v[188:191], v[126:129]
	v_mfma_f32_16x16x32_bf16 v[122:125], v[158:161], v[188:191], v[122:125]
	v_mfma_f32_16x16x32_bf16 v[110:113], v[134:137], v[196:199], v[110:113]
	v_mfma_f32_16x16x32_bf16 v[106:109], v[158:161], v[196:199], v[106:109]
	v_mfma_f32_16x16x32_bf16 v[94:97], v[134:137], v[204:207], v[94:97]
	v_mfma_f32_16x16x32_bf16 v[90:93], v[158:161], v[204:207], v[90:93]
	v_mfma_f32_16x16x32_bf16 v[78:81], v[134:137], v[212:215], v[78:81]
	v_mfma_f32_16x16x32_bf16 v[74:77], v[158:161], v[212:215], v[74:77]
	v_mfma_f32_16x16x32_bf16 v[118:121], v[162:165], v[184:187], v[118:121]
	v_mfma_f32_16x16x32_bf16 v[114:117], v[176:179], v[184:187], v[114:117]
	v_mfma_f32_16x16x32_bf16 v[102:105], v[162:165], v[192:195], v[102:105]
	v_mfma_f32_16x16x32_bf16 v[98:101], v[176:179], v[192:195], v[98:101]
	v_mfma_f32_16x16x32_bf16 v[86:89], v[162:165], v[200:203], v[86:89]
	v_mfma_f32_16x16x32_bf16 v[82:85], v[176:179], v[200:203], v[82:85]
	v_mfma_f32_16x16x32_bf16 v[70:73], v[162:165], v[208:211], v[70:73]
	v_mfma_f32_16x16x32_bf16 v[66:69], v[176:179], v[208:211], v[66:69]
	v_mfma_f32_16x16x32_bf16 v[118:121], v[172:175], v[188:191], v[118:121]
	v_mfma_f32_16x16x32_bf16 v[114:117], v[180:183], v[188:191], v[114:117]
	v_mfma_f32_16x16x32_bf16 v[102:105], v[172:175], v[196:199], v[102:105]
	v_mfma_f32_16x16x32_bf16 v[98:101], v[180:183], v[196:199], v[98:101]
	v_mfma_f32_16x16x32_bf16 v[86:89], v[172:175], v[204:207], v[86:89]
	v_mfma_f32_16x16x32_bf16 v[82:85], v[180:183], v[204:207], v[82:85]
	v_mfma_f32_16x16x32_bf16 v[70:73], v[172:175], v[212:215], v[70:73]
	v_mfma_f32_16x16x32_bf16 v[66:69], v[180:183], v[212:215], v[66:69]
	s_barrier
	s_add_i32 s28, s50, s34
	s_mov_b32 m0, s28
	ds_read_b128 v[184:187], v170 offset:49152
	ds_read_b128 v[188:191], v170 offset:50176
	ds_read_b128 v[192:195], v170 offset:51200
	ds_read_b128 v[196:199], v170 offset:52224
	ds_read_b128 v[200:203], v170 offset:53248
	ds_read_b128 v[204:207], v170 offset:54272
	ds_read_b128 v[208:211], v170 offset:55296
	ds_read_b128 v[212:215], v170 offset:56320
	global_load_lds_dwordx4 v144, s[98:99]
	s_add_i32 m0, s28, 0x2000
	s_add_u32 s26, s26, 0x20080
	s_addc_u32 s27, s27, 0
	s_add_i32 s28, s51, s34
	global_load_lds_dwordx4 v148, s[98:99]
	s_mov_b32 m0, s28
	s_nop 0
	global_load_lds_dwordx4 v144, s[26:27]
	s_add_i32 m0, s28, 0x2000
	s_nop 0
	global_load_lds_dwordx4 v148, s[26:27]
	s_mov_b32 m0, s39
	s_nop 0
	global_load_lds_dwordx4 v142, s[100:101]
	s_mov_b32 m0, s40
	s_nop 0
	global_load_lds_dwordx4 v146, s[100:101]
	s_waitcnt vmcnt(8)
	s_waitcnt lgkmcnt(0)
	s_barrier
	s_waitcnt lgkmcnt(0)
	v_mfma_f32_16x16x32_bf16 v[62:65], v[130:133], v[184:187], v[62:65]
	v_mfma_f32_16x16x32_bf16 v[58:61], v[138:141], v[184:187], v[58:61]
	v_mfma_f32_16x16x32_bf16 v[46:49], v[130:133], v[192:195], v[46:49]
	v_mfma_f32_16x16x32_bf16 v[42:45], v[138:141], v[192:195], v[42:45]
	v_mfma_f32_16x16x32_bf16 v[30:33], v[130:133], v[200:203], v[30:33]
	v_mfma_f32_16x16x32_bf16 v[26:29], v[138:141], v[200:203], v[26:29]
	v_mfma_f32_16x16x32_bf16 v[14:17], v[130:133], v[208:211], v[14:17]
	v_mfma_f32_16x16x32_bf16 v[10:13], v[138:141], v[208:211], v[10:13]
	v_mfma_f32_16x16x32_bf16 v[62:65], v[134:137], v[188:191], v[62:65]
	v_mfma_f32_16x16x32_bf16 v[58:61], v[158:161], v[188:191], v[58:61]
	v_mfma_f32_16x16x32_bf16 v[46:49], v[134:137], v[196:199], v[46:49]
	v_mfma_f32_16x16x32_bf16 v[42:45], v[158:161], v[196:199], v[42:45]
	v_mfma_f32_16x16x32_bf16 v[30:33], v[134:137], v[204:207], v[30:33]
	v_mfma_f32_16x16x32_bf16 v[26:29], v[158:161], v[204:207], v[26:29]
	v_mfma_f32_16x16x32_bf16 v[14:17], v[134:137], v[212:215], v[14:17]
	v_mfma_f32_16x16x32_bf16 v[10:13], v[158:161], v[212:215], v[10:13]
	v_mfma_f32_16x16x32_bf16 v[54:57], v[162:165], v[184:187], v[54:57]
	v_mfma_f32_16x16x32_bf16 v[50:53], v[176:179], v[184:187], v[50:53]
	v_mfma_f32_16x16x32_bf16 v[38:41], v[162:165], v[192:195], v[38:41]
	v_mfma_f32_16x16x32_bf16 v[34:37], v[176:179], v[192:195], v[34:37]
	v_mfma_f32_16x16x32_bf16 v[22:25], v[162:165], v[200:203], v[22:25]
	v_mfma_f32_16x16x32_bf16 v[18:21], v[176:179], v[200:203], v[18:21]
	v_mfma_f32_16x16x32_bf16 v[6:9], v[162:165], v[208:211], v[6:9]
	v_mfma_f32_16x16x32_bf16 v[2:5], v[176:179], v[208:211], v[2:5]
	v_mfma_f32_16x16x32_bf16 v[54:57], v[172:175], v[188:191], v[54:57]
	v_mfma_f32_16x16x32_bf16 v[50:53], v[180:183], v[188:191], v[50:53]
	v_mfma_f32_16x16x32_bf16 v[38:41], v[172:175], v[196:199], v[38:41]
	v_mfma_f32_16x16x32_bf16 v[34:37], v[180:183], v[196:199], v[34:37]
	v_mfma_f32_16x16x32_bf16 v[22:25], v[172:175], v[204:207], v[22:25]
	v_mfma_f32_16x16x32_bf16 v[18:21], v[180:183], v[204:207], v[18:21]
	v_mfma_f32_16x16x32_bf16 v[6:9], v[172:175], v[212:215], v[6:9]
	v_mfma_f32_16x16x32_bf16 v[2:5], v[180:183], v[212:215], v[2:5]
	s_barrier
	s_add_i32 s49, s49, 2
	s_add_u32 s24, s24, 0x100
	s_addc_u32 s25, s25, 0
	s_add_u32 s47, s47, 0x100
	s_addc_u32 s48, s48, 0
	s_cmp_gt_u32 s49, 5
	s_cbranch_scc0 .LBB0_1086
	s_and_b64 vcc, exec, s[12:13]
	s_cbranch_vccz .LBB0_1089
	s_barrier

; #define PG8_STAGE(bufoff, gbase, voff) do { _Pragma("unroll") for (int _i = 0; _i < 2; ++_i) \
;         __builtin_amdgcn_global_load_lds((const unsigned*)((const char*)(gbase) + (voff)[_i]), (PG8_LAS unsigned*)(lds + (bufoff) + ldsw + _i * 8192), 16, 0, 0); } while (0)
; #define PG8_LDA(dst, b, h) do { _Pragma("unroll") for (int m = 0; m < 4; ++m) _Pragma("unroll") for (int k = 0; k < 2; ++k) dst[m][k] = *(const PG8_LAS bf16x8*)(lds + PG8_SA(b, h) + aoff + m * 2048 + k * 1024); } while (0)
; #define PG8_LDB(dst, b, h) do { _Pragma("unroll") for (int n = 0; n < 2; ++n) _Pragma("unroll") for (int k = 0; k < 2; ++k) dst[n][k] = *(const PG8_LAS bf16x8*)(lds + PG8_SB(b, h) + boff + n * 2048 + k * 1024); } while (0)
; #define PG8_MMA(ai, bj, At, Bt) do { __builtin_amdgcn_s_setprio(1); _Pragma("unroll") for (int m = 0; m < 4; ++m) _Pragma("unroll") for (int n = 0; n < 2; ++n) _Pragma("unroll") for (int k = 0; k < 2; ++k) \
;         acc[ai][bj][m][n] = __builtin_amdgcn_mfma_f32_16x16x32_bf16(Bt[n][k], At[m][k], acc[ai][bj][m][n], 0, 0, 0); __builtin_amdgcn_s_setprio(0); } while (0)
; #define PG8_WAIT_V(n) asm volatile("s_waitcnt vmcnt(" #n ")" ::: "memory")
; #define PG8_WAIT_L(n) asm volatile("s_waitcnt lgkmcnt(" #n ")" ::: "memory")
; #define PG8_BAR __builtin_amdgcn_s_barrier()
; #define PG8_SCHED __builtin_amdgcn_sched_barrier(0)
; template <class Epi, class Sched, bool ALIGN_EPI = false, bool SP2 = false>
; __device__ __forceinline__ void gemm_phase(PG8_LAS unsigned char* lds, const Gemm g, const Sched& S, const Epi& E) {
;     ...
;             PG8_LDB(B0, 0, 0); PG8_LDB(B1, 0, 1); PG8_SCHED; PG8_LDA(At, 0, 0); PG8_STAGE(PG8_SA(1, 1), a1 + hstepA, voffA);
;             PG8_WAIT_V(8); PG8_WAIT_L(0); PG8_BAR; PG8_MMA(0, 0, At, B0); PG8_MMA(0, 1, At, B1); PG8_BAR; PG8_SCHED;
;             PG8_LDA(At, 0, 1); PG8_STAGE(PG8_SB(0, 0), b2, voffB); PG8_STAGE(PG8_SB(0, 1), b2 + hstepB, voffB); PG8_STAGE(PG8_SA(0, 0), a2, voffA);
;             PG8_WAIT_V(8); PG8_WAIT_L(0); PG8_BAR; PG8_MMA(1, 0, At, B0); PG8_MMA(1, 1, At, B1); PG8_BAR; PG8_SCHED;
.LBB0_1269:
	v_add_u32_e32 v24, s56, v22
	ds_read_b128 v[50:53], v24
	ds_read_b128 v[54:57], v24 offset:1024
	ds_read_b128 v[70:73], v24 offset:2048
	ds_read_b128 v[74:77], v24 offset:3072
	v_add_u32_e32 v24, s57, v22
	s_add_u32 s36, s20, s34
	ds_read_b128 v[78:81], v24
	ds_read_b128 v[90:93], v24 offset:1024
	ds_read_b128 v[94:97], v24 offset:2048
	ds_read_b128 v[154:157], v24 offset:3072
	s_addc_u32 s37, s21, s35
	s_add_u32 s36, s36, 0x100
	s_addc_u32 s37, s37, 0
	s_add_u32 s64, s59, s34
	s_addc_u32 s65, s60, s35
	s_cmpk_eq_i32 s34, 0x700
	s_cselect_b32 s39, s27, s37
	s_cselect_b32 s38, s61, s36
	s_cselect_b32 s37, s25, s65
	s_cselect_b32 s36, s62, s64
	v_lshl_add_u64 v[24:25], v[18:19], 0, s[34:35]
	s_add_i32 m0, s48, 0xc000
	ds_read_b128 v[158:161], v23
	ds_read_b128 v[178:181], v23 offset:1024
	ds_read_b128 v[194:197], v23 offset:2048
	ds_read_b128 v[198:201], v23 offset:3072
	ds_read_b128 v[202:205], v23 offset:4096
	ds_read_b128 v[206:209], v23 offset:5120
	ds_read_b128 v[210:213], v23 offset:6144
	ds_read_b128 v[214:217], v23 offset:7168
	global_load_lds_dwordx4 v[24:25], off
	v_lshl_add_u64 v[24:25], v[20:21], 0, s[34:35]
	s_add_i32 m0, s48, 0xe000
	s_nop 0
	global_load_lds_dwordx4 v[24:25], off
	s_waitcnt vmcnt(8)
	s_waitcnt lgkmcnt(0)
	s_barrier
	s_waitcnt lgkmcnt(0)
	v_mfma_f32_16x16x32_bf16 v[62:65], v[50:53], v[158:161], v[62:65]
	v_mfma_f32_16x16x32_bf16 v[170:173], v[70:73], v[158:161], v[170:173]
	v_mfma_f32_16x16x32_bf16 v[166:169], v[50:53], v[194:197], v[166:169]
	v_mfma_f32_16x16x32_bf16 v[162:165], v[70:73], v[194:197], v[162:165]
	v_mfma_f32_16x16x32_bf16 v[174:177], v[50:53], v[202:205], v[174:177]
	v_mfma_f32_16x16x32_bf16 v[190:193], v[70:73], v[202:205], v[190:193]
	v_mfma_f32_16x16x32_bf16 v[186:189], v[50:53], v[210:213], v[186:189]
	v_mfma_f32_16x16x32_bf16 v[182:185], v[70:73], v[210:213], v[182:185]
	v_mfma_f32_16x16x32_bf16 v[62:65], v[54:57], v[178:181], v[62:65]
	v_mfma_f32_16x16x32_bf16 v[170:173], v[74:77], v[178:181], v[170:173]
	v_mfma_f32_16x16x32_bf16 v[166:169], v[54:57], v[198:201], v[166:169]
	v_mfma_f32_16x16x32_bf16 v[162:165], v[74:77], v[198:201], v[162:165]
	v_mfma_f32_16x16x32_bf16 v[174:177], v[54:57], v[206:209], v[174:177]
	v_mfma_f32_16x16x32_bf16 v[190:193], v[74:77], v[206:209], v[190:193]
	v_mfma_f32_16x16x32_bf16 v[186:189], v[54:57], v[214:217], v[186:189]
	v_mfma_f32_16x16x32_bf16 v[182:185], v[74:77], v[214:217], v[182:185]
	v_mfma_f32_16x16x32_bf16 v[86:89], v[78:81], v[158:161], v[86:89]
	v_mfma_f32_16x16x32_bf16 v[82:85], v[94:97], v[158:161], v[82:85]
	v_mfma_f32_16x16x32_bf16 v[66:69], v[78:81], v[194:197], v[66:69]
	v_mfma_f32_16x16x32_bf16 v[58:61], v[94:97], v[194:197], v[58:61]
	v_mfma_f32_16x16x32_bf16 v[114:117], v[78:81], v[202:205], v[114:117]
	v_mfma_f32_16x16x32_bf16 v[110:113], v[94:97], v[202:205], v[110:113]
	v_mfma_f32_16x16x32_bf16 v[106:109], v[78:81], v[210:213], v[106:109]
	v_mfma_f32_16x16x32_bf16 v[102:105], v[94:97], v[210:213], v[102:105]
	v_mfma_f32_16x16x32_bf16 v[86:89], v[90:93], v[178:181], v[86:89]
	v_mfma_f32_16x16x32_bf16 v[82:85], v[154:157], v[178:181], v[82:85]
	v_mfma_f32_16x16x32_bf16 v[66:69], v[90:93], v[198:201], v[66:69]
	v_mfma_f32_16x16x32_bf16 v[58:61], v[154:157], v[198:201], v[58:61]
	v_mfma_f32_16x16x32_bf16 v[114:117], v[90:93], v[206:209], v[114:117]
	v_mfma_f32_16x16x32_bf16 v[110:113], v[154:157], v[206:209], v[110:113]
	v_mfma_f32_16x16x32_bf16 v[106:109], v[90:93], v[214:217], v[106:109]
	v_mfma_f32_16x16x32_bf16 v[102:105], v[154:157], v[214:217], v[102:105]
	s_barrier
	s_add_i32 s64, s56, s47
	s_add_u32 s98, s36, 0x80
	s_addc_u32 s99, s37, 0
	s_mov_b32 m0, s64
	ds_read_b128 v[158:161], v23 offset:16384
	ds_read_b128 v[178:181], v23 offset:17408
	ds_read_b128 v[194:197], v23 offset:18432
	ds_read_b128 v[198:201], v23 offset:19456
	ds_read_b128 v[202:205], v23 offset:20480
	ds_read_b128 v[206:209], v23 offset:21504
	ds_read_b128 v[210:213], v23 offset:22528
	ds_read_b128 v[214:217], v23 offset:23552
	global_load_lds_dwordx4 v4, s[36:37]
	s_add_i32 m0, s64, 0x2000
	s_add_u32 s64, s36, 0x40000
	s_addc_u32 s65, s37, 0
	s_add_i32 s66, s57, s47
	global_load_lds_dwordx4 v8, s[36:37]
	s_mov_b32 m0, s66
	s_add_u32 s100, s38, 0x80
	s_addc_u32 s101, s39, 0
	global_load_lds_dwordx4 v4, s[64:65]
	s_add_i32 m0, s66, 0x2000
	s_nop 0
	global_load_lds_dwordx4 v8, s[64:65]
	s_mov_b32 m0, s48
	s_nop 0
	global_load_lds_dwordx4 v2, s[38:39]
	s_mov_b32 m0, s49
	s_nop 0
	global_load_lds_dwordx4 v6, s[38:39]
	s_waitcnt vmcnt(8)
	s_waitcnt lgkmcnt(0)
	s_barrier
; #define PG8_STAGE(bufoff, gbase, voff) do { _Pragma("unroll") for (int _i = 0; _i < 2; ++_i) \
;         __builtin_amdgcn_global_load_lds((const unsigned*)((const char*)(gbase) + (voff)[_i]), (PG8_LAS unsigned*)(lds + (bufoff) + ldsw + _i * 8192), 16, 0, 0); } while (0)
; #define PG8_LDA(dst, b, h) do { _Pragma("unroll") for (int m = 0; m < 4; ++m) _Pragma("unroll") for (int k = 0; k < 2; ++k) dst[m][k] = *(const PG8_LAS bf16x8*)(lds + PG8_SA(b, h) + aoff + m * 2048 + k * 1024); } while (0)
; #define PG8_LDB(dst, b, h) do { _Pragma("unroll") for (int n = 0; n < 2; ++n) _Pragma("unroll") for (int k = 0; k < 2; ++k) dst[n][k] = *(const PG8_LAS bf16x8*)(lds + PG8_SB(b, h) + boff + n * 2048 + k * 1024); } while (0)
; #define PG8_MMA(ai, bj, At, Bt) do { __builtin_amdgcn_s_setprio(1); _Pragma("unroll") for (int m = 0; m < 4; ++m) _Pragma("unroll") for (int n = 0; n < 2; ++n) _Pragma("unroll") for (int k = 0; k < 2; ++k) \
;         acc[ai][bj][m][n] = __builtin_amdgcn_mfma_f32_16x16x32_bf16(Bt[n][k], At[m][k], acc[ai][bj][m][n], 0, 0, 0); __builtin_amdgcn_s_setprio(0); } while (0)
; #define PG8_WAIT_V(n) asm volatile("s_waitcnt vmcnt(" #n ")" ::: "memory")
; #define PG8_WAIT_L(n) asm volatile("s_waitcnt lgkmcnt(" #n ")" ::: "memory")
; #define PG8_BAR __builtin_amdgcn_s_barrier()
; #define PG8_SCHED __builtin_amdgcn_sched_barrier(0)
; template <class Epi, class Sched, bool ALIGN_EPI = false, bool SP2 = false>
; __device__ __forceinline__ void gemm_phase(PG8_LAS unsigned char* lds, const Gemm g, const Sched& S, const Epi& E) {
;     ...
;             PG8_WAIT_V(8); PG8_WAIT_L(0); PG8_BAR; PG8_MMA(1, 0, At, B0); PG8_MMA(1, 1, At, B1); PG8_BAR; PG8_SCHED;
;             PG8_LDB(B0, 1, 0); PG8_LDB(B1, 1, 1); PG8_SCHED; PG8_LDA(At, 1, 0); PG8_STAGE(PG8_SA(0, 1), a2 + hstepA, voffA);
;             PG8_WAIT_V(8); PG8_WAIT_L(0); PG8_BAR; PG8_MMA(0, 0, At, B0); PG8_MMA(0, 1, At, B1); PG8_BAR; PG8_SCHED;
	s_waitcnt lgkmcnt(0)
	v_mfma_f32_16x16x32_bf16 v[150:153], v[50:53], v[158:161], v[150:153]
	v_mfma_f32_16x16x32_bf16 v[146:149], v[70:73], v[158:161], v[146:149]
	v_mfma_f32_16x16x32_bf16 v[142:145], v[50:53], v[194:197], v[142:145]
	v_mfma_f32_16x16x32_bf16 v[138:141], v[70:73], v[194:197], v[138:141]
	v_mfma_f32_16x16x32_bf16 v[126:129], v[50:53], v[202:205], v[126:129]
	v_mfma_f32_16x16x32_bf16 v[98:101], v[70:73], v[202:205], v[98:101]
	v_mfma_f32_16x16x32_bf16 v[46:49], v[50:53], v[210:213], v[46:49]
	v_mfma_f32_16x16x32_bf16 v[42:45], v[70:73], v[210:213], v[42:45]
	v_mfma_f32_16x16x32_bf16 v[150:153], v[54:57], v[178:181], v[150:153]
	v_mfma_f32_16x16x32_bf16 v[146:149], v[74:77], v[178:181], v[146:149]
	v_mfma_f32_16x16x32_bf16 v[142:145], v[54:57], v[198:201], v[142:145]
	v_mfma_f32_16x16x32_bf16 v[138:141], v[74:77], v[198:201], v[138:141]
	v_mfma_f32_16x16x32_bf16 v[126:129], v[54:57], v[206:209], v[126:129]
	v_mfma_f32_16x16x32_bf16 v[98:101], v[74:77], v[206:209], v[98:101]
	v_mfma_f32_16x16x32_bf16 v[46:49], v[54:57], v[214:217], v[46:49]
	v_mfma_f32_16x16x32_bf16 v[42:45], v[74:77], v[214:217], v[42:45]
	v_mfma_f32_16x16x32_bf16 v[38:41], v[78:81], v[202:205], v[38:41]
	v_mfma_f32_16x16x32_bf16 v[34:37], v[94:97], v[202:205], v[34:37]
	v_mfma_f32_16x16x32_bf16 v[30:33], v[78:81], v[210:213], v[30:33]
	v_mfma_f32_16x16x32_bf16 v[24:27], v[94:97], v[210:213], v[26:29]
	v_mfma_f32_16x16x32_bf16 v[50:53], v[78:81], v[158:161], v[134:137]
	v_mfma_f32_16x16x32_bf16 v[54:57], v[94:97], v[158:161], v[130:133]
	v_mfma_f32_16x16x32_bf16 v[70:73], v[78:81], v[194:197], v[122:125]
	v_mfma_f32_16x16x32_bf16 v[74:77], v[94:97], v[194:197], v[118:121]
	v_mfma_f32_16x16x32_bf16 v[38:41], v[90:93], v[206:209], v[38:41]
	v_mfma_f32_16x16x32_bf16 v[34:37], v[154:157], v[206:209], v[34:37]
	v_mfma_f32_16x16x32_bf16 v[30:33], v[90:93], v[214:217], v[30:33]
	v_mfma_f32_16x16x32_bf16 v[24:27], v[154:157], v[214:217], v[24:27]
	v_mfma_f32_16x16x32_bf16 v[50:53], v[90:93], v[178:181], v[50:53]
	v_mfma_f32_16x16x32_bf16 v[54:57], v[154:157], v[178:181], v[54:57]
	v_mfma_f32_16x16x32_bf16 v[70:73], v[90:93], v[198:201], v[70:73]
	v_mfma_f32_16x16x32_bf16 v[74:77], v[154:157], v[198:201], v[74:77]
	s_barrier
	s_add_i32 s64, 0, 0x18000
	v_add_u32_e32 v28, s64, v22
	s_add_i32 s65, 0, 0x1c000
	ds_read_b128 v[78:81], v28
	ds_read_b128 v[90:93], v28 offset:1024
	ds_read_b128 v[94:97], v28 offset:2048
	ds_read_b128 v[118:121], v28 offset:3072
	v_add_u32_e32 v28, s65, v22
	ds_read_b128 v[154:157], v28
	ds_read_b128 v[158:161], v28 offset:1024
	ds_read_b128 v[178:181], v28 offset:2048
	ds_read_b128 v[194:197], v28 offset:3072
	s_add_u32 s38, s38, 0x40000
	s_addc_u32 s39, s39, 0
	s_mov_b32 m0, s51
	ds_read_b128 v[122:125], v23 offset:32768
	ds_read_b128 v[130:133], v23 offset:33792
	ds_read_b128 v[134:137], v23 offset:34816
	ds_read_b128 v[198:201], v23 offset:35840
	ds_read_b128 v[202:205], v23 offset:36864
	ds_read_b128 v[206:209], v23 offset:37888
	ds_read_b128 v[210:213], v23 offset:38912
	ds_read_b128 v[214:217], v23 offset:39936
	global_load_lds_dwordx4 v2, s[38:39]
	s_mov_b32 m0, s52
	s_nop 0
	global_load_lds_dwordx4 v6, s[38:39]
	s_waitcnt vmcnt(8)
	s_waitcnt lgkmcnt(0)
	s_barrier
	s_waitcnt lgkmcnt(0)
	v_mfma_f32_16x16x32_bf16 v[62:65], v[78:81], v[122:125], v[62:65]
	v_mfma_f32_16x16x32_bf16 v[170:173], v[94:97], v[122:125], v[170:173]
	v_mfma_f32_16x16x32_bf16 v[166:169], v[78:81], v[134:137], v[166:169]
	v_mfma_f32_16x16x32_bf16 v[162:165], v[94:97], v[134:137], v[162:165]
	v_mfma_f32_16x16x32_bf16 v[174:177], v[78:81], v[202:205], v[174:177]
	v_mfma_f32_16x16x32_bf16 v[190:193], v[94:97], v[202:205], v[190:193]
	v_mfma_f32_16x16x32_bf16 v[186:189], v[78:81], v[210:213], v[186:189]
	v_mfma_f32_16x16x32_bf16 v[182:185], v[94:97], v[210:213], v[182:185]
	v_mfma_f32_16x16x32_bf16 v[62:65], v[90:93], v[130:133], v[62:65]
	v_mfma_f32_16x16x32_bf16 v[170:173], v[118:121], v[130:133], v[170:173]
	v_mfma_f32_16x16x32_bf16 v[166:169], v[90:93], v[198:201], v[166:169]
	v_mfma_f32_16x16x32_bf16 v[162:165], v[118:121], v[198:201], v[162:165]
	v_mfma_f32_16x16x32_bf16 v[174:177], v[90:93], v[206:209], v[174:177]
	v_mfma_f32_16x16x32_bf16 v[190:193], v[118:121], v[206:209], v[190:193]
	v_mfma_f32_16x16x32_bf16 v[186:189], v[90:93], v[214:217], v[186:189]
	v_mfma_f32_16x16x32_bf16 v[182:185], v[118:121], v[214:217], v[182:185]
	v_mfma_f32_16x16x32_bf16 v[86:89], v[154:157], v[122:125], v[86:89]
	v_mfma_f32_16x16x32_bf16 v[82:85], v[178:181], v[122:125], v[82:85]
	v_mfma_f32_16x16x32_bf16 v[66:69], v[154:157], v[134:137], v[66:69]
	v_mfma_f32_16x16x32_bf16 v[58:61], v[178:181], v[134:137], v[58:61]
	v_mfma_f32_16x16x32_bf16 v[114:117], v[154:157], v[202:205], v[114:117]
	v_mfma_f32_16x16x32_bf16 v[110:113], v[178:181], v[202:205], v[110:113]
	v_mfma_f32_16x16x32_bf16 v[106:109], v[154:157], v[210:213], v[106:109]
	v_mfma_f32_16x16x32_bf16 v[102:105], v[178:181], v[210:213], v[102:105]
	v_mfma_f32_16x16x32_bf16 v[86:89], v[158:161], v[130:133], v[86:89]
	v_mfma_f32_16x16x32_bf16 v[82:85], v[194:197], v[130:133], v[82:85]
	v_mfma_f32_16x16x32_bf16 v[66:69], v[158:161], v[198:201], v[66:69]
	v_mfma_f32_16x16x32_bf16 v[58:61], v[194:197], v[198:201], v[58:61]
	v_mfma_f32_16x16x32_bf16 v[114:117], v[158:161], v[206:209], v[114:117]
	v_mfma_f32_16x16x32_bf16 v[110:113], v[194:197], v[206:209], v[110:113]
	v_mfma_f32_16x16x32_bf16 v[106:109], v[158:161], v[214:217], v[106:109]
	v_mfma_f32_16x16x32_bf16 v[102:105], v[194:197], v[214:217], v[102:105]
	s_barrier
; #define PG8_STAGE(bufoff, gbase, voff) do { _Pragma("unroll") for (int _i = 0; _i < 2; ++_i) \
;         __builtin_amdgcn_global_load_lds((const unsigned*)((const char*)(gbase) + (voff)[_i]), (PG8_LAS unsigned*)(lds + (bufoff) + ldsw + _i * 8192), 16, 0, 0); } while (0)
; #define PG8_LDA(dst, b, h) do { _Pragma("unroll") for (int m = 0; m < 4; ++m) _Pragma("unroll") for (int k = 0; k < 2; ++k) dst[m][k] = *(const PG8_LAS bf16x8*)(lds + PG8_SA(b, h) + aoff + m * 2048 + k * 1024); } while (0)
; #define PG8_MMA(ai, bj, At, Bt) do { __builtin_amdgcn_s_setprio(1); _Pragma("unroll") for (int m = 0; m < 4; ++m) _Pragma("unroll") for (int n = 0; n < 2; ++n) _Pragma("unroll") for (int k = 0; k < 2; ++k) \
;         acc[ai][bj][m][n] = __builtin_amdgcn_mfma_f32_16x16x32_bf16(Bt[n][k], At[m][k], acc[ai][bj][m][n], 0, 0, 0); __builtin_amdgcn_s_setprio(0); } while (0)
; #define PG8_WAIT_V(n) asm volatile("s_waitcnt vmcnt(" #n ")" ::: "memory")
; #define PG8_WAIT_L(n) asm volatile("s_waitcnt lgkmcnt(" #n ")" ::: "memory")
; #define PG8_BAR __builtin_amdgcn_s_barrier()
; #define PG8_SCHED __builtin_amdgcn_sched_barrier(0)
; template <class Epi, class Sched, bool ALIGN_EPI = false, bool SP2 = false>
; __device__ __forceinline__ void gemm_phase(PG8_LAS unsigned char* lds, const Gemm g, const Sched& S, const Epi& E) {
;     ...
;             PG8_LDA(At, 1, 1); PG8_STAGE(PG8_SB(1, 0), b3, voffB); PG8_STAGE(PG8_SB(1, 1), b3 + hstepB, voffB); PG8_STAGE(PG8_SA(1, 0), a3, voffA);
;             PG8_WAIT_V(8); PG8_WAIT_L(0); PG8_BAR; PG8_MMA(1, 0, At, B0); PG8_MMA(1, 1, At, B1); PG8_BAR; PG8_SCHED;
;     ...
; #pragma unroll
;         for (int a = 0; a < 2; ++a)
; #pragma unroll
;             for (int b = 0; b < 2; ++b)
; #pragma unroll
;                 for (int m = 0; m < 4; ++m)
; #pragma unroll
;                     for (int n = 0; n < 2; ++n) acc[a][b][m][n] = (f32x4){0.f, 0.f, 0.f, 0.f};
	s_add_i32 s38, s64, s47
	s_mov_b32 m0, s38
	ds_read_b128 v[122:125], v23 offset:49152
	ds_read_b128 v[130:133], v23 offset:50176
	ds_read_b128 v[198:201], v23 offset:51200
	ds_read_b128 v[202:205], v23 offset:52224
	ds_read_b128 v[206:209], v23 offset:53248
	ds_read_b128 v[210:213], v23 offset:54272
	ds_read_b128 v[214:217], v23 offset:55296
	ds_read_b128 v[218:221], v23 offset:56320
	global_load_lds_dwordx4 v4, s[98:99]
	s_add_i32 m0, s38, 0x2000
	s_add_u32 s36, s36, 0x40080
	s_addc_u32 s37, s37, 0
	s_add_i32 s38, s65, s47
	global_load_lds_dwordx4 v8, s[98:99]
	s_mov_b32 m0, s38
	s_nop 0
	global_load_lds_dwordx4 v4, s[36:37]
	s_add_i32 m0, s38, 0x2000
	s_nop 0
	global_load_lds_dwordx4 v8, s[36:37]
	s_mov_b32 m0, s54
	s_nop 0
	global_load_lds_dwordx4 v2, s[100:101]
	s_mov_b32 m0, s55
	s_nop 0
	global_load_lds_dwordx4 v6, s[100:101]
	s_waitcnt vmcnt(8)
	s_waitcnt lgkmcnt(0)
	s_barrier
	s_waitcnt lgkmcnt(0)
	v_mfma_f32_16x16x32_bf16 v[134:137], v[78:81], v[122:125], v[150:153]
	v_mfma_f32_16x16x32_bf16 v[150:153], v[90:93], v[130:133], v[134:137]
	v_mfma_f32_16x16x32_bf16 v[134:137], v[94:97], v[122:125], v[146:149]
	v_mfma_f32_16x16x32_bf16 v[146:149], v[118:121], v[130:133], v[134:137]
	v_mfma_f32_16x16x32_bf16 v[134:137], v[78:81], v[198:201], v[142:145]
	v_mfma_f32_16x16x32_bf16 v[142:145], v[90:93], v[202:205], v[134:137]
	v_mfma_f32_16x16x32_bf16 v[134:137], v[94:97], v[198:201], v[138:141]
	v_mfma_f32_16x16x32_bf16 v[126:129], v[78:81], v[206:209], v[126:129]
	v_mfma_f32_16x16x32_bf16 v[98:101], v[94:97], v[206:209], v[98:101]
	v_mfma_f32_16x16x32_bf16 v[46:49], v[78:81], v[214:217], v[46:49]
	v_mfma_f32_16x16x32_bf16 v[42:45], v[94:97], v[214:217], v[42:45]
	v_mfma_f32_16x16x32_bf16 v[138:141], v[118:121], v[202:205], v[134:137]
	v_mfma_f32_16x16x32_bf16 v[126:129], v[90:93], v[210:213], v[126:129]
	v_mfma_f32_16x16x32_bf16 v[98:101], v[118:121], v[210:213], v[98:101]
	v_mfma_f32_16x16x32_bf16 v[46:49], v[90:93], v[218:221], v[46:49]
	v_mfma_f32_16x16x32_bf16 v[42:45], v[118:121], v[218:221], v[42:45]
	v_mfma_f32_16x16x32_bf16 v[50:53], v[154:157], v[122:125], v[50:53]
	v_mfma_f32_16x16x32_bf16 v[134:137], v[158:161], v[130:133], v[50:53]
	v_mfma_f32_16x16x32_bf16 v[50:53], v[178:181], v[122:125], v[54:57]
	v_mfma_f32_16x16x32_bf16 v[130:133], v[194:197], v[130:133], v[50:53]
	v_mfma_f32_16x16x32_bf16 v[50:53], v[154:157], v[198:201], v[70:73]
	v_mfma_f32_16x16x32_bf16 v[122:125], v[158:161], v[202:205], v[50:53]
	v_mfma_f32_16x16x32_bf16 v[50:53], v[178:181], v[198:201], v[74:77]
	v_mfma_f32_16x16x32_bf16 v[38:41], v[154:157], v[206:209], v[38:41]
	v_mfma_f32_16x16x32_bf16 v[34:37], v[178:181], v[206:209], v[34:37]
	v_mfma_f32_16x16x32_bf16 v[28:31], v[154:157], v[214:217], v[30:33]
	v_mfma_f32_16x16x32_bf16 v[24:27], v[178:181], v[214:217], v[24:27]
	v_mfma_f32_16x16x32_bf16 v[118:121], v[194:197], v[202:205], v[50:53]
	v_mfma_f32_16x16x32_bf16 v[38:41], v[158:161], v[210:213], v[38:41]
	v_mfma_f32_16x16x32_bf16 v[34:37], v[194:197], v[210:213], v[34:37]
	v_mfma_f32_16x16x32_bf16 v[30:33], v[158:161], v[218:221], v[28:31]
	v_mfma_f32_16x16x32_bf16 v[26:29], v[194:197], v[218:221], v[24:27]
	s_barrier
	s_add_i32 s63, s63, 2
	s_add_u32 s34, s34, 0x100
	s_addc_u32 s35, s35, 0
	s_cmp_gt_u32 s63, 13
	s_cbranch_scc0 .LBB0_1269
	s_add_u32 s34, s59, 0xffffff00
	s_addc_u32 s35, s60, -1
	s_andn2_b64 vcc, exec, s[4:5]
	s_cbranch_vccnz .LBB0_1260
	v_mov_b32_e32 v26, 0
	s_mov_b32 s14, s24
	s_mov_b32 s12, s26
	s_mov_b64 s[20:21], s[30:31]
	s_mov_b32 s53, s58
	v_mov_b32_e32 v27, v26
	v_mov_b32_e32 v28, v26
	v_mov_b32_e32 v29, v26
	v_mov_b32_e32 v30, v26
	v_mov_b32_e32 v31, v26
	v_mov_b32_e32 v32, v26
	v_mov_b32_e32 v33, v26
	v_mov_b32_e32 v34, v26
	v_mov_b32_e32 v35, v26
	v_mov_b32_e32 v36, v26
	v_mov_b32_e32 v37, v26
	v_mov_b32_e32 v38, v26
	v_mov_b32_e32 v39, v26
	v_mov_b32_e32 v40, v26
	v_mov_b32_e32 v41, v26
	v_mov_b32_e32 v118, v26
	v_mov_b32_e32 v119, v26
	v_mov_b32_e32 v120, v26
	v_mov_b32_e32 v121, v26
	v_mov_b32_e32 v122, v26
	v_mov_b32_e32 v123, v26
	v_mov_b32_e32 v124, v26
	v_mov_b32_e32 v125, v26
	v_mov_b32_e32 v130, v26
	v_mov_b32_e32 v131, v26
	v_mov_b32_e32 v132, v26
	v_mov_b32_e32 v133, v26
	v_mov_b32_e32 v134, v26
	v_mov_b32_e32 v135, v26
	v_mov_b32_e32 v136, v26
	v_mov_b32_e32 v137, v26
	v_mov_b32_e32 v42, v26
	v_mov_b32_e32 v43, v26
	v_mov_b32_e32 v44, v26
	v_mov_b32_e32 v45, v26
	v_mov_b32_e32 v46, v26
	v_mov_b32_e32 v47, v26
	v_mov_b32_e32 v48, v26
	v_mov_b32_e32 v49, v26
	v_mov_b32_e32 v98, v26
	v_mov_b32_e32 v99, v26
	v_mov_b32_e32 v100, v26
	v_mov_b32_e32 v101, v26
	v_mov_b32_e32 v126, v26
	v_mov_b32_e32 v127, v26
	v_mov_b32_e32 v128, v26
	v_mov_b32_e32 v129, v26
	v_mov_b32_e32 v138, v26
	v_mov_b32_e32 v139, v26
	v_mov_b32_e32 v140, v26
	v_mov_b32_e32 v141, v26
	v_mov_b32_e32 v142, v26
	v_mov_b32_e32 v143, v26
	v_mov_b32_e32 v144, v26
	v_mov_b32_e32 v145, v26
	v_mov_b32_e32 v146, v26
	v_mov_b32_e32 v147, v26
	v_mov_b32_e32 v148, v26
	v_mov_b32_e32 v149, v26
	v_mov_b32_e32 v150, v26
	v_mov_b32_e32 v151, v26
	v_mov_b32_e32 v152, v26
	v_mov_b32_e32 v153, v26
	v_mov_b32_e32 v102, v26
	v_mov_b32_e32 v103, v26
	v_mov_b32_e32 v104, v26
	v_mov_b32_e32 v105, v26
	v_mov_b32_e32 v106, v26
	v_mov_b32_e32 v107, v26
	v_mov_b32_e32 v108, v26
	v_mov_b32_e32 v109, v26
	v_mov_b32_e32 v110, v26
	v_mov_b32_e32 v111, v26
	v_mov_b32_e32 v112, v26
	v_mov_b32_e32 v113, v26
	v_mov_b32_e32 v114, v26
	v_mov_b32_e32 v115, v26
	v_mov_b32_e32 v116, v26
	v_mov_b32_e32 v117, v26
	v_mov_b32_e32 v58, v26
	v_mov_b32_e32 v59, v26
	v_mov_b32_e32 v60, v26
	v_mov_b32_e32 v61, v26
	v_mov_b32_e32 v66, v26
	v_mov_b32_e32 v67, v26
	v_mov_b32_e32 v68, v26
	v_mov_b32_e32 v69, v26
	v_mov_b32_e32 v82, v26
	v_mov_b32_e32 v83, v26
	v_mov_b32_e32 v84, v26
	v_mov_b32_e32 v85, v26
	v_mov_b32_e32 v86, v26
	v_mov_b32_e32 v87, v26
	v_mov_b32_e32 v88, v26
	v_mov_b32_e32 v89, v26
	v_mov_b32_e32 v182, v26
	v_mov_b32_e32 v183, v26
	v_mov_b32_e32 v184, v26
	v_mov_b32_e32 v185, v26
	v_mov_b32_e32 v186, v26
	v_mov_b32_e32 v187, v26
	v_mov_b32_e32 v188, v26
	v_mov_b32_e32 v189, v26
	v_mov_b32_e32 v190, v26
	v_mov_b32_e32 v191, v26
	v_mov_b32_e32 v192, v26
	v_mov_b32_e32 v193, v26
	v_mov_b32_e32 v174, v26
	v_mov_b32_e32 v175, v26
	v_mov_b32_e32 v176, v26
	v_mov_b32_e32 v177, v26
	v_mov_b32_e32 v162, v26
	v_mov_b32_e32 v163, v26
	v_mov_b32_e32 v164, v26
	v_mov_b32_e32 v165, v26
	v_mov_b32_e32 v166, v26
	v_mov_b32_e32 v167, v26
	v_mov_b32_e32 v168, v26
	v_mov_b32_e32 v169, v26
	v_mov_b32_e32 v170, v26
	v_mov_b32_e32 v171, v26
	v_mov_b32_e32 v172, v26
	v_mov_b32_e32 v173, v26
	v_mov_b32_e32 v62, v26
	v_mov_b32_e32 v63, v26
	v_mov_b32_e32 v64, v26
	v_mov_b32_e32 v65, v26
	s_andn2_b64 vcc, exec, s[2:3]
	s_cbranch_vccnz .LBB0_1261

; #define PG8_STAGE(bufoff, gbase, voff) do { _Pragma("unroll") for (int _i = 0; _i < 2; ++_i) \
;         __builtin_amdgcn_global_load_lds((const unsigned*)((const char*)(gbase) + (voff)[_i]), (PG8_LAS unsigned*)(lds + (bufoff) + ldsw + _i * 8192), 16, 0, 0); } while (0)
; #define PG8_LDA(dst, b, h) do { _Pragma("unroll") for (int m = 0; m < 4; ++m) _Pragma("unroll") for (int k = 0; k < 2; ++k) dst[m][k] = *(const PG8_LAS bf16x8*)(lds + PG8_SA(b, h) + aoff + m * 2048 + k * 1024); } while (0)
; #define PG8_LDB(dst, b, h) do { _Pragma("unroll") for (int n = 0; n < 2; ++n) _Pragma("unroll") for (int k = 0; k < 2; ++k) dst[n][k] = *(const PG8_LAS bf16x8*)(lds + PG8_SB(b, h) + boff + n * 2048 + k * 1024); } while (0)
; #define PG8_MMA(ai, bj, At, Bt) do { __builtin_amdgcn_s_setprio(1); _Pragma("unroll") for (int m = 0; m < 4; ++m) _Pragma("unroll") for (int n = 0; n < 2; ++n) _Pragma("unroll") for (int k = 0; k < 2; ++k) \
;         acc[ai][bj][m][n] = __builtin_amdgcn_mfma_f32_16x16x32_bf16(Bt[n][k], At[m][k], acc[ai][bj][m][n], 0, 0, 0); __builtin_amdgcn_s_setprio(0); } while (0)
; #define PG8_WAIT_V(n) asm volatile("s_waitcnt vmcnt(" #n ")" ::: "memory")
; #define PG8_WAIT_L(n) asm volatile("s_waitcnt lgkmcnt(" #n ")" ::: "memory")
; #define PG8_BAR __builtin_amdgcn_s_barrier()
; #define PG8_SCHED __builtin_amdgcn_sched_barrier(0)
; template <class Epi, class Sched, bool ALIGN_EPI = false, bool SP2 = false>
; __device__ __forceinline__ void gemm_phase(PG8_LAS unsigned char* lds, const Gemm g, const Sched& S, const Epi& E) {
;     ...
;             PG8_LDB(B0, 0, 0); PG8_LDB(B1, 0, 1); PG8_SCHED; PG8_LDA(At, 0, 0); PG8_STAGE(PG8_SA(1, 1), a1 + hstepA, voffA);
;             PG8_WAIT_V(8); PG8_WAIT_L(0); PG8_BAR; PG8_MMA(0, 0, At, B0); PG8_MMA(0, 1, At, B1); PG8_BAR; PG8_SCHED;
;             PG8_LDA(At, 0, 1); PG8_STAGE(PG8_SB(0, 0), b2, voffB); PG8_STAGE(PG8_SB(0, 1), b2 + hstepB, voffB); PG8_STAGE(PG8_SA(0, 0), a2, voffA);
;             PG8_WAIT_V(8); PG8_WAIT_L(0); PG8_BAR; PG8_MMA(1, 0, At, B0); PG8_MMA(1, 1, At, B1); PG8_BAR; PG8_SCHED;
.LBB0_1528:
	ds_read_b128 v[130:133], v182
	ds_read_b128 v[134:137], v182 offset:1024
	ds_read_b128 v[154:157], v182 offset:2048
	ds_read_b128 v[158:161], v182 offset:3072
	ds_read_b128 v[162:165], v183
	ds_read_b128 v[166:169], v183 offset:1024
	ds_read_b128 v[170:173], v183 offset:2048
	ds_read_b128 v[186:189], v183 offset:3072
	s_add_u32 s44, s42, 0xfffc0080
	s_addc_u32 s45, s43, -1
	s_cmp_eq_u32 s69, 12
	s_cselect_b32 s47, s31, s45
	s_cselect_b32 s46, s39, s44
	s_cselect_b32 s45, s29, s68
	s_cselect_b32 s44, s66, s67
	s_add_i32 m0, s41, 0xc000
	ds_read_b128 v[190:193], v184
	ds_read_b128 v[194:197], v184 offset:1024
	ds_read_b128 v[198:201], v184 offset:2048
	ds_read_b128 v[202:205], v184 offset:3072
	ds_read_b128 v[206:209], v184 offset:4096
	ds_read_b128 v[210:213], v184 offset:5120
	ds_read_b128 v[214:217], v184 offset:6144
	ds_read_b128 v[218:221], v184 offset:7168
	global_load_lds_dwordx4 v146, s[42:43]
	s_add_i32 m0, s41, 0xe000
	s_nop 0
	global_load_lds_dwordx4 v148, s[42:43]
	s_waitcnt vmcnt(8)
	s_waitcnt lgkmcnt(0)
	s_barrier
	s_waitcnt lgkmcnt(0)
	v_mfma_f32_16x16x32_bf16 v[126:129], v[130:133], v[190:193], v[126:129]
	v_mfma_f32_16x16x32_bf16 v[94:97], v[154:157], v[190:193], v[94:97]
	v_mfma_f32_16x16x32_bf16 v[118:121], v[130:133], v[198:201], v[118:121]
	v_mfma_f32_16x16x32_bf16 v[86:89], v[154:157], v[198:201], v[86:89]
	v_mfma_f32_16x16x32_bf16 v[114:117], v[130:133], v[206:209], v[114:117]
	v_mfma_f32_16x16x32_bf16 v[82:85], v[154:157], v[206:209], v[82:85]
	v_mfma_f32_16x16x32_bf16 v[102:105], v[130:133], v[214:217], v[102:105]
	v_mfma_f32_16x16x32_bf16 v[70:73], v[154:157], v[214:217], v[70:73]
	v_mfma_f32_16x16x32_bf16 v[126:129], v[134:137], v[194:197], v[126:129]
	v_mfma_f32_16x16x32_bf16 v[94:97], v[158:161], v[194:197], v[94:97]
	v_mfma_f32_16x16x32_bf16 v[118:121], v[134:137], v[202:205], v[118:121]
	v_mfma_f32_16x16x32_bf16 v[86:89], v[158:161], v[202:205], v[86:89]
	v_mfma_f32_16x16x32_bf16 v[114:117], v[134:137], v[210:213], v[114:117]
	v_mfma_f32_16x16x32_bf16 v[82:85], v[158:161], v[210:213], v[82:85]
	v_mfma_f32_16x16x32_bf16 v[102:105], v[134:137], v[218:221], v[102:105]
	v_mfma_f32_16x16x32_bf16 v[70:73], v[158:161], v[218:221], v[70:73]
	v_mfma_f32_16x16x32_bf16 v[122:125], v[162:165], v[190:193], v[122:125]
	v_mfma_f32_16x16x32_bf16 v[90:93], v[170:173], v[190:193], v[90:93]
	v_mfma_f32_16x16x32_bf16 v[110:113], v[162:165], v[198:201], v[110:113]
	v_mfma_f32_16x16x32_bf16 v[78:81], v[170:173], v[198:201], v[78:81]
	v_mfma_f32_16x16x32_bf16 v[106:109], v[162:165], v[206:209], v[106:109]
	v_mfma_f32_16x16x32_bf16 v[74:77], v[170:173], v[206:209], v[74:77]
	v_mfma_f32_16x16x32_bf16 v[98:101], v[162:165], v[214:217], v[98:101]
	v_mfma_f32_16x16x32_bf16 v[66:69], v[170:173], v[214:217], v[66:69]
	v_mfma_f32_16x16x32_bf16 v[122:125], v[166:169], v[194:197], v[122:125]
	v_mfma_f32_16x16x32_bf16 v[90:93], v[186:189], v[194:197], v[90:93]
	v_mfma_f32_16x16x32_bf16 v[110:113], v[166:169], v[202:205], v[110:113]
	v_mfma_f32_16x16x32_bf16 v[78:81], v[186:189], v[202:205], v[78:81]
	v_mfma_f32_16x16x32_bf16 v[106:109], v[166:169], v[210:213], v[106:109]
	v_mfma_f32_16x16x32_bf16 v[74:77], v[186:189], v[210:213], v[74:77]
	v_mfma_f32_16x16x32_bf16 v[98:101], v[166:169], v[218:221], v[98:101]
	v_mfma_f32_16x16x32_bf16 v[66:69], v[186:189], v[218:221], v[66:69]
	s_barrier
	s_add_i32 s70, s63, s51
	s_add_u32 s98, s44, 0x80
	s_addc_u32 s99, s45, 0
	s_mov_b32 m0, s70
	ds_read_b128 v[190:193], v184 offset:16384
	ds_read_b128 v[194:197], v184 offset:17408
	ds_read_b128 v[198:201], v184 offset:18432
	ds_read_b128 v[202:205], v184 offset:19456
	ds_read_b128 v[206:209], v184 offset:20480
	ds_read_b128 v[210:213], v184 offset:21504
	ds_read_b128 v[214:217], v184 offset:22528
	ds_read_b128 v[218:221], v184 offset:23552
	global_load_lds_dwordx4 v140, s[44:45]
	s_add_i32 m0, s70, 0x2000
	s_add_u32 s70, s44, 0x40000
	s_addc_u32 s71, s45, 0
	s_add_i32 s72, s64, s51
	global_load_lds_dwordx4 v144, s[44:45]
	s_mov_b32 m0, s72
	v_lshl_add_u64 v[226:227], s[46:47], 0, v[142:143]
	global_load_lds_dwordx4 v140, s[70:71]
	s_add_i32 m0, s72, 0x2000
	s_nop 0
	global_load_lds_dwordx4 v144, s[70:71]
	s_add_u32 s100, s46, 0x80
	s_addc_u32 s101, s47, 0
	s_mov_b32 m0, s41
	s_nop 0
	global_load_lds_dwordx4 v138, s[46:47]
	s_mov_b32 m0, s52
	s_nop 0
	global_load_lds_dwordx4 v142, s[46:47]
	s_waitcnt vmcnt(8)
	s_waitcnt lgkmcnt(0)
	s_barrier
	s_waitcnt lgkmcnt(0)
	v_mfma_f32_16x16x32_bf16 v[62:65], v[130:133], v[190:193], v[62:65]
	v_mfma_f32_16x16x32_bf16 v[30:33], v[154:157], v[190:193], v[30:33]
	v_mfma_f32_16x16x32_bf16 v[54:57], v[130:133], v[198:201], v[54:57]
	v_mfma_f32_16x16x32_bf16 v[22:25], v[154:157], v[198:201], v[22:25]
	v_mfma_f32_16x16x32_bf16 v[50:53], v[130:133], v[206:209], v[50:53]
	v_mfma_f32_16x16x32_bf16 v[18:21], v[154:157], v[206:209], v[18:21]
	v_mfma_f32_16x16x32_bf16 v[38:41], v[130:133], v[214:217], v[38:41]
	v_mfma_f32_16x16x32_bf16 v[6:9], v[154:157], v[214:217], v[6:9]
	v_mfma_f32_16x16x32_bf16 v[62:65], v[134:137], v[194:197], v[62:65]
	v_mfma_f32_16x16x32_bf16 v[30:33], v[158:161], v[194:197], v[30:33]
	v_mfma_f32_16x16x32_bf16 v[54:57], v[134:137], v[202:205], v[54:57]
	v_mfma_f32_16x16x32_bf16 v[22:25], v[158:161], v[202:205], v[22:25]
	v_mfma_f32_16x16x32_bf16 v[50:53], v[134:137], v[210:213], v[50:53]
	v_mfma_f32_16x16x32_bf16 v[18:21], v[158:161], v[210:213], v[18:21]
	v_mfma_f32_16x16x32_bf16 v[38:41], v[134:137], v[218:221], v[38:41]
	v_mfma_f32_16x16x32_bf16 v[6:9], v[158:161], v[218:221], v[6:9]
	v_mfma_f32_16x16x32_bf16 v[58:61], v[162:165], v[190:193], v[58:61]
	v_mfma_f32_16x16x32_bf16 v[26:29], v[170:173], v[190:193], v[26:29]
	v_mfma_f32_16x16x32_bf16 v[46:49], v[162:165], v[198:201], v[46:49]
	v_mfma_f32_16x16x32_bf16 v[14:17], v[170:173], v[198:201], v[14:17]
	v_mfma_f32_16x16x32_bf16 v[42:45], v[162:165], v[206:209], v[42:45]
	v_mfma_f32_16x16x32_bf16 v[10:13], v[170:173], v[206:209], v[10:13]
	v_mfma_f32_16x16x32_bf16 v[34:37], v[162:165], v[214:217], v[34:37]
	v_mfma_f32_16x16x32_bf16 v[2:5], v[170:173], v[214:217], v[2:5]
	v_mfma_f32_16x16x32_bf16 v[58:61], v[166:169], v[194:197], v[58:61]
	v_mfma_f32_16x16x32_bf16 v[26:29], v[186:189], v[194:197], v[26:29]
	v_mfma_f32_16x16x32_bf16 v[46:49], v[166:169], v[202:205], v[46:49]
	v_mfma_f32_16x16x32_bf16 v[14:17], v[186:189], v[202:205], v[14:17]
	v_mfma_f32_16x16x32_bf16 v[42:45], v[166:169], v[210:213], v[42:45]
	v_mfma_f32_16x16x32_bf16 v[10:13], v[186:189], v[210:213], v[10:13]
	v_mfma_f32_16x16x32_bf16 v[34:37], v[166:169], v[218:221], v[34:37]
	v_mfma_f32_16x16x32_bf16 v[2:5], v[186:189], v[218:221], v[2:5]
	s_barrier
; #define PG8_STAGE(bufoff, gbase, voff) do { _Pragma("unroll") for (int _i = 0; _i < 2; ++_i) \
;         __builtin_amdgcn_global_load_lds((const unsigned*)((const char*)(gbase) + (voff)[_i]), (PG8_LAS unsigned*)(lds + (bufoff) + ldsw + _i * 8192), 16, 0, 0); } while (0)
; #define PG8_LDA(dst, b, h) do { _Pragma("unroll") for (int m = 0; m < 4; ++m) _Pragma("unroll") for (int k = 0; k < 2; ++k) dst[m][k] = *(const PG8_LAS bf16x8*)(lds + PG8_SA(b, h) + aoff + m * 2048 + k * 1024); } while (0)
; #define PG8_LDB(dst, b, h) do { _Pragma("unroll") for (int n = 0; n < 2; ++n) _Pragma("unroll") for (int k = 0; k < 2; ++k) dst[n][k] = *(const PG8_LAS bf16x8*)(lds + PG8_SB(b, h) + boff + n * 2048 + k * 1024); } while (0)
; #define PG8_MMA(ai, bj, At, Bt) do { __builtin_amdgcn_s_setprio(1); _Pragma("unroll") for (int m = 0; m < 4; ++m) _Pragma("unroll") for (int n = 0; n < 2; ++n) _Pragma("unroll") for (int k = 0; k < 2; ++k) \
;         acc[ai][bj][m][n] = __builtin_amdgcn_mfma_f32_16x16x32_bf16(Bt[n][k], At[m][k], acc[ai][bj][m][n], 0, 0, 0); __builtin_amdgcn_s_setprio(0); } while (0)
; #define PG8_WAIT_V(n) asm volatile("s_waitcnt vmcnt(" #n ")" ::: "memory")
; #define PG8_WAIT_L(n) asm volatile("s_waitcnt lgkmcnt(" #n ")" ::: "memory")
; #define PG8_BAR __builtin_amdgcn_s_barrier()
; #define PG8_SCHED __builtin_amdgcn_sched_barrier(0)
; template <class Epi, class Sched, bool ALIGN_EPI = false, bool SP2 = false>
; __device__ __forceinline__ void gemm_phase(PG8_LAS unsigned char* lds, const Gemm g, const Sched& S, const Epi& E) {
;     ...
;             PG8_LDB(B0, 1, 0); PG8_LDB(B1, 1, 1); PG8_SCHED; PG8_LDA(At, 1, 0); PG8_STAGE(PG8_SA(0, 1), a2 + hstepA, voffA);
;             PG8_WAIT_V(8); PG8_WAIT_L(0); PG8_BAR; PG8_MMA(0, 0, At, B0); PG8_MMA(0, 1, At, B1); PG8_BAR; PG8_SCHED;
;             PG8_LDA(At, 1, 1); PG8_STAGE(PG8_SB(1, 0), b3, voffB); PG8_STAGE(PG8_SB(1, 1), b3 + hstepB, voffB); PG8_STAGE(PG8_SA(1, 0), a3, voffA);
;             PG8_WAIT_V(8); PG8_WAIT_L(0); PG8_BAR; PG8_MMA(1, 0, At, B0); PG8_MMA(1, 1, At, B1); PG8_BAR; PG8_SCHED;
	s_add_i32 s70, 0, 0x18000
	s_add_i32 s71, 0, 0x1c000
	v_add_u32_e32 v158, s70, v176
	v_add_u32_e32 v185, s71, v176
	ds_read_b128 v[130:133], v158
	ds_read_b128 v[134:137], v158 offset:1024
	ds_read_b128 v[154:157], v158 offset:2048
	ds_read_b128 v[158:161], v158 offset:3072
	ds_read_b128 v[162:165], v185
	ds_read_b128 v[166:169], v185 offset:1024
	ds_read_b128 v[170:173], v185 offset:2048
	ds_read_b128 v[186:189], v185 offset:3072
	s_add_u32 s46, s46, 0x40000
	s_addc_u32 s47, s47, 0
	s_mov_b32 m0, s53
	ds_read_b128 v[190:193], v184 offset:32768
	ds_read_b128 v[194:197], v184 offset:33792
	ds_read_b128 v[198:201], v184 offset:34816
	ds_read_b128 v[202:205], v184 offset:35840
	ds_read_b128 v[206:209], v184 offset:36864
	ds_read_b128 v[210:213], v184 offset:37888
	ds_read_b128 v[214:217], v184 offset:38912
	ds_read_b128 v[218:221], v184 offset:39936
	global_load_lds_dwordx4 v138, s[46:47]
	s_mov_b32 m0, s54
	s_nop 0
	global_load_lds_dwordx4 v142, s[46:47]
	s_waitcnt vmcnt(8)
	s_waitcnt lgkmcnt(0)
	s_barrier
	s_waitcnt lgkmcnt(0)
	v_mfma_f32_16x16x32_bf16 v[126:129], v[130:133], v[190:193], v[126:129]
	v_mfma_f32_16x16x32_bf16 v[94:97], v[154:157], v[190:193], v[94:97]
	v_mfma_f32_16x16x32_bf16 v[118:121], v[130:133], v[198:201], v[118:121]
	v_mfma_f32_16x16x32_bf16 v[86:89], v[154:157], v[198:201], v[86:89]
	v_mfma_f32_16x16x32_bf16 v[114:117], v[130:133], v[206:209], v[114:117]
	v_mfma_f32_16x16x32_bf16 v[82:85], v[154:157], v[206:209], v[82:85]
	v_mfma_f32_16x16x32_bf16 v[102:105], v[130:133], v[214:217], v[102:105]
	v_mfma_f32_16x16x32_bf16 v[70:73], v[154:157], v[214:217], v[70:73]
	v_mfma_f32_16x16x32_bf16 v[126:129], v[134:137], v[194:197], v[126:129]
	v_mfma_f32_16x16x32_bf16 v[94:97], v[158:161], v[194:197], v[94:97]
	v_mfma_f32_16x16x32_bf16 v[118:121], v[134:137], v[202:205], v[118:121]
	v_mfma_f32_16x16x32_bf16 v[86:89], v[158:161], v[202:205], v[86:89]
	v_mfma_f32_16x16x32_bf16 v[114:117], v[134:137], v[210:213], v[114:117]
	v_mfma_f32_16x16x32_bf16 v[82:85], v[158:161], v[210:213], v[82:85]
	v_mfma_f32_16x16x32_bf16 v[102:105], v[134:137], v[218:221], v[102:105]
	v_mfma_f32_16x16x32_bf16 v[70:73], v[158:161], v[218:221], v[70:73]
	v_mfma_f32_16x16x32_bf16 v[122:125], v[162:165], v[190:193], v[122:125]
	v_mfma_f32_16x16x32_bf16 v[90:93], v[170:173], v[190:193], v[90:93]
	v_mfma_f32_16x16x32_bf16 v[110:113], v[162:165], v[198:201], v[110:113]
	v_mfma_f32_16x16x32_bf16 v[78:81], v[170:173], v[198:201], v[78:81]
	v_mfma_f32_16x16x32_bf16 v[106:109], v[162:165], v[206:209], v[106:109]
	v_mfma_f32_16x16x32_bf16 v[74:77], v[170:173], v[206:209], v[74:77]
	v_mfma_f32_16x16x32_bf16 v[98:101], v[162:165], v[214:217], v[98:101]
	v_mfma_f32_16x16x32_bf16 v[66:69], v[170:173], v[214:217], v[66:69]
	v_mfma_f32_16x16x32_bf16 v[122:125], v[166:169], v[194:197], v[122:125]
	v_mfma_f32_16x16x32_bf16 v[90:93], v[186:189], v[194:197], v[90:93]
	v_mfma_f32_16x16x32_bf16 v[110:113], v[166:169], v[202:205], v[110:113]
	v_mfma_f32_16x16x32_bf16 v[78:81], v[186:189], v[202:205], v[78:81]
	v_mfma_f32_16x16x32_bf16 v[106:109], v[166:169], v[210:213], v[106:109]
	v_mfma_f32_16x16x32_bf16 v[74:77], v[186:189], v[210:213], v[74:77]
	v_mfma_f32_16x16x32_bf16 v[98:101], v[166:169], v[218:221], v[98:101]
	v_mfma_f32_16x16x32_bf16 v[66:69], v[186:189], v[218:221], v[66:69]
	s_barrier
	s_add_i32 s46, s70, s51
	s_mov_b32 m0, s46
	ds_read_b128 v[190:193], v184 offset:49152
	ds_read_b128 v[194:197], v184 offset:50176
	ds_read_b128 v[198:201], v184 offset:51200
	ds_read_b128 v[202:205], v184 offset:52224
	ds_read_b128 v[206:209], v184 offset:53248
	ds_read_b128 v[210:213], v184 offset:54272
	ds_read_b128 v[214:217], v184 offset:55296
	ds_read_b128 v[218:221], v184 offset:56320
	global_load_lds_dwordx4 v140, s[98:99]
	s_add_i32 m0, s46, 0x2000
	s_add_u32 s44, s44, 0x40080
	s_addc_u32 s45, s45, 0
	s_add_i32 s46, s71, s51
	global_load_lds_dwordx4 v144, s[98:99]
	s_mov_b32 m0, s46
	s_nop 0
	global_load_lds_dwordx4 v140, s[44:45]
	s_add_i32 m0, s46, 0x2000
	s_nop 0
	global_load_lds_dwordx4 v144, s[44:45]
	s_mov_b32 m0, s59
	s_nop 0
	global_load_lds_dwordx4 v138, s[100:101]
	v_lshl_add_u64 v[174:175], v[226:227], 0, s[24:25]
	s_mov_b32 m0, s60
	s_nop 0
	global_load_lds_dwordx4 v142, s[100:101]
	s_waitcnt vmcnt(8)
	s_waitcnt lgkmcnt(0)
	s_barrier
	s_waitcnt lgkmcnt(0)
	v_mfma_f32_16x16x32_bf16 v[62:65], v[130:133], v[190:193], v[62:65]
	v_mfma_f32_16x16x32_bf16 v[30:33], v[154:157], v[190:193], v[30:33]
	v_mfma_f32_16x16x32_bf16 v[54:57], v[130:133], v[198:201], v[54:57]
	v_mfma_f32_16x16x32_bf16 v[22:25], v[154:157], v[198:201], v[22:25]
	v_mfma_f32_16x16x32_bf16 v[50:53], v[130:133], v[206:209], v[50:53]
	v_mfma_f32_16x16x32_bf16 v[18:21], v[154:157], v[206:209], v[18:21]
	v_mfma_f32_16x16x32_bf16 v[38:41], v[130:133], v[214:217], v[38:41]
	v_mfma_f32_16x16x32_bf16 v[6:9], v[154:157], v[214:217], v[6:9]
	v_mfma_f32_16x16x32_bf16 v[62:65], v[134:137], v[194:197], v[62:65]
	v_mfma_f32_16x16x32_bf16 v[30:33], v[158:161], v[194:197], v[30:33]
	v_mfma_f32_16x16x32_bf16 v[54:57], v[134:137], v[202:205], v[54:57]
	v_mfma_f32_16x16x32_bf16 v[22:25], v[158:161], v[202:205], v[22:25]
	v_mfma_f32_16x16x32_bf16 v[50:53], v[134:137], v[210:213], v[50:53]
	v_mfma_f32_16x16x32_bf16 v[18:21], v[158:161], v[210:213], v[18:21]
	v_mfma_f32_16x16x32_bf16 v[38:41], v[134:137], v[218:221], v[38:41]
	v_mfma_f32_16x16x32_bf16 v[6:9], v[158:161], v[218:221], v[6:9]
	v_mfma_f32_16x16x32_bf16 v[58:61], v[162:165], v[190:193], v[58:61]
	v_mfma_f32_16x16x32_bf16 v[26:29], v[170:173], v[190:193], v[26:29]
	v_mfma_f32_16x16x32_bf16 v[46:49], v[162:165], v[198:201], v[46:49]
	v_mfma_f32_16x16x32_bf16 v[14:17], v[170:173], v[198:201], v[14:17]
	v_mfma_f32_16x16x32_bf16 v[42:45], v[162:165], v[206:209], v[42:45]
	v_mfma_f32_16x16x32_bf16 v[10:13], v[170:173], v[206:209], v[10:13]
	v_mfma_f32_16x16x32_bf16 v[34:37], v[162:165], v[214:217], v[34:37]
	v_mfma_f32_16x16x32_bf16 v[2:5], v[170:173], v[214:217], v[2:5]
	v_mfma_f32_16x16x32_bf16 v[58:61], v[166:169], v[194:197], v[58:61]
	v_mfma_f32_16x16x32_bf16 v[26:29], v[186:189], v[194:197], v[26:29]
	v_mfma_f32_16x16x32_bf16 v[46:49], v[166:169], v[202:205], v[46:49]
	v_mfma_f32_16x16x32_bf16 v[14:17], v[186:189], v[202:205], v[14:17]
	v_mfma_f32_16x16x32_bf16 v[42:45], v[166:169], v[210:213], v[42:45]
	v_mfma_f32_16x16x32_bf16 v[10:13], v[186:189], v[210:213], v[10:13]
	v_mfma_f32_16x16x32_bf16 v[34:37], v[166:169], v[218:221], v[34:37]
	v_mfma_f32_16x16x32_bf16 v[2:5], v[186:189], v[218:221], v[2:5]
	s_barrier
	s_add_i32 s69, s69, 2
	s_add_u32 s42, s42, 0x100
	s_addc_u32 s43, s43, 0
	s_add_u32 s67, s67, 0x100
	s_addc_u32 s68, s68, 0
	s_cmp_gt_u32 s69, 13
	s_cbranch_scc0 .LBB0_1528
	s_and_b64 vcc, exec, s[26:27]
	s_cbranch_vccz .LBB0_1531
	s_barrier

; #define PG8_STAGE(bufoff, gbase, voff) do { _Pragma("unroll") for (int _i = 0; _i < 2; ++_i) \
;         __builtin_amdgcn_global_load_lds((const unsigned*)((const char*)(gbase) + (voff)[_i]), (PG8_LAS unsigned*)(lds + (bufoff) + ldsw + _i * 8192), 16, 0, 0); } while (0)
; #define PG8_LDA(dst, b, h) do { _Pragma("unroll") for (int m = 0; m < 4; ++m) _Pragma("unroll") for (int k = 0; k < 2; ++k) dst[m][k] = *(const PG8_LAS bf16x8*)(lds + PG8_SA(b, h) + aoff + m * 2048 + k * 1024); } while (0)
; #define PG8_LDB(dst, b, h) do { _Pragma("unroll") for (int n = 0; n < 2; ++n) _Pragma("unroll") for (int k = 0; k < 2; ++k) dst[n][k] = *(const PG8_LAS bf16x8*)(lds + PG8_SB(b, h) + boff + n * 2048 + k * 1024); } while (0)
; #define PG8_MMA(ai, bj, At, Bt) do { __builtin_amdgcn_s_setprio(1); _Pragma("unroll") for (int m = 0; m < 4; ++m) _Pragma("unroll") for (int n = 0; n < 2; ++n) _Pragma("unroll") for (int k = 0; k < 2; ++k) \
;         acc[ai][bj][m][n] = __builtin_amdgcn_mfma_f32_16x16x32_bf16(Bt[n][k], At[m][k], acc[ai][bj][m][n], 0, 0, 0); __builtin_amdgcn_s_setprio(0); } while (0)
; #define PG8_WAIT_V(n) asm volatile("s_waitcnt vmcnt(" #n ")" ::: "memory")
; #define PG8_WAIT_L(n) asm volatile("s_waitcnt lgkmcnt(" #n ")" ::: "memory")
; #define PG8_BAR __builtin_amdgcn_s_barrier()
; #define PG8_SCHED __builtin_amdgcn_sched_barrier(0)
; template <class Epi, class Sched, bool ALIGN_EPI = false, bool SP2 = false>
; __device__ __forceinline__ void gemm_phase(PG8_LAS unsigned char* lds, const Gemm g, const Sched& S, const Epi& E) {
;     ...
;             PG8_LDB(B0, 0, 0); PG8_LDB(B1, 0, 1); PG8_SCHED; PG8_LDA(At, 0, 0); PG8_STAGE(PG8_SA(1, 1), a1 + hstepA, voffA);
;             PG8_WAIT_V(8); PG8_WAIT_L(0); PG8_BAR; PG8_MMA(0, 0, At, B0); PG8_MMA(0, 1, At, B1); PG8_BAR; PG8_SCHED;
;             PG8_LDA(At, 0, 1); PG8_STAGE(PG8_SB(0, 0), b2, voffB); PG8_STAGE(PG8_SB(0, 1), b2 + hstepB, voffB); PG8_STAGE(PG8_SA(0, 0), a2, voffA);
;             PG8_WAIT_V(8); PG8_WAIT_L(0); PG8_BAR; PG8_MMA(1, 0, At, B0); PG8_MMA(1, 1, At, B1); PG8_BAR; PG8_SCHED;
.LBB0_1838:
	v_add_u32_e32 v24, s50, v22
	ds_read_b128 v[34:37], v24
	ds_read_b128 v[38:41], v24 offset:1024
	ds_read_b128 v[42:45], v24 offset:2048
	ds_read_b128 v[46:49], v24 offset:3072
	v_add_u32_e32 v24, s51, v22
	s_add_u32 s22, s14, s20
	ds_read_b128 v[50:53], v24
	ds_read_b128 v[54:57], v24 offset:1024
	ds_read_b128 v[66:69], v24 offset:2048
	ds_read_b128 v[70:73], v24 offset:3072
	s_addc_u32 s23, s15, s21
	s_add_u32 s22, s22, 0x100
	s_addc_u32 s23, s23, 0
	s_add_u32 s58, s55, s20
	s_addc_u32 s59, s56, s21
	s_cmpk_eq_i32 s20, 0x1500
	s_cselect_b32 s25, s19, s23
	s_cselect_b32 s24, s18, s22
	s_cselect_b32 s23, s1, s59
	s_cselect_b32 s22, s0, s58
	v_lshl_add_u64 v[24:25], v[18:19], 0, s[20:21]
	s_add_i32 m0, s42, 0xc000
	ds_read_b128 v[162:165], v23
	ds_read_b128 v[166:169], v23 offset:1024
	ds_read_b128 v[194:197], v23 offset:2048
	ds_read_b128 v[198:201], v23 offset:3072
	ds_read_b128 v[202:205], v23 offset:4096
	ds_read_b128 v[206:209], v23 offset:5120
	ds_read_b128 v[210:213], v23 offset:6144
	ds_read_b128 v[216:219], v23 offset:7168
	global_load_lds_dwordx4 v[24:25], off
	v_lshl_add_u64 v[24:25], v[20:21], 0, s[20:21]
	s_add_i32 m0, s42, 0xe000
	s_nop 0
	global_load_lds_dwordx4 v[24:25], off
	s_waitcnt vmcnt(8)
	s_waitcnt lgkmcnt(0)
	s_barrier
	s_waitcnt lgkmcnt(0)
	v_mfma_f32_16x16x32_bf16 v[170:173], v[34:37], v[162:165], v[170:173]
	v_mfma_f32_16x16x32_bf16 v[174:177], v[42:45], v[162:165], v[174:177]
	v_mfma_f32_16x16x32_bf16 v[178:181], v[34:37], v[194:197], v[178:181]
	v_mfma_f32_16x16x32_bf16 v[182:185], v[42:45], v[194:197], v[182:185]
	v_mfma_f32_16x16x32_bf16 v[186:189], v[34:37], v[202:205], v[186:189]
	v_mfma_f32_16x16x32_bf16 v[190:193], v[42:45], v[202:205], v[190:193]
	v_mfma_f32_16x16x32_bf16 v[158:161], v[34:37], v[210:213], v[158:161]
	v_mfma_f32_16x16x32_bf16 v[154:157], v[42:45], v[210:213], v[154:157]
	v_mfma_f32_16x16x32_bf16 v[170:173], v[38:41], v[166:169], v[170:173]
	v_mfma_f32_16x16x32_bf16 v[174:177], v[46:49], v[166:169], v[174:177]
	v_mfma_f32_16x16x32_bf16 v[178:181], v[38:41], v[198:201], v[178:181]
	v_mfma_f32_16x16x32_bf16 v[182:185], v[46:49], v[198:201], v[182:185]
	v_mfma_f32_16x16x32_bf16 v[186:189], v[38:41], v[206:209], v[186:189]
	v_mfma_f32_16x16x32_bf16 v[190:193], v[46:49], v[206:209], v[190:193]
	v_mfma_f32_16x16x32_bf16 v[158:161], v[38:41], v[216:219], v[158:161]
	v_mfma_f32_16x16x32_bf16 v[154:157], v[46:49], v[216:219], v[154:157]
	v_mfma_f32_16x16x32_bf16 v[62:65], v[50:53], v[162:165], v[62:65]
	v_mfma_f32_16x16x32_bf16 v[58:61], v[66:69], v[162:165], v[58:61]
	v_mfma_f32_16x16x32_bf16 v[74:77], v[50:53], v[194:197], v[74:77]
	v_mfma_f32_16x16x32_bf16 v[78:81], v[66:69], v[194:197], v[78:81]
	v_mfma_f32_16x16x32_bf16 v[90:93], v[50:53], v[202:205], v[90:93]
	v_mfma_f32_16x16x32_bf16 v[94:97], v[66:69], v[202:205], v[94:97]
	v_mfma_f32_16x16x32_bf16 v[106:109], v[50:53], v[210:213], v[106:109]
	v_mfma_f32_16x16x32_bf16 v[110:113], v[66:69], v[210:213], v[110:113]
	v_mfma_f32_16x16x32_bf16 v[62:65], v[54:57], v[166:169], v[62:65]
	v_mfma_f32_16x16x32_bf16 v[58:61], v[70:73], v[166:169], v[58:61]
	v_mfma_f32_16x16x32_bf16 v[74:77], v[54:57], v[198:201], v[74:77]
	v_mfma_f32_16x16x32_bf16 v[78:81], v[70:73], v[198:201], v[78:81]
	v_mfma_f32_16x16x32_bf16 v[90:93], v[54:57], v[206:209], v[90:93]
	v_mfma_f32_16x16x32_bf16 v[94:97], v[70:73], v[206:209], v[94:97]
	v_mfma_f32_16x16x32_bf16 v[106:109], v[54:57], v[216:219], v[106:109]
	v_mfma_f32_16x16x32_bf16 v[110:113], v[70:73], v[216:219], v[110:113]
	s_barrier
	s_add_i32 s58, s50, s41
	s_add_u32 s98, s22, 0x80
	s_addc_u32 s99, s23, 0
	s_mov_b32 m0, s58
	ds_read_b128 v[162:165], v23 offset:16384
	ds_read_b128 v[166:169], v23 offset:17408
	ds_read_b128 v[194:197], v23 offset:18432
	ds_read_b128 v[198:201], v23 offset:19456
	ds_read_b128 v[202:205], v23 offset:20480
	ds_read_b128 v[206:209], v23 offset:21504
	ds_read_b128 v[210:213], v23 offset:22528
	ds_read_b128 v[216:219], v23 offset:23552
	global_load_lds_dwordx4 v4, s[22:23]
	s_add_i32 m0, s58, 0x2000
	s_add_u32 s58, s22, 0xb0000
	s_addc_u32 s59, s23, 0
	s_add_i32 s60, s51, s41
	global_load_lds_dwordx4 v8, s[22:23]
	s_mov_b32 m0, s60
	s_add_u32 s100, s24, 0x80
	s_addc_u32 s101, s25, 0
	global_load_lds_dwordx4 v4, s[58:59]
	s_add_i32 m0, s60, 0x2000
	s_nop 0
	global_load_lds_dwordx4 v8, s[58:59]
	s_mov_b32 m0, s42
	s_nop 0
	global_load_lds_dwordx4 v2, s[24:25]
	s_mov_b32 m0, s43
	s_nop 0
	global_load_lds_dwordx4 v6, s[24:25]
	s_waitcnt vmcnt(8)
	s_waitcnt lgkmcnt(0)
	s_barrier
	s_waitcnt lgkmcnt(0)
	v_mfma_f32_16x16x32_bf16 v[150:153], v[34:37], v[162:165], v[150:153]
	v_mfma_f32_16x16x32_bf16 v[146:149], v[42:45], v[162:165], v[146:149]
	v_mfma_f32_16x16x32_bf16 v[142:145], v[34:37], v[194:197], v[142:145]
	v_mfma_f32_16x16x32_bf16 v[138:141], v[42:45], v[194:197], v[138:141]
	v_mfma_f32_16x16x32_bf16 v[134:137], v[34:37], v[202:205], v[134:137]
	v_mfma_f32_16x16x32_bf16 v[130:133], v[42:45], v[202:205], v[130:133]
	v_mfma_f32_16x16x32_bf16 v[34:37], v[34:37], v[210:213], v[98:101]
	v_mfma_f32_16x16x32_bf16 v[150:153], v[38:41], v[166:169], v[150:153]
	v_mfma_f32_16x16x32_bf16 v[146:149], v[46:49], v[166:169], v[146:149]
	v_mfma_f32_16x16x32_bf16 v[142:145], v[38:41], v[198:201], v[142:145]
	v_mfma_f32_16x16x32_bf16 v[138:141], v[46:49], v[198:201], v[138:141]
	v_mfma_f32_16x16x32_bf16 v[134:137], v[38:41], v[206:209], v[134:137]
	v_mfma_f32_16x16x32_bf16 v[130:133], v[46:49], v[206:209], v[130:133]
	v_mfma_f32_16x16x32_bf16 v[34:37], v[38:41], v[216:219], v[34:37]
	v_mfma_f32_16x16x32_bf16 v[38:41], v[42:45], v[210:213], v[82:85]
	v_mfma_f32_16x16x32_bf16 v[38:41], v[46:49], v[216:219], v[38:41]
	v_mfma_f32_16x16x32_bf16 v[82:85], v[50:53], v[194:197], v[122:125]
	v_mfma_f32_16x16x32_bf16 v[122:125], v[54:57], v[198:201], v[82:85]
	v_mfma_f32_16x16x32_bf16 v[82:85], v[66:69], v[194:197], v[126:129]
	v_mfma_f32_16x16x32_bf16 v[126:129], v[70:73], v[198:201], v[82:85]
	v_mfma_f32_16x16x32_bf16 v[82:85], v[50:53], v[202:205], v[102:105]
	v_mfma_f32_16x16x32_bf16 v[102:105], v[54:57], v[206:209], v[82:85]
	v_mfma_f32_16x16x32_bf16 v[82:85], v[66:69], v[202:205], v[86:89]
	v_mfma_f32_16x16x32_bf16 v[30:33], v[50:53], v[210:213], v[30:33]
	v_mfma_f32_16x16x32_bf16 v[24:27], v[66:69], v[210:213], v[26:29]
	v_mfma_f32_16x16x32_bf16 v[42:45], v[50:53], v[162:165], v[114:117]
	v_mfma_f32_16x16x32_bf16 v[46:49], v[66:69], v[162:165], v[118:121]
	v_mfma_f32_16x16x32_bf16 v[86:89], v[70:73], v[206:209], v[82:85]
	v_mfma_f32_16x16x32_bf16 v[30:33], v[54:57], v[216:219], v[30:33]
	v_mfma_f32_16x16x32_bf16 v[24:27], v[70:73], v[216:219], v[24:27]
	v_mfma_f32_16x16x32_bf16 v[42:45], v[54:57], v[166:169], v[42:45]
	v_mfma_f32_16x16x32_bf16 v[46:49], v[70:73], v[166:169], v[46:49]
	s_barrier
; #define PG8_STAGE(bufoff, gbase, voff) do { _Pragma("unroll") for (int _i = 0; _i < 2; ++_i) \
;         __builtin_amdgcn_global_load_lds((const unsigned*)((const char*)(gbase) + (voff)[_i]), (PG8_LAS unsigned*)(lds + (bufoff) + ldsw + _i * 8192), 16, 0, 0); } while (0)
; #define PG8_LDA(dst, b, h) do { _Pragma("unroll") for (int m = 0; m < 4; ++m) _Pragma("unroll") for (int k = 0; k < 2; ++k) dst[m][k] = *(const PG8_LAS bf16x8*)(lds + PG8_SA(b, h) + aoff + m * 2048 + k * 1024); } while (0)
; #define PG8_LDB(dst, b, h) do { _Pragma("unroll") for (int n = 0; n < 2; ++n) _Pragma("unroll") for (int k = 0; k < 2; ++k) dst[n][k] = *(const PG8_LAS bf16x8*)(lds + PG8_SB(b, h) + boff + n * 2048 + k * 1024); } while (0)
; #define PG8_MMA(ai, bj, At, Bt) do { __builtin_amdgcn_s_setprio(1); _Pragma("unroll") for (int m = 0; m < 4; ++m) _Pragma("unroll") for (int n = 0; n < 2; ++n) _Pragma("unroll") for (int k = 0; k < 2; ++k) \
;         acc[ai][bj][m][n] = __builtin_amdgcn_mfma_f32_16x16x32_bf16(Bt[n][k], At[m][k], acc[ai][bj][m][n], 0, 0, 0); __builtin_amdgcn_s_setprio(0); } while (0)
; #define PG8_WAIT_V(n) asm volatile("s_waitcnt vmcnt(" #n ")" ::: "memory")
; #define PG8_WAIT_L(n) asm volatile("s_waitcnt lgkmcnt(" #n ")" ::: "memory")
; #define PG8_BAR __builtin_amdgcn_s_barrier()
; #define PG8_SCHED __builtin_amdgcn_sched_barrier(0)
; template <class Epi, class Sched, bool ALIGN_EPI = false, bool SP2 = false>
; __device__ __forceinline__ void gemm_phase(PG8_LAS unsigned char* lds, const Gemm g, const Sched& S, const Epi& E) {
;     ...
;             PG8_LDB(B0, 1, 0); PG8_LDB(B1, 1, 1); PG8_SCHED; PG8_LDA(At, 1, 0); PG8_STAGE(PG8_SA(0, 1), a2 + hstepA, voffA);
;             PG8_WAIT_V(8); PG8_WAIT_L(0); PG8_BAR; PG8_MMA(0, 0, At, B0); PG8_MMA(0, 1, At, B1); PG8_BAR; PG8_SCHED;
;             PG8_LDA(At, 1, 1); PG8_STAGE(PG8_SB(1, 0), b3, voffB); PG8_STAGE(PG8_SB(1, 1), b3 + hstepB, voffB); PG8_STAGE(PG8_SA(1, 0), a3, voffA);
	s_add_i32 s58, 0, 0x18000
	v_add_u32_e32 v28, s58, v22
	s_add_i32 s59, 0, 0x1c000
	ds_read_b128 v[50:53], v28
	ds_read_b128 v[54:57], v28 offset:1024
	ds_read_b128 v[66:69], v28 offset:2048
	ds_read_b128 v[70:73], v28 offset:3072
	v_add_u32_e32 v28, s59, v22
	ds_read_b128 v[162:165], v28
	ds_read_b128 v[166:169], v28 offset:1024
	ds_read_b128 v[194:197], v28 offset:2048
	ds_read_b128 v[198:201], v28 offset:3072
	s_add_u32 s24, s24, 0xb0000
	s_addc_u32 s25, s25, 0
	s_mov_b32 m0, s45
	ds_read_b128 v[82:85], v23 offset:32768
	ds_read_b128 v[98:101], v23 offset:33792
	ds_read_b128 v[114:117], v23 offset:34816
	ds_read_b128 v[118:121], v23 offset:35840
	ds_read_b128 v[202:205], v23 offset:36864
	ds_read_b128 v[206:209], v23 offset:37888
	ds_read_b128 v[210:213], v23 offset:38912
	ds_read_b128 v[216:219], v23 offset:39936
	global_load_lds_dwordx4 v2, s[24:25]
	s_mov_b32 m0, s46
	s_nop 0
	global_load_lds_dwordx4 v6, s[24:25]
	s_waitcnt vmcnt(8)
	s_waitcnt lgkmcnt(0)
	s_barrier
	s_waitcnt lgkmcnt(0)
	v_mfma_f32_16x16x32_bf16 v[170:173], v[50:53], v[82:85], v[170:173]
	v_mfma_f32_16x16x32_bf16 v[174:177], v[66:69], v[82:85], v[174:177]
	v_mfma_f32_16x16x32_bf16 v[178:181], v[50:53], v[114:117], v[178:181]
	v_mfma_f32_16x16x32_bf16 v[182:185], v[66:69], v[114:117], v[182:185]
	v_mfma_f32_16x16x32_bf16 v[186:189], v[50:53], v[202:205], v[186:189]
	v_mfma_f32_16x16x32_bf16 v[190:193], v[66:69], v[202:205], v[190:193]
	v_mfma_f32_16x16x32_bf16 v[158:161], v[50:53], v[210:213], v[158:161]
	v_mfma_f32_16x16x32_bf16 v[154:157], v[66:69], v[210:213], v[154:157]
	v_mfma_f32_16x16x32_bf16 v[170:173], v[54:57], v[98:101], v[170:173]
	v_mfma_f32_16x16x32_bf16 v[174:177], v[70:73], v[98:101], v[174:177]
	v_mfma_f32_16x16x32_bf16 v[178:181], v[54:57], v[118:121], v[178:181]
	v_mfma_f32_16x16x32_bf16 v[182:185], v[70:73], v[118:121], v[182:185]
	v_mfma_f32_16x16x32_bf16 v[186:189], v[54:57], v[206:209], v[186:189]
	v_mfma_f32_16x16x32_bf16 v[190:193], v[70:73], v[206:209], v[190:193]
	v_mfma_f32_16x16x32_bf16 v[158:161], v[54:57], v[216:219], v[158:161]
	v_mfma_f32_16x16x32_bf16 v[154:157], v[70:73], v[216:219], v[154:157]
	v_mfma_f32_16x16x32_bf16 v[62:65], v[162:165], v[82:85], v[62:65]
	v_mfma_f32_16x16x32_bf16 v[58:61], v[194:197], v[82:85], v[58:61]
	v_mfma_f32_16x16x32_bf16 v[82:85], v[162:165], v[202:205], v[90:93]
	v_mfma_f32_16x16x32_bf16 v[90:93], v[166:169], v[206:209], v[82:85]
	v_mfma_f32_16x16x32_bf16 v[82:85], v[194:197], v[202:205], v[94:97]
	v_mfma_f32_16x16x32_bf16 v[94:97], v[198:201], v[206:209], v[82:85]
	v_mfma_f32_16x16x32_bf16 v[82:85], v[162:165], v[210:213], v[106:109]
	v_mfma_f32_16x16x32_bf16 v[74:77], v[162:165], v[114:117], v[74:77]
	v_mfma_f32_16x16x32_bf16 v[78:81], v[194:197], v[114:117], v[78:81]
	v_mfma_f32_16x16x32_bf16 v[106:109], v[166:169], v[216:219], v[82:85]
	v_mfma_f32_16x16x32_bf16 v[82:85], v[194:197], v[210:213], v[110:113]
	v_mfma_f32_16x16x32_bf16 v[62:65], v[166:169], v[98:101], v[62:65]
	v_mfma_f32_16x16x32_bf16 v[58:61], v[198:201], v[98:101], v[58:61]
	v_mfma_f32_16x16x32_bf16 v[74:77], v[166:169], v[118:121], v[74:77]
	v_mfma_f32_16x16x32_bf16 v[78:81], v[198:201], v[118:121], v[78:81]
	v_mfma_f32_16x16x32_bf16 v[110:113], v[198:201], v[216:219], v[82:85]
	s_barrier
	s_add_i32 s24, s58, s41
	s_mov_b32 m0, s24
	ds_read_b128 v[118:121], v23 offset:49152
	ds_read_b128 v[202:205], v23 offset:50176
	ds_read_b128 v[206:209], v23 offset:51200
	ds_read_b128 v[210:213], v23 offset:52224
	ds_read_b128 v[216:219], v23 offset:53248
	ds_read_b128 v[220:223], v23 offset:54272
	ds_read_b128 v[224:227], v23 offset:55296
	ds_read_b128 v[228:231], v23 offset:56320
	global_load_lds_dwordx4 v4, s[98:99]
	s_add_i32 m0, s24, 0x2000
	s_add_u32 s22, s22, 0xb0080
	s_addc_u32 s23, s23, 0
	s_add_i32 s24, s59, s41
	global_load_lds_dwordx4 v8, s[98:99]
	s_mov_b32 m0, s24
	s_nop 0
	global_load_lds_dwordx4 v4, s[22:23]
	s_add_i32 m0, s24, 0x2000
	s_nop 0
	global_load_lds_dwordx4 v8, s[22:23]
	s_mov_b32 m0, s48
	s_nop 0
	global_load_lds_dwordx4 v2, s[100:101]
	s_mov_b32 m0, s49
	s_nop 0
	global_load_lds_dwordx4 v6, s[100:101]
	s_waitcnt vmcnt(8)
	s_waitcnt lgkmcnt(0)
	s_barrier
; #define PG8_MMA(ai, bj, At, Bt) do { __builtin_amdgcn_s_setprio(1); _Pragma("unroll") for (int m = 0; m < 4; ++m) _Pragma("unroll") for (int n = 0; n < 2; ++n) _Pragma("unroll") for (int k = 0; k < 2; ++k) \
;         acc[ai][bj][m][n] = __builtin_amdgcn_mfma_f32_16x16x32_bf16(Bt[n][k], At[m][k], acc[ai][bj][m][n], 0, 0, 0); __builtin_amdgcn_s_setprio(0); } while (0)
; #define PG8_WAIT_V(n) asm volatile("s_waitcnt vmcnt(" #n ")" ::: "memory")
; #define PG8_WAIT_L(n) asm volatile("s_waitcnt lgkmcnt(" #n ")" ::: "memory")
; #define PG8_BAR __builtin_amdgcn_s_barrier()
; #define PG8_SCHED __builtin_amdgcn_sched_barrier(0)
; template <class Epi, class Sched, bool ALIGN_EPI = false, bool SP2 = false>
; __device__ __forceinline__ void gemm_phase(PG8_LAS unsigned char* lds, const Gemm g, const Sched& S, const Epi& E) {
;     ...
;             PG8_WAIT_V(8); PG8_WAIT_L(0); PG8_BAR; PG8_MMA(1, 0, At, B0); PG8_MMA(1, 1, At, B1); PG8_BAR; PG8_SCHED;
;     ...
; #pragma unroll
;         for (int a = 0; a < 2; ++a)
; #pragma unroll
;             for (int b = 0; b < 2; ++b)
; #pragma unroll
;                 for (int m = 0; m < 4; ++m)
; #pragma unroll
;                     for (int n = 0; n < 2; ++n) acc[a][b][m][n] = (f32x4){0.f, 0.f, 0.f, 0.f};
	s_waitcnt lgkmcnt(0)
	v_mfma_f32_16x16x32_bf16 v[82:85], v[50:53], v[118:121], v[150:153]
	v_mfma_f32_16x16x32_bf16 v[150:153], v[54:57], v[202:205], v[82:85]
	v_mfma_f32_16x16x32_bf16 v[82:85], v[66:69], v[118:121], v[146:149]
	v_mfma_f32_16x16x32_bf16 v[146:149], v[70:73], v[202:205], v[82:85]
	v_mfma_f32_16x16x32_bf16 v[82:85], v[50:53], v[206:209], v[142:145]
	v_mfma_f32_16x16x32_bf16 v[142:145], v[54:57], v[210:213], v[82:85]
	v_mfma_f32_16x16x32_bf16 v[82:85], v[66:69], v[206:209], v[138:141]
	v_mfma_f32_16x16x32_bf16 v[138:141], v[70:73], v[210:213], v[82:85]
	v_mfma_f32_16x16x32_bf16 v[82:85], v[50:53], v[216:219], v[134:137]
	v_mfma_f32_16x16x32_bf16 v[34:37], v[50:53], v[224:227], v[34:37]
	v_mfma_f32_16x16x32_bf16 v[134:137], v[54:57], v[220:223], v[82:85]
	v_mfma_f32_16x16x32_bf16 v[82:85], v[66:69], v[216:219], v[130:133]
	v_mfma_f32_16x16x32_bf16 v[98:101], v[54:57], v[228:231], v[34:37]
	v_mfma_f32_16x16x32_bf16 v[34:37], v[66:69], v[224:227], v[38:41]
	v_mfma_f32_16x16x32_bf16 v[130:133], v[70:73], v[220:223], v[82:85]
	v_mfma_f32_16x16x32_bf16 v[82:85], v[70:73], v[228:231], v[34:37]
	v_mfma_f32_16x16x32_bf16 v[34:37], v[162:165], v[118:121], v[42:45]
	v_mfma_f32_16x16x32_bf16 v[114:117], v[166:169], v[202:205], v[34:37]
	v_mfma_f32_16x16x32_bf16 v[34:37], v[194:197], v[118:121], v[46:49]
	v_mfma_f32_16x16x32_bf16 v[118:121], v[198:201], v[202:205], v[34:37]
	v_mfma_f32_16x16x32_bf16 v[34:37], v[162:165], v[206:209], v[122:125]
	v_mfma_f32_16x16x32_bf16 v[122:125], v[166:169], v[210:213], v[34:37]
	v_mfma_f32_16x16x32_bf16 v[34:37], v[194:197], v[206:209], v[126:129]
	v_mfma_f32_16x16x32_bf16 v[126:129], v[198:201], v[210:213], v[34:37]
	v_mfma_f32_16x16x32_bf16 v[34:37], v[162:165], v[216:219], v[102:105]
	v_mfma_f32_16x16x32_bf16 v[102:105], v[166:169], v[220:223], v[34:37]
	v_mfma_f32_16x16x32_bf16 v[34:37], v[194:197], v[216:219], v[86:89]
	v_mfma_f32_16x16x32_bf16 v[28:31], v[162:165], v[224:227], v[30:33]
	v_mfma_f32_16x16x32_bf16 v[24:27], v[194:197], v[224:227], v[24:27]
	v_mfma_f32_16x16x32_bf16 v[86:89], v[198:201], v[220:223], v[34:37]
	v_mfma_f32_16x16x32_bf16 v[30:33], v[166:169], v[228:231], v[28:31]
	v_mfma_f32_16x16x32_bf16 v[26:29], v[198:201], v[228:231], v[24:27]
	s_barrier
	s_add_i32 s57, s57, 2
	s_add_u32 s20, s20, 0x100
	s_addc_u32 s21, s21, 0
	s_cmp_gt_u32 s57, 41
	s_cbranch_scc0 .LBB0_1838
	s_add_u32 s20, s55, 0xffffff00
	s_addc_u32 s21, s56, -1
	s_and_b64 vcc, exec, s[4:5]
	s_cbranch_vccnz .LBB0_1825
	v_mov_b32_e32 v26, 0
	s_mov_b32 s12, s52
	s_mov_b32 s27, s53
	s_mov_b64 s[14:15], s[18:19]
	s_mov_b32 s47, s54
	v_mov_b32_e32 v27, v26
	v_mov_b32_e32 v28, v26
	v_mov_b32_e32 v29, v26
	v_mov_b32_e32 v30, v26
	v_mov_b32_e32 v31, v26
	v_mov_b32_e32 v32, v26
	v_mov_b32_e32 v33, v26
	v_mov_b32_e32 v86, v26
	v_mov_b32_e32 v87, v26
	v_mov_b32_e32 v88, v26
	v_mov_b32_e32 v89, v26
	v_mov_b32_e32 v102, v26
	v_mov_b32_e32 v103, v26
	v_mov_b32_e32 v104, v26
	v_mov_b32_e32 v105, v26
	v_mov_b32_e32 v126, v26
	v_mov_b32_e32 v127, v26
	v_mov_b32_e32 v128, v26
	v_mov_b32_e32 v129, v26
	v_mov_b32_e32 v122, v26
	v_mov_b32_e32 v123, v26
	v_mov_b32_e32 v124, v26
	v_mov_b32_e32 v125, v26
	v_mov_b32_e32 v118, v26
	v_mov_b32_e32 v119, v26
	v_mov_b32_e32 v120, v26
	v_mov_b32_e32 v121, v26
	v_mov_b32_e32 v114, v26
	v_mov_b32_e32 v115, v26
	v_mov_b32_e32 v116, v26
	v_mov_b32_e32 v117, v26
	v_mov_b32_e32 v82, v26
	v_mov_b32_e32 v83, v26
	v_mov_b32_e32 v84, v26
	v_mov_b32_e32 v85, v26
	v_mov_b32_e32 v98, v26
	v_mov_b32_e32 v99, v26
	v_mov_b32_e32 v100, v26
	v_mov_b32_e32 v101, v26
	v_mov_b32_e32 v130, v26
	v_mov_b32_e32 v131, v26
	v_mov_b32_e32 v132, v26
	v_mov_b32_e32 v133, v26
	v_mov_b32_e32 v134, v26
	v_mov_b32_e32 v135, v26
	v_mov_b32_e32 v136, v26
	v_mov_b32_e32 v137, v26
	v_mov_b32_e32 v138, v26
	v_mov_b32_e32 v139, v26
	v_mov_b32_e32 v140, v26
	v_mov_b32_e32 v141, v26
	v_mov_b32_e32 v142, v26
	v_mov_b32_e32 v143, v26
	v_mov_b32_e32 v144, v26
	v_mov_b32_e32 v145, v26
	v_mov_b32_e32 v146, v26
	v_mov_b32_e32 v147, v26
	v_mov_b32_e32 v148, v26
	v_mov_b32_e32 v149, v26
	v_mov_b32_e32 v150, v26
	v_mov_b32_e32 v151, v26
	v_mov_b32_e32 v152, v26
	v_mov_b32_e32 v153, v26
	v_mov_b32_e32 v110, v26
	v_mov_b32_e32 v111, v26
	v_mov_b32_e32 v112, v26
	v_mov_b32_e32 v113, v26
	v_mov_b32_e32 v106, v26
	v_mov_b32_e32 v107, v26
	v_mov_b32_e32 v108, v26
	v_mov_b32_e32 v109, v26
	v_mov_b32_e32 v94, v26
	v_mov_b32_e32 v95, v26
	v_mov_b32_e32 v96, v26
	v_mov_b32_e32 v97, v26
	v_mov_b32_e32 v90, v26
	v_mov_b32_e32 v91, v26
	v_mov_b32_e32 v92, v26
	v_mov_b32_e32 v93, v26
	v_mov_b32_e32 v78, v26
	v_mov_b32_e32 v79, v26
	v_mov_b32_e32 v80, v26
	v_mov_b32_e32 v81, v26
	v_mov_b32_e32 v74, v26
	v_mov_b32_e32 v75, v26
	v_mov_b32_e32 v76, v26
	v_mov_b32_e32 v77, v26
	v_mov_b32_e32 v58, v26
	v_mov_b32_e32 v59, v26
	v_mov_b32_e32 v60, v26
	v_mov_b32_e32 v61, v26
	v_mov_b32_e32 v62, v26
	v_mov_b32_e32 v63, v26
	v_mov_b32_e32 v64, v26
	v_mov_b32_e32 v65, v26
	v_mov_b32_e32 v154, v26
	v_mov_b32_e32 v155, v26
	v_mov_b32_e32 v156, v26
	v_mov_b32_e32 v157, v26
	v_mov_b32_e32 v158, v26
	v_mov_b32_e32 v159, v26
	v_mov_b32_e32 v160, v26
	v_mov_b32_e32 v161, v26
	v_mov_b32_e32 v190, v26
	v_mov_b32_e32 v191, v26
	v_mov_b32_e32 v192, v26
	v_mov_b32_e32 v193, v26
	v_mov_b32_e32 v186, v26
	v_mov_b32_e32 v187, v26
	v_mov_b32_e32 v188, v26
	v_mov_b32_e32 v189, v26
	v_mov_b32_e32 v182, v26
	v_mov_b32_e32 v183, v26
	v_mov_b32_e32 v184, v26
	v_mov_b32_e32 v185, v26
	v_mov_b32_e32 v178, v26
	v_mov_b32_e32 v179, v26
	v_mov_b32_e32 v180, v26
	v_mov_b32_e32 v181, v26
	v_mov_b32_e32 v174, v26
	v_mov_b32_e32 v175, v26
	v_mov_b32_e32 v176, v26
	v_mov_b32_e32 v177, v26
	v_mov_b32_e32 v170, v26
	v_mov_b32_e32 v171, v26
	v_mov_b32_e32 v172, v26
	v_mov_b32_e32 v173, v26
	s_andn2_b64 vcc, exec, s[2:3]
	s_cbranch_vccnz .LBB0_1826

; #define PG8_STAGE(bufoff, gbase, voff) do { _Pragma("unroll") for (int _i = 0; _i < 2; ++_i) \
;         __builtin_amdgcn_global_load_lds((const unsigned*)((const char*)(gbase) + (voff)[_i]), (PG8_LAS unsigned*)(lds + (bufoff) + ldsw + _i * 8192), 16, 0, 0); } while (0)
; #define PG8_LDA(dst, b, h) do { _Pragma("unroll") for (int m = 0; m < 4; ++m) _Pragma("unroll") for (int k = 0; k < 2; ++k) dst[m][k] = *(const PG8_LAS bf16x8*)(lds + PG8_SA(b, h) + aoff + m * 2048 + k * 1024); } while (0)
; #define PG8_LDB(dst, b, h) do { _Pragma("unroll") for (int n = 0; n < 2; ++n) _Pragma("unroll") for (int k = 0; k < 2; ++k) dst[n][k] = *(const PG8_LAS bf16x8*)(lds + PG8_SB(b, h) + boff + n * 2048 + k * 1024); } while (0)
; #define PG8_MMA(ai, bj, At, Bt) do { __builtin_amdgcn_s_setprio(1); _Pragma("unroll") for (int m = 0; m < 4; ++m) _Pragma("unroll") for (int n = 0; n < 2; ++n) _Pragma("unroll") for (int k = 0; k < 2; ++k) \
;         acc[ai][bj][m][n] = __builtin_amdgcn_mfma_f32_16x16x32_bf16(Bt[n][k], At[m][k], acc[ai][bj][m][n], 0, 0, 0); __builtin_amdgcn_s_setprio(0); } while (0)
; #define PG8_WAIT_V(n) asm volatile("s_waitcnt vmcnt(" #n ")" ::: "memory")
; #define PG8_WAIT_L(n) asm volatile("s_waitcnt lgkmcnt(" #n ")" ::: "memory")
; #define PG8_BAR __builtin_amdgcn_s_barrier()
; #define PG8_SCHED __builtin_amdgcn_sched_barrier(0)
; template <class Epi, class Sched, bool ALIGN_EPI = false, bool SP2 = false>
; __device__ __forceinline__ void gemm_phase(PG8_LAS unsigned char* lds, const Gemm g, const Sched& S, const Epi& E) {
;     ...
;             PG8_LDB(B0, 0, 0); PG8_LDB(B1, 0, 1); PG8_SCHED; PG8_LDA(At, 0, 0); PG8_STAGE(PG8_SA(1, 1), a1 + hstepA, voffA);
;             PG8_WAIT_V(8); PG8_WAIT_L(0); PG8_BAR; PG8_MMA(0, 0, At, B0); PG8_MMA(0, 1, At, B1); PG8_BAR; PG8_SCHED;
;             PG8_LDA(At, 0, 1); PG8_STAGE(PG8_SB(0, 0), b2, voffB); PG8_STAGE(PG8_SB(0, 1), b2 + hstepB, voffB); PG8_STAGE(PG8_SA(0, 0), a2, voffA);
;             PG8_WAIT_V(8); PG8_WAIT_L(0); PG8_BAR; PG8_MMA(1, 0, At, B0); PG8_MMA(1, 1, At, B1); PG8_BAR; PG8_SCHED;
.LBB0_1897:
	ds_read_b128 v[130:133], v162
	ds_read_b128 v[134:137], v162 offset:1024
	ds_read_b128 v[138:141], v162 offset:2048
	ds_read_b128 v[142:145], v162 offset:3072
	ds_read_b128 v[156:159], v163
	ds_read_b128 v[166:169], v163 offset:1024
	ds_read_b128 v[170:173], v163 offset:2048
	ds_read_b128 v[174:177], v163 offset:3072
	s_add_u32 s22, s20, 0x100
	s_addc_u32 s23, s21, 0
	s_cmp_eq_u32 s68, 4
	s_cselect_b32 s27, s17, s23
	s_cselect_b32 s26, s16, s22
	s_cselect_b32 s25, s19, s67
	s_cselect_b32 s24, s18, s66
	v_lshl_add_u64 v[210:211], s[20:21], 0, v[152:153]
	s_add_i32 m0, s42, 0xc000
	ds_read_b128 v[178:181], v164
	ds_read_b128 v[182:185], v164 offset:1024
	ds_read_b128 v[186:189], v164 offset:2048
	ds_read_b128 v[190:193], v164 offset:3072
	ds_read_b128 v[194:197], v164 offset:4096
	ds_read_b128 v[198:201], v164 offset:5120
	ds_read_b128 v[202:205], v164 offset:6144
	ds_read_b128 v[206:209], v164 offset:7168
	global_load_lds_dwordx4 v[210:211], off
	v_lshl_add_u64 v[210:211], s[20:21], 0, v[154:155]
	s_add_i32 m0, s42, 0xe000
	s_nop 0
	global_load_lds_dwordx4 v[210:211], off
	s_waitcnt vmcnt(8)
	s_waitcnt lgkmcnt(0)
	s_barrier
	s_waitcnt lgkmcnt(0)
	v_mfma_f32_16x16x32_bf16 v[126:129], v[130:133], v[178:181], v[126:129]
	v_mfma_f32_16x16x32_bf16 v[122:125], v[138:141], v[178:181], v[122:125]
	v_mfma_f32_16x16x32_bf16 v[118:121], v[130:133], v[186:189], v[118:121]
	v_mfma_f32_16x16x32_bf16 v[114:117], v[138:141], v[186:189], v[114:117]
	v_mfma_f32_16x16x32_bf16 v[102:105], v[130:133], v[194:197], v[102:105]
	v_mfma_f32_16x16x32_bf16 v[90:93], v[138:141], v[194:197], v[90:93]
	v_mfma_f32_16x16x32_bf16 v[82:85], v[130:133], v[202:205], v[82:85]
	v_mfma_f32_16x16x32_bf16 v[74:77], v[138:141], v[202:205], v[74:77]
	v_mfma_f32_16x16x32_bf16 v[126:129], v[134:137], v[182:185], v[126:129]
	v_mfma_f32_16x16x32_bf16 v[122:125], v[142:145], v[182:185], v[122:125]
	v_mfma_f32_16x16x32_bf16 v[118:121], v[134:137], v[190:193], v[118:121]
	v_mfma_f32_16x16x32_bf16 v[114:117], v[142:145], v[190:193], v[114:117]
	v_mfma_f32_16x16x32_bf16 v[102:105], v[134:137], v[198:201], v[102:105]
	v_mfma_f32_16x16x32_bf16 v[90:93], v[142:145], v[198:201], v[90:93]
	v_mfma_f32_16x16x32_bf16 v[82:85], v[134:137], v[206:209], v[82:85]
	v_mfma_f32_16x16x32_bf16 v[74:77], v[142:145], v[206:209], v[74:77]
	v_mfma_f32_16x16x32_bf16 v[110:113], v[156:159], v[178:181], v[110:113]
	v_mfma_f32_16x16x32_bf16 v[106:109], v[170:173], v[178:181], v[106:109]
	v_mfma_f32_16x16x32_bf16 v[98:101], v[156:159], v[186:189], v[98:101]
	v_mfma_f32_16x16x32_bf16 v[94:97], v[170:173], v[186:189], v[94:97]
	v_mfma_f32_16x16x32_bf16 v[86:89], v[156:159], v[194:197], v[86:89]
	v_mfma_f32_16x16x32_bf16 v[78:81], v[170:173], v[194:197], v[78:81]
	v_mfma_f32_16x16x32_bf16 v[70:73], v[156:159], v[202:205], v[70:73]
	v_mfma_f32_16x16x32_bf16 v[66:69], v[170:173], v[202:205], v[66:69]
	v_mfma_f32_16x16x32_bf16 v[110:113], v[166:169], v[182:185], v[110:113]
	v_mfma_f32_16x16x32_bf16 v[106:109], v[174:177], v[182:185], v[106:109]
	v_mfma_f32_16x16x32_bf16 v[98:101], v[166:169], v[190:193], v[98:101]
	v_mfma_f32_16x16x32_bf16 v[94:97], v[174:177], v[190:193], v[94:97]
	v_mfma_f32_16x16x32_bf16 v[86:89], v[166:169], v[198:201], v[86:89]
	v_mfma_f32_16x16x32_bf16 v[78:81], v[174:177], v[198:201], v[78:81]
	v_mfma_f32_16x16x32_bf16 v[70:73], v[166:169], v[206:209], v[70:73]
	v_mfma_f32_16x16x32_bf16 v[66:69], v[174:177], v[206:209], v[66:69]
	s_barrier
	s_add_i32 s20, s54, s40
	s_add_u32 s98, s24, 0x80
	s_addc_u32 s99, s25, 0
	s_mov_b32 m0, s20
	ds_read_b128 v[178:181], v164 offset:16384
	ds_read_b128 v[182:185], v164 offset:17408
	ds_read_b128 v[186:189], v164 offset:18432
	ds_read_b128 v[190:193], v164 offset:19456
	ds_read_b128 v[194:197], v164 offset:20480
	ds_read_b128 v[198:201], v164 offset:21504
	ds_read_b128 v[202:205], v164 offset:22528
	ds_read_b128 v[206:209], v164 offset:23552
	global_load_lds_dwordx4 v148, s[24:25]
	s_add_i32 m0, s20, 0x2000
	s_add_u32 s20, s24, 0xb0000
	s_addc_u32 s21, s25, 0
	s_add_i32 s69, s55, s40
	global_load_lds_dwordx4 v146, s[24:25]
	s_mov_b32 m0, s69
	s_nop 0
	global_load_lds_dwordx4 v148, s[20:21]
	s_add_i32 m0, s69, 0x2000
	s_nop 0
	global_load_lds_dwordx4 v146, s[20:21]
	s_add_u32 s100, s26, 0x80
	s_addc_u32 s101, s27, 0
	s_mov_b32 m0, s42
	s_nop 0
	global_load_lds_dwordx4 v148, s[26:27]
	s_mov_b32 m0, s43
	s_nop 0
	global_load_lds_dwordx4 v146, s[26:27]
	s_waitcnt vmcnt(8)
	s_waitcnt lgkmcnt(0)
	s_barrier
	s_waitcnt lgkmcnt(0)
	v_mfma_f32_16x16x32_bf16 v[62:65], v[130:133], v[178:181], v[62:65]
	v_mfma_f32_16x16x32_bf16 v[58:61], v[138:141], v[178:181], v[58:61]
	v_mfma_f32_16x16x32_bf16 v[54:57], v[130:133], v[186:189], v[54:57]
	v_mfma_f32_16x16x32_bf16 v[50:53], v[138:141], v[186:189], v[50:53]
	v_mfma_f32_16x16x32_bf16 v[46:49], v[130:133], v[194:197], v[46:49]
	v_mfma_f32_16x16x32_bf16 v[38:41], v[138:141], v[194:197], v[38:41]
	v_mfma_f32_16x16x32_bf16 v[18:21], v[130:133], v[202:205], v[18:21]
	v_mfma_f32_16x16x32_bf16 v[10:13], v[138:141], v[202:205], v[10:13]
	v_mfma_f32_16x16x32_bf16 v[62:65], v[134:137], v[182:185], v[62:65]
	v_mfma_f32_16x16x32_bf16 v[58:61], v[142:145], v[182:185], v[58:61]
	v_mfma_f32_16x16x32_bf16 v[54:57], v[134:137], v[190:193], v[54:57]
	v_mfma_f32_16x16x32_bf16 v[50:53], v[142:145], v[190:193], v[50:53]
	v_mfma_f32_16x16x32_bf16 v[46:49], v[134:137], v[198:201], v[46:49]
	v_mfma_f32_16x16x32_bf16 v[38:41], v[142:145], v[198:201], v[38:41]
	v_mfma_f32_16x16x32_bf16 v[18:21], v[134:137], v[206:209], v[18:21]
	v_mfma_f32_16x16x32_bf16 v[10:13], v[142:145], v[206:209], v[10:13]
	v_mfma_f32_16x16x32_bf16 v[42:45], v[156:159], v[178:181], v[42:45]
	v_mfma_f32_16x16x32_bf16 v[34:37], v[170:173], v[178:181], v[34:37]
	v_mfma_f32_16x16x32_bf16 v[30:33], v[156:159], v[186:189], v[30:33]
	v_mfma_f32_16x16x32_bf16 v[26:29], v[170:173], v[186:189], v[26:29]
	v_mfma_f32_16x16x32_bf16 v[22:25], v[156:159], v[194:197], v[22:25]
	v_mfma_f32_16x16x32_bf16 v[14:17], v[170:173], v[194:197], v[14:17]
	v_mfma_f32_16x16x32_bf16 v[6:9], v[156:159], v[202:205], v[6:9]
	v_mfma_f32_16x16x32_bf16 v[2:5], v[170:173], v[202:205], v[2:5]
	v_mfma_f32_16x16x32_bf16 v[42:45], v[166:169], v[182:185], v[42:45]
	v_mfma_f32_16x16x32_bf16 v[34:37], v[174:177], v[182:185], v[34:37]
	v_mfma_f32_16x16x32_bf16 v[30:33], v[166:169], v[190:193], v[30:33]
	v_mfma_f32_16x16x32_bf16 v[26:29], v[174:177], v[190:193], v[26:29]
	v_mfma_f32_16x16x32_bf16 v[22:25], v[166:169], v[198:201], v[22:25]
	v_mfma_f32_16x16x32_bf16 v[14:17], v[174:177], v[198:201], v[14:17]
	v_mfma_f32_16x16x32_bf16 v[6:9], v[166:169], v[206:209], v[6:9]
	v_mfma_f32_16x16x32_bf16 v[2:5], v[174:177], v[206:209], v[2:5]
	s_barrier
; #define PG8_STAGE(bufoff, gbase, voff) do { _Pragma("unroll") for (int _i = 0; _i < 2; ++_i) \
;         __builtin_amdgcn_global_load_lds((const unsigned*)((const char*)(gbase) + (voff)[_i]), (PG8_LAS unsigned*)(lds + (bufoff) + ldsw + _i * 8192), 16, 0, 0); } while (0)
; #define PG8_LDA(dst, b, h) do { _Pragma("unroll") for (int m = 0; m < 4; ++m) _Pragma("unroll") for (int k = 0; k < 2; ++k) dst[m][k] = *(const PG8_LAS bf16x8*)(lds + PG8_SA(b, h) + aoff + m * 2048 + k * 1024); } while (0)
; #define PG8_LDB(dst, b, h) do { _Pragma("unroll") for (int n = 0; n < 2; ++n) _Pragma("unroll") for (int k = 0; k < 2; ++k) dst[n][k] = *(const PG8_LAS bf16x8*)(lds + PG8_SB(b, h) + boff + n * 2048 + k * 1024); } while (0)
; #define PG8_MMA(ai, bj, At, Bt) do { __builtin_amdgcn_s_setprio(1); _Pragma("unroll") for (int m = 0; m < 4; ++m) _Pragma("unroll") for (int n = 0; n < 2; ++n) _Pragma("unroll") for (int k = 0; k < 2; ++k) \
;         acc[ai][bj][m][n] = __builtin_amdgcn_mfma_f32_16x16x32_bf16(Bt[n][k], At[m][k], acc[ai][bj][m][n], 0, 0, 0); __builtin_amdgcn_s_setprio(0); } while (0)
; #define PG8_WAIT_V(n) asm volatile("s_waitcnt vmcnt(" #n ")" ::: "memory")
; #define PG8_WAIT_L(n) asm volatile("s_waitcnt lgkmcnt(" #n ")" ::: "memory")
; #define PG8_BAR __builtin_amdgcn_s_barrier()
; #define PG8_SCHED __builtin_amdgcn_sched_barrier(0)
; template <class Epi, class Sched, bool ALIGN_EPI = false, bool SP2 = false>
; __device__ __forceinline__ void gemm_phase(PG8_LAS unsigned char* lds, const Gemm g, const Sched& S, const Epi& E) {
;     ...
;         for (int t = 0; t < nt; t += 2) {
;             const bool last = (t == nt - 2);
;     ...
;             PG8_LDB(B0, 1, 0); PG8_LDB(B1, 1, 1); PG8_SCHED; PG8_LDA(At, 1, 0); PG8_STAGE(PG8_SA(0, 1), a2 + hstepA, voffA);
;             PG8_WAIT_V(8); PG8_WAIT_L(0); PG8_BAR; PG8_MMA(0, 0, At, B0); PG8_MMA(0, 1, At, B1); PG8_BAR; PG8_SCHED;
;             PG8_LDA(At, 1, 1); PG8_STAGE(PG8_SB(1, 0), b3, voffB); PG8_STAGE(PG8_SB(1, 1), b3 + hstepB, voffB); PG8_STAGE(PG8_SA(1, 0), a3, voffA);
;             PG8_WAIT_V(8); PG8_WAIT_L(0); PG8_BAR; PG8_MMA(1, 0, At, B0); PG8_MMA(1, 1, At, B1); PG8_BAR; PG8_SCHED;
	s_add_i32 s69, 0, 0x18000
	s_add_i32 s70, 0, 0x1c000
	v_add_u32_e32 v142, s69, v1
	v_add_u32_e32 v174, s70, v1
	ds_read_b128 v[130:133], v142
	ds_read_b128 v[134:137], v142 offset:1024
	ds_read_b128 v[138:141], v142 offset:2048
	ds_read_b128 v[142:145], v142 offset:3072
	ds_read_b128 v[156:159], v174
	ds_read_b128 v[166:169], v174 offset:1024
	ds_read_b128 v[170:173], v174 offset:2048
	ds_read_b128 v[174:177], v174 offset:3072
	s_add_u32 s20, s26, 0xb0000
	s_addc_u32 s21, s27, 0
	s_mov_b32 m0, s44
	ds_read_b128 v[178:181], v164 offset:32768
	ds_read_b128 v[182:185], v164 offset:33792
	ds_read_b128 v[186:189], v164 offset:34816
	ds_read_b128 v[190:193], v164 offset:35840
	ds_read_b128 v[194:197], v164 offset:36864
	ds_read_b128 v[198:201], v164 offset:37888
	ds_read_b128 v[202:205], v164 offset:38912
	ds_read_b128 v[206:209], v164 offset:39936
	global_load_lds_dwordx4 v148, s[20:21]
	s_mov_b32 m0, s45
	s_nop 0
	global_load_lds_dwordx4 v146, s[20:21]
	s_waitcnt vmcnt(8)
	s_waitcnt lgkmcnt(0)
	s_barrier
	s_waitcnt lgkmcnt(0)
	v_mfma_f32_16x16x32_bf16 v[126:129], v[130:133], v[178:181], v[126:129]
	v_mfma_f32_16x16x32_bf16 v[122:125], v[138:141], v[178:181], v[122:125]
	v_mfma_f32_16x16x32_bf16 v[118:121], v[130:133], v[186:189], v[118:121]
	v_mfma_f32_16x16x32_bf16 v[114:117], v[138:141], v[186:189], v[114:117]
	v_mfma_f32_16x16x32_bf16 v[102:105], v[130:133], v[194:197], v[102:105]
	v_mfma_f32_16x16x32_bf16 v[90:93], v[138:141], v[194:197], v[90:93]
	v_mfma_f32_16x16x32_bf16 v[82:85], v[130:133], v[202:205], v[82:85]
	v_mfma_f32_16x16x32_bf16 v[74:77], v[138:141], v[202:205], v[74:77]
	v_mfma_f32_16x16x32_bf16 v[126:129], v[134:137], v[182:185], v[126:129]
	v_mfma_f32_16x16x32_bf16 v[122:125], v[142:145], v[182:185], v[122:125]
	v_mfma_f32_16x16x32_bf16 v[118:121], v[134:137], v[190:193], v[118:121]
	v_mfma_f32_16x16x32_bf16 v[114:117], v[142:145], v[190:193], v[114:117]
	v_mfma_f32_16x16x32_bf16 v[102:105], v[134:137], v[198:201], v[102:105]
	v_mfma_f32_16x16x32_bf16 v[90:93], v[142:145], v[198:201], v[90:93]
	v_mfma_f32_16x16x32_bf16 v[82:85], v[134:137], v[206:209], v[82:85]
	v_mfma_f32_16x16x32_bf16 v[74:77], v[142:145], v[206:209], v[74:77]
	v_mfma_f32_16x16x32_bf16 v[110:113], v[156:159], v[178:181], v[110:113]
	v_mfma_f32_16x16x32_bf16 v[106:109], v[170:173], v[178:181], v[106:109]
	v_mfma_f32_16x16x32_bf16 v[98:101], v[156:159], v[186:189], v[98:101]
	v_mfma_f32_16x16x32_bf16 v[94:97], v[170:173], v[186:189], v[94:97]
	v_mfma_f32_16x16x32_bf16 v[86:89], v[156:159], v[194:197], v[86:89]
	v_mfma_f32_16x16x32_bf16 v[78:81], v[170:173], v[194:197], v[78:81]
	v_mfma_f32_16x16x32_bf16 v[70:73], v[156:159], v[202:205], v[70:73]
	v_mfma_f32_16x16x32_bf16 v[66:69], v[170:173], v[202:205], v[66:69]
	v_mfma_f32_16x16x32_bf16 v[110:113], v[166:169], v[182:185], v[110:113]
	v_mfma_f32_16x16x32_bf16 v[106:109], v[174:177], v[182:185], v[106:109]
	v_mfma_f32_16x16x32_bf16 v[98:101], v[166:169], v[190:193], v[98:101]
	v_mfma_f32_16x16x32_bf16 v[94:97], v[174:177], v[190:193], v[94:97]
	v_mfma_f32_16x16x32_bf16 v[86:89], v[166:169], v[198:201], v[86:89]
	v_mfma_f32_16x16x32_bf16 v[78:81], v[174:177], v[198:201], v[78:81]
	v_mfma_f32_16x16x32_bf16 v[70:73], v[166:169], v[206:209], v[70:73]
	v_mfma_f32_16x16x32_bf16 v[66:69], v[174:177], v[206:209], v[66:69]
	s_barrier
	s_add_i32 s20, s69, s40
	s_mov_b32 m0, s20
	ds_read_b128 v[178:181], v164 offset:49152
	ds_read_b128 v[182:185], v164 offset:50176
	ds_read_b128 v[186:189], v164 offset:51200
	ds_read_b128 v[190:193], v164 offset:52224
	ds_read_b128 v[194:197], v164 offset:53248
	ds_read_b128 v[198:201], v164 offset:54272
	ds_read_b128 v[202:205], v164 offset:55296
	ds_read_b128 v[206:209], v164 offset:56320
	global_load_lds_dwordx4 v148, s[98:99]
	s_add_i32 m0, s20, 0x2000
	s_add_u32 s20, s24, 0xb0080
	s_addc_u32 s21, s25, 0
	s_add_i32 s24, s70, s40
	global_load_lds_dwordx4 v146, s[98:99]
	s_mov_b32 m0, s24
	s_nop 0
	global_load_lds_dwordx4 v148, s[20:21]
	s_add_i32 m0, s24, 0x2000
	s_nop 0
	global_load_lds_dwordx4 v146, s[20:21]
	s_mov_b32 m0, s51
	s_nop 0
	global_load_lds_dwordx4 v148, s[100:101]
	s_mov_b32 m0, s52
	s_nop 0
	global_load_lds_dwordx4 v146, s[100:101]
	s_waitcnt vmcnt(8)
	s_waitcnt lgkmcnt(0)
	s_barrier
	s_waitcnt lgkmcnt(0)
	v_mfma_f32_16x16x32_bf16 v[62:65], v[130:133], v[178:181], v[62:65]
	v_mfma_f32_16x16x32_bf16 v[58:61], v[138:141], v[178:181], v[58:61]
	v_mfma_f32_16x16x32_bf16 v[54:57], v[130:133], v[186:189], v[54:57]
	v_mfma_f32_16x16x32_bf16 v[50:53], v[138:141], v[186:189], v[50:53]
	v_mfma_f32_16x16x32_bf16 v[46:49], v[130:133], v[194:197], v[46:49]
	v_mfma_f32_16x16x32_bf16 v[38:41], v[138:141], v[194:197], v[38:41]
	v_mfma_f32_16x16x32_bf16 v[18:21], v[130:133], v[202:205], v[18:21]
	v_mfma_f32_16x16x32_bf16 v[10:13], v[138:141], v[202:205], v[10:13]
	v_mfma_f32_16x16x32_bf16 v[62:65], v[134:137], v[182:185], v[62:65]
	v_mfma_f32_16x16x32_bf16 v[58:61], v[142:145], v[182:185], v[58:61]
	v_mfma_f32_16x16x32_bf16 v[54:57], v[134:137], v[190:193], v[54:57]
	v_mfma_f32_16x16x32_bf16 v[50:53], v[142:145], v[190:193], v[50:53]
	v_mfma_f32_16x16x32_bf16 v[46:49], v[134:137], v[198:201], v[46:49]
	v_mfma_f32_16x16x32_bf16 v[38:41], v[142:145], v[198:201], v[38:41]
	v_mfma_f32_16x16x32_bf16 v[18:21], v[134:137], v[206:209], v[18:21]
	v_mfma_f32_16x16x32_bf16 v[10:13], v[142:145], v[206:209], v[10:13]
	v_mfma_f32_16x16x32_bf16 v[42:45], v[156:159], v[178:181], v[42:45]
	v_mfma_f32_16x16x32_bf16 v[34:37], v[170:173], v[178:181], v[34:37]
	v_mfma_f32_16x16x32_bf16 v[30:33], v[156:159], v[186:189], v[30:33]
	v_mfma_f32_16x16x32_bf16 v[26:29], v[170:173], v[186:189], v[26:29]
	v_mfma_f32_16x16x32_bf16 v[22:25], v[156:159], v[194:197], v[22:25]
	v_mfma_f32_16x16x32_bf16 v[14:17], v[170:173], v[194:197], v[14:17]
	v_mfma_f32_16x16x32_bf16 v[6:9], v[156:159], v[202:205], v[6:9]
	v_mfma_f32_16x16x32_bf16 v[2:5], v[170:173], v[202:205], v[2:5]
	v_mfma_f32_16x16x32_bf16 v[42:45], v[166:169], v[182:185], v[42:45]
	v_mfma_f32_16x16x32_bf16 v[34:37], v[174:177], v[182:185], v[34:37]
	v_mfma_f32_16x16x32_bf16 v[30:33], v[166:169], v[190:193], v[30:33]
	v_mfma_f32_16x16x32_bf16 v[26:29], v[174:177], v[190:193], v[26:29]
	v_mfma_f32_16x16x32_bf16 v[22:25], v[166:169], v[198:201], v[22:25]
	v_mfma_f32_16x16x32_bf16 v[14:17], v[174:177], v[198:201], v[14:17]
	v_mfma_f32_16x16x32_bf16 v[6:9], v[166:169], v[206:209], v[6:9]
	v_mfma_f32_16x16x32_bf16 v[2:5], v[174:177], v[206:209], v[2:5]
	s_barrier
	s_add_i32 s68, s68, 2
	s_add_u32 s66, s66, 0x100
	s_addc_u32 s67, s67, 0
	s_cmp_gt_u32 s68, 5
	s_mov_b64 s[20:21], s[22:23]
	s_cbranch_scc0 .LBB0_1897
	s_and_b64 vcc, exec, s[10:11]
	s_cbranch_vccz .LBB0_1900
	s_barrier

; #define PG8_STAGE(bufoff, gbase, voff) do { _Pragma("unroll") for (int _i = 0; _i < 2; ++_i) \
;         __builtin_amdgcn_global_load_lds((const unsigned*)((const char*)(gbase) + (voff)[_i]), (PG8_LAS unsigned*)(lds + (bufoff) + ldsw + _i * 8192), 16, 0, 0); } while (0)
; #define PG8_LDA(dst, b, h) do { _Pragma("unroll") for (int m = 0; m < 4; ++m) _Pragma("unroll") for (int k = 0; k < 2; ++k) dst[m][k] = *(const PG8_LAS bf16x8*)(lds + PG8_SA(b, h) + aoff + m * 2048 + k * 1024); } while (0)
; #define PG8_LDB(dst, b, h) do { _Pragma("unroll") for (int n = 0; n < 2; ++n) _Pragma("unroll") for (int k = 0; k < 2; ++k) dst[n][k] = *(const PG8_LAS bf16x8*)(lds + PG8_SB(b, h) + boff + n * 2048 + k * 1024); } while (0)
; #define PG8_MMA(ai, bj, At, Bt) do { __builtin_amdgcn_s_setprio(1); _Pragma("unroll") for (int m = 0; m < 4; ++m) _Pragma("unroll") for (int n = 0; n < 2; ++n) _Pragma("unroll") for (int k = 0; k < 2; ++k) \
;         acc[ai][bj][m][n] = __builtin_amdgcn_mfma_f32_16x16x32_bf16(Bt[n][k], At[m][k], acc[ai][bj][m][n], 0, 0, 0); __builtin_amdgcn_s_setprio(0); } while (0)
; #define PG8_WAIT_V(n) asm volatile("s_waitcnt vmcnt(" #n ")" ::: "memory")
; #define PG8_BAR __builtin_amdgcn_s_barrier()
; template <class Epi, class Sched, bool ALIGN_EPI = false, bool SP2 = false>
; __device__ __forceinline__ void gemm_phase(PG8_LAS unsigned char* lds, const Gemm g, const Sched& S, const Epi& E) {
;     ...
;         for (int t = 0; t < nt; t += 2) {
;             const bool last = (t == nt - 2);
;             const char* a1 = cA + (size_t)(t + 1) * kstep;
;             const char* a2 = last ? nA : cA + (size_t)(t + 2) * kstep; const char* b2 = last ? nB : cB + (size_t)(t + 2) * kstep;
;             const char* a3 = a2 + kstep; const char* b3 = b2 + kstep;
;             if (last && has_next) S.a_ready(nxt);
;             if constexpr (SP2) {
;             PG8_LDB(B0, 0, 0); PG8_LDB(B1, 0, 1); PG8_SCHED; PG8_LDA(At, 0, 0); PG8_STAGE(PG8_SA(1, 1), a1 + hstepA, voffA);
;             PG8_WAIT_V(8); PG8_WAIT_L(0); PG8_BAR; PG8_MMA(0, 0, At, B0); PG8_MMA(0, 1, At, B1); PG8_BAR; PG8_SCHED;
;             PG8_LDA(At, 0, 1); PG8_STAGE(PG8_SB(0, 0), b2, voffB); PG8_STAGE(PG8_SB(0, 1), b2 + hstepB, voffB); PG8_STAGE(PG8_SA(0, 0), a2, voffA);
;             PG8_WAIT_V(8); PG8_WAIT_L(0); PG8_BAR; PG8_MMA(1, 0, At, B0); PG8_MMA(1, 1, At, B1); PG8_BAR; PG8_SCHED;
.LBB0_2153:
	ds_read_b128 v[148:151], v156
	ds_read_b128 v[160:163], v156 offset:1024
	ds_read_b128 v[164:167], v156 offset:2048
	ds_read_b128 v[168:171], v156 offset:3072
	ds_read_b128 v[172:175], v157
	ds_read_b128 v[176:179], v157 offset:1024
	ds_read_b128 v[180:183], v157 offset:2048
	ds_read_b128 v[184:187], v157 offset:3072
	s_add_u32 s36, s34, 0xfffc0080
	s_addc_u32 s37, s35, -1
	s_cmp_eq_u32 s59, 12
	s_cselect_b32 s39, s5, s37
	s_cselect_b32 s38, s25, s36
	s_cselect_b32 s37, s23, s58
	s_cselect_b32 s36, s31, s57
	s_add_i32 m0, s44, 0xc000
	ds_read_b128 v[188:191], v158
	ds_read_b128 v[192:195], v158 offset:1024
	ds_read_b128 v[196:199], v158 offset:2048
	ds_read_b128 v[200:203], v158 offset:3072
	ds_read_b128 v[204:207], v158 offset:4096
	ds_read_b128 v[208:211], v158 offset:5120
	ds_read_b128 v[212:215], v158 offset:6144
	ds_read_b128 v[216:219], v158 offset:7168
	global_load_lds_dwordx4 v140, s[34:35]
	s_add_i32 m0, s44, 0xe000
	s_nop 0
	global_load_lds_dwordx4 v142, s[34:35]
	s_waitcnt vmcnt(8)
	s_waitcnt lgkmcnt(0)
	s_barrier
	s_waitcnt lgkmcnt(0)
	v_mfma_f32_16x16x32_bf16 v[126:129], v[148:151], v[188:191], v[126:129]
	v_mfma_f32_16x16x32_bf16 v[122:125], v[164:167], v[188:191], v[122:125]
	v_mfma_f32_16x16x32_bf16 v[110:113], v[148:151], v[196:199], v[110:113]
	v_mfma_f32_16x16x32_bf16 v[106:109], v[164:167], v[196:199], v[106:109]
	v_mfma_f32_16x16x32_bf16 v[94:97], v[148:151], v[204:207], v[94:97]
	v_mfma_f32_16x16x32_bf16 v[90:93], v[164:167], v[204:207], v[90:93]
	v_mfma_f32_16x16x32_bf16 v[78:81], v[148:151], v[212:215], v[78:81]
	v_mfma_f32_16x16x32_bf16 v[74:77], v[164:167], v[212:215], v[74:77]
	v_mfma_f32_16x16x32_bf16 v[126:129], v[160:163], v[192:195], v[126:129]
	v_mfma_f32_16x16x32_bf16 v[122:125], v[168:171], v[192:195], v[122:125]
	v_mfma_f32_16x16x32_bf16 v[110:113], v[160:163], v[200:203], v[110:113]
	v_mfma_f32_16x16x32_bf16 v[106:109], v[168:171], v[200:203], v[106:109]
	v_mfma_f32_16x16x32_bf16 v[94:97], v[160:163], v[208:211], v[94:97]
	v_mfma_f32_16x16x32_bf16 v[90:93], v[168:171], v[208:211], v[90:93]
	v_mfma_f32_16x16x32_bf16 v[78:81], v[160:163], v[216:219], v[78:81]
	v_mfma_f32_16x16x32_bf16 v[74:77], v[168:171], v[216:219], v[74:77]
	v_mfma_f32_16x16x32_bf16 v[118:121], v[172:175], v[188:191], v[118:121]
	v_mfma_f32_16x16x32_bf16 v[114:117], v[180:183], v[188:191], v[114:117]
	v_mfma_f32_16x16x32_bf16 v[102:105], v[172:175], v[196:199], v[102:105]
	v_mfma_f32_16x16x32_bf16 v[98:101], v[180:183], v[196:199], v[98:101]
	v_mfma_f32_16x16x32_bf16 v[86:89], v[172:175], v[204:207], v[86:89]
	v_mfma_f32_16x16x32_bf16 v[82:85], v[180:183], v[204:207], v[82:85]
	v_mfma_f32_16x16x32_bf16 v[70:73], v[172:175], v[212:215], v[70:73]
	v_mfma_f32_16x16x32_bf16 v[66:69], v[180:183], v[212:215], v[66:69]
	v_mfma_f32_16x16x32_bf16 v[118:121], v[176:179], v[192:195], v[118:121]
	v_mfma_f32_16x16x32_bf16 v[114:117], v[184:187], v[192:195], v[114:117]
	v_mfma_f32_16x16x32_bf16 v[102:105], v[176:179], v[200:203], v[102:105]
	v_mfma_f32_16x16x32_bf16 v[98:101], v[184:187], v[200:203], v[98:101]
	v_mfma_f32_16x16x32_bf16 v[86:89], v[176:179], v[208:211], v[86:89]
	v_mfma_f32_16x16x32_bf16 v[82:85], v[184:187], v[208:211], v[82:85]
	v_mfma_f32_16x16x32_bf16 v[70:73], v[176:179], v[216:219], v[70:73]
	v_mfma_f32_16x16x32_bf16 v[66:69], v[184:187], v[216:219], v[66:69]
	s_barrier
	s_add_i32 s60, s54, s43
	s_add_u32 s98, s36, 0x80
	s_addc_u32 s99, s37, 0
	s_mov_b32 m0, s60
	ds_read_b128 v[188:191], v158 offset:16384
	ds_read_b128 v[192:195], v158 offset:17408
	ds_read_b128 v[196:199], v158 offset:18432
	ds_read_b128 v[200:203], v158 offset:19456
	ds_read_b128 v[204:207], v158 offset:20480
	ds_read_b128 v[208:211], v158 offset:21504
	ds_read_b128 v[212:215], v158 offset:22528
	ds_read_b128 v[216:219], v158 offset:23552
	global_load_lds_dwordx4 v132, s[36:37]
	s_add_i32 m0, s60, 0x2000
	s_add_u32 s60, s36, 0x40000
	s_addc_u32 s61, s37, 0
	s_add_i32 s62, s55, s43
	global_load_lds_dwordx4 v136, s[36:37]
	s_mov_b32 m0, s62
	s_nop 0
	global_load_lds_dwordx4 v132, s[60:61]
	s_add_i32 m0, s62, 0x2000
	s_nop 0
	global_load_lds_dwordx4 v136, s[60:61]
	s_add_u32 s100, s38, 0x80
	s_addc_u32 s101, s39, 0
	s_mov_b32 m0, s44
	s_nop 0
	global_load_lds_dwordx4 v130, s[38:39]
	s_mov_b32 m0, s45
	s_nop 0
	global_load_lds_dwordx4 v134, s[38:39]
	s_waitcnt vmcnt(8)
	s_waitcnt lgkmcnt(0)
	s_barrier
	s_waitcnt lgkmcnt(0)
	v_mfma_f32_16x16x32_bf16 v[62:65], v[148:151], v[188:191], v[62:65]
	v_mfma_f32_16x16x32_bf16 v[58:61], v[164:167], v[188:191], v[58:61]
	v_mfma_f32_16x16x32_bf16 v[46:49], v[148:151], v[196:199], v[46:49]
	v_mfma_f32_16x16x32_bf16 v[42:45], v[164:167], v[196:199], v[42:45]
	v_mfma_f32_16x16x32_bf16 v[30:33], v[148:151], v[204:207], v[30:33]
	v_mfma_f32_16x16x32_bf16 v[26:29], v[164:167], v[204:207], v[26:29]
	v_mfma_f32_16x16x32_bf16 v[14:17], v[148:151], v[212:215], v[14:17]
	v_mfma_f32_16x16x32_bf16 v[10:13], v[164:167], v[212:215], v[10:13]
	v_mfma_f32_16x16x32_bf16 v[62:65], v[160:163], v[192:195], v[62:65]
	v_mfma_f32_16x16x32_bf16 v[58:61], v[168:171], v[192:195], v[58:61]
	v_mfma_f32_16x16x32_bf16 v[46:49], v[160:163], v[200:203], v[46:49]
	v_mfma_f32_16x16x32_bf16 v[42:45], v[168:171], v[200:203], v[42:45]
	v_mfma_f32_16x16x32_bf16 v[30:33], v[160:163], v[208:211], v[30:33]
	v_mfma_f32_16x16x32_bf16 v[26:29], v[168:171], v[208:211], v[26:29]
	v_mfma_f32_16x16x32_bf16 v[14:17], v[160:163], v[216:219], v[14:17]
	v_mfma_f32_16x16x32_bf16 v[10:13], v[168:171], v[216:219], v[10:13]
	v_mfma_f32_16x16x32_bf16 v[54:57], v[172:175], v[188:191], v[54:57]
	v_mfma_f32_16x16x32_bf16 v[50:53], v[180:183], v[188:191], v[50:53]
	v_mfma_f32_16x16x32_bf16 v[38:41], v[172:175], v[196:199], v[38:41]
	v_mfma_f32_16x16x32_bf16 v[34:37], v[180:183], v[196:199], v[34:37]
	v_mfma_f32_16x16x32_bf16 v[22:25], v[172:175], v[204:207], v[22:25]
	v_mfma_f32_16x16x32_bf16 v[18:21], v[180:183], v[204:207], v[18:21]
	v_mfma_f32_16x16x32_bf16 v[6:9], v[172:175], v[212:215], v[6:9]
	v_mfma_f32_16x16x32_bf16 v[2:5], v[180:183], v[212:215], v[2:5]
	v_mfma_f32_16x16x32_bf16 v[54:57], v[176:179], v[192:195], v[54:57]
	v_mfma_f32_16x16x32_bf16 v[50:53], v[184:187], v[192:195], v[50:53]
	v_mfma_f32_16x16x32_bf16 v[38:41], v[176:179], v[200:203], v[38:41]
	v_mfma_f32_16x16x32_bf16 v[34:37], v[184:187], v[200:203], v[34:37]
	v_mfma_f32_16x16x32_bf16 v[22:25], v[176:179], v[208:211], v[22:25]
	v_mfma_f32_16x16x32_bf16 v[18:21], v[184:187], v[208:211], v[18:21]
	v_mfma_f32_16x16x32_bf16 v[6:9], v[176:179], v[216:219], v[6:9]
	v_mfma_f32_16x16x32_bf16 v[2:5], v[184:187], v[216:219], v[2:5]
	s_barrier
; #define PG8_STAGE(bufoff, gbase, voff) do { _Pragma("unroll") for (int _i = 0; _i < 2; ++_i) \
;         __builtin_amdgcn_global_load_lds((const unsigned*)((const char*)(gbase) + (voff)[_i]), (PG8_LAS unsigned*)(lds + (bufoff) + ldsw + _i * 8192), 16, 0, 0); } while (0)
; #define PG8_LDA(dst, b, h) do { _Pragma("unroll") for (int m = 0; m < 4; ++m) _Pragma("unroll") for (int k = 0; k < 2; ++k) dst[m][k] = *(const PG8_LAS bf16x8*)(lds + PG8_SA(b, h) + aoff + m * 2048 + k * 1024); } while (0)
; #define PG8_LDB(dst, b, h) do { _Pragma("unroll") for (int n = 0; n < 2; ++n) _Pragma("unroll") for (int k = 0; k < 2; ++k) dst[n][k] = *(const PG8_LAS bf16x8*)(lds + PG8_SB(b, h) + boff + n * 2048 + k * 1024); } while (0)
; #define PG8_MMA(ai, bj, At, Bt) do { __builtin_amdgcn_s_setprio(1); _Pragma("unroll") for (int m = 0; m < 4; ++m) _Pragma("unroll") for (int n = 0; n < 2; ++n) _Pragma("unroll") for (int k = 0; k < 2; ++k) \
;         acc[ai][bj][m][n] = __builtin_amdgcn_mfma_f32_16x16x32_bf16(Bt[n][k], At[m][k], acc[ai][bj][m][n], 0, 0, 0); __builtin_amdgcn_s_setprio(0); } while (0)
; #define PG8_WAIT_V(n) asm volatile("s_waitcnt vmcnt(" #n ")" ::: "memory")
; #define PG8_WAIT_L(n) asm volatile("s_waitcnt lgkmcnt(" #n ")" ::: "memory")
; #define PG8_BAR __builtin_amdgcn_s_barrier()
; #define PG8_SCHED __builtin_amdgcn_sched_barrier(0)
; template <class Epi, class Sched, bool ALIGN_EPI = false, bool SP2 = false>
; __device__ __forceinline__ void gemm_phase(PG8_LAS unsigned char* lds, const Gemm g, const Sched& S, const Epi& E) {
;     ...
;         for (int t = 0; t < nt; t += 2) {
;             const bool last = (t == nt - 2);
;     ...
;             PG8_LDB(B0, 1, 0); PG8_LDB(B1, 1, 1); PG8_SCHED; PG8_LDA(At, 1, 0); PG8_STAGE(PG8_SA(0, 1), a2 + hstepA, voffA);
;             PG8_WAIT_V(8); PG8_WAIT_L(0); PG8_BAR; PG8_MMA(0, 0, At, B0); PG8_MMA(0, 1, At, B1); PG8_BAR; PG8_SCHED;
;             PG8_LDA(At, 1, 1); PG8_STAGE(PG8_SB(1, 0), b3, voffB); PG8_STAGE(PG8_SB(1, 1), b3 + hstepB, voffB); PG8_STAGE(PG8_SA(1, 0), a3, voffA);
;             PG8_WAIT_V(8); PG8_WAIT_L(0); PG8_BAR; PG8_MMA(1, 0, At, B0); PG8_MMA(1, 1, At, B1); PG8_BAR; PG8_SCHED;
	s_add_i32 s60, 0, 0x18000
	v_add_u32_e32 v138, s60, v154
	s_add_i32 s61, 0, 0x1c000
	ds_read_b128 v[148:151], v138
	ds_read_b128 v[160:163], v138 offset:1024
	ds_read_b128 v[164:167], v138 offset:2048
	ds_read_b128 v[168:171], v138 offset:3072
	v_add_u32_e32 v138, s61, v154
	ds_read_b128 v[172:175], v138
	ds_read_b128 v[176:179], v138 offset:1024
	ds_read_b128 v[180:183], v138 offset:2048
	ds_read_b128 v[184:187], v138 offset:3072
	s_add_u32 s38, s38, 0x40000
	s_addc_u32 s39, s39, 0
	s_mov_b32 m0, s46
	ds_read_b128 v[188:191], v158 offset:32768
	ds_read_b128 v[192:195], v158 offset:33792
	ds_read_b128 v[196:199], v158 offset:34816
	ds_read_b128 v[200:203], v158 offset:35840
	ds_read_b128 v[204:207], v158 offset:36864
	ds_read_b128 v[208:211], v158 offset:37888
	ds_read_b128 v[212:215], v158 offset:38912
	ds_read_b128 v[216:219], v158 offset:39936
	global_load_lds_dwordx4 v130, s[38:39]
	s_mov_b32 m0, s47
	s_nop 0
	global_load_lds_dwordx4 v134, s[38:39]
	s_waitcnt vmcnt(8)
	s_waitcnt lgkmcnt(0)
	s_barrier
	s_waitcnt lgkmcnt(0)
	v_mfma_f32_16x16x32_bf16 v[126:129], v[148:151], v[188:191], v[126:129]
	v_mfma_f32_16x16x32_bf16 v[122:125], v[164:167], v[188:191], v[122:125]
	v_mfma_f32_16x16x32_bf16 v[110:113], v[148:151], v[196:199], v[110:113]
	v_mfma_f32_16x16x32_bf16 v[106:109], v[164:167], v[196:199], v[106:109]
	v_mfma_f32_16x16x32_bf16 v[94:97], v[148:151], v[204:207], v[94:97]
	v_mfma_f32_16x16x32_bf16 v[90:93], v[164:167], v[204:207], v[90:93]
	v_mfma_f32_16x16x32_bf16 v[78:81], v[148:151], v[212:215], v[78:81]
	v_mfma_f32_16x16x32_bf16 v[74:77], v[164:167], v[212:215], v[74:77]
	v_mfma_f32_16x16x32_bf16 v[126:129], v[160:163], v[192:195], v[126:129]
	v_mfma_f32_16x16x32_bf16 v[122:125], v[168:171], v[192:195], v[122:125]
	v_mfma_f32_16x16x32_bf16 v[110:113], v[160:163], v[200:203], v[110:113]
	v_mfma_f32_16x16x32_bf16 v[106:109], v[168:171], v[200:203], v[106:109]
	v_mfma_f32_16x16x32_bf16 v[94:97], v[160:163], v[208:211], v[94:97]
	v_mfma_f32_16x16x32_bf16 v[90:93], v[168:171], v[208:211], v[90:93]
	v_mfma_f32_16x16x32_bf16 v[78:81], v[160:163], v[216:219], v[78:81]
	v_mfma_f32_16x16x32_bf16 v[74:77], v[168:171], v[216:219], v[74:77]
	v_mfma_f32_16x16x32_bf16 v[118:121], v[172:175], v[188:191], v[118:121]
	v_mfma_f32_16x16x32_bf16 v[114:117], v[180:183], v[188:191], v[114:117]
	v_mfma_f32_16x16x32_bf16 v[102:105], v[172:175], v[196:199], v[102:105]
	v_mfma_f32_16x16x32_bf16 v[98:101], v[180:183], v[196:199], v[98:101]
	v_mfma_f32_16x16x32_bf16 v[86:89], v[172:175], v[204:207], v[86:89]
	v_mfma_f32_16x16x32_bf16 v[82:85], v[180:183], v[204:207], v[82:85]
	v_mfma_f32_16x16x32_bf16 v[70:73], v[172:175], v[212:215], v[70:73]
	v_mfma_f32_16x16x32_bf16 v[66:69], v[180:183], v[212:215], v[66:69]
	v_mfma_f32_16x16x32_bf16 v[118:121], v[176:179], v[192:195], v[118:121]
	v_mfma_f32_16x16x32_bf16 v[114:117], v[184:187], v[192:195], v[114:117]
	v_mfma_f32_16x16x32_bf16 v[102:105], v[176:179], v[200:203], v[102:105]
	v_mfma_f32_16x16x32_bf16 v[98:101], v[184:187], v[200:203], v[98:101]
	v_mfma_f32_16x16x32_bf16 v[86:89], v[176:179], v[208:211], v[86:89]
	v_mfma_f32_16x16x32_bf16 v[82:85], v[184:187], v[208:211], v[82:85]
	v_mfma_f32_16x16x32_bf16 v[70:73], v[176:179], v[216:219], v[70:73]
	v_mfma_f32_16x16x32_bf16 v[66:69], v[184:187], v[216:219], v[66:69]
	s_barrier
	s_add_i32 s38, s60, s43
	s_mov_b32 m0, s38
	ds_read_b128 v[188:191], v158 offset:49152
	ds_read_b128 v[192:195], v158 offset:50176
	ds_read_b128 v[196:199], v158 offset:51200
	ds_read_b128 v[200:203], v158 offset:52224
	ds_read_b128 v[204:207], v158 offset:53248
	ds_read_b128 v[208:211], v158 offset:54272
	ds_read_b128 v[212:215], v158 offset:55296
	ds_read_b128 v[216:219], v158 offset:56320
	global_load_lds_dwordx4 v132, s[98:99]
	s_add_i32 m0, s38, 0x2000
	s_add_u32 s36, s36, 0x40080
	s_addc_u32 s37, s37, 0
	s_add_i32 s38, s61, s43
	global_load_lds_dwordx4 v136, s[98:99]
	s_mov_b32 m0, s38
	s_nop 0
	global_load_lds_dwordx4 v132, s[36:37]
	s_add_i32 m0, s38, 0x2000
	s_nop 0
	global_load_lds_dwordx4 v136, s[36:37]
	s_mov_b32 m0, s49
	s_nop 0
	global_load_lds_dwordx4 v130, s[100:101]
	s_mov_b32 m0, s50
	s_nop 0
	global_load_lds_dwordx4 v134, s[100:101]
	s_waitcnt vmcnt(8)
	s_waitcnt lgkmcnt(0)
	s_barrier
	s_waitcnt lgkmcnt(0)
	v_mfma_f32_16x16x32_bf16 v[62:65], v[148:151], v[188:191], v[62:65]
	v_mfma_f32_16x16x32_bf16 v[58:61], v[164:167], v[188:191], v[58:61]
	v_mfma_f32_16x16x32_bf16 v[46:49], v[148:151], v[196:199], v[46:49]
	v_mfma_f32_16x16x32_bf16 v[42:45], v[164:167], v[196:199], v[42:45]
	v_mfma_f32_16x16x32_bf16 v[30:33], v[148:151], v[204:207], v[30:33]
	v_mfma_f32_16x16x32_bf16 v[26:29], v[164:167], v[204:207], v[26:29]
	v_mfma_f32_16x16x32_bf16 v[14:17], v[148:151], v[212:215], v[14:17]
	v_mfma_f32_16x16x32_bf16 v[10:13], v[164:167], v[212:215], v[10:13]
	v_mfma_f32_16x16x32_bf16 v[62:65], v[160:163], v[192:195], v[62:65]
	v_mfma_f32_16x16x32_bf16 v[58:61], v[168:171], v[192:195], v[58:61]
	v_mfma_f32_16x16x32_bf16 v[46:49], v[160:163], v[200:203], v[46:49]
	v_mfma_f32_16x16x32_bf16 v[42:45], v[168:171], v[200:203], v[42:45]
	v_mfma_f32_16x16x32_bf16 v[30:33], v[160:163], v[208:211], v[30:33]
	v_mfma_f32_16x16x32_bf16 v[26:29], v[168:171], v[208:211], v[26:29]
	v_mfma_f32_16x16x32_bf16 v[14:17], v[160:163], v[216:219], v[14:17]
	v_mfma_f32_16x16x32_bf16 v[10:13], v[168:171], v[216:219], v[10:13]
	v_mfma_f32_16x16x32_bf16 v[54:57], v[172:175], v[188:191], v[54:57]
	v_mfma_f32_16x16x32_bf16 v[50:53], v[180:183], v[188:191], v[50:53]
	v_mfma_f32_16x16x32_bf16 v[38:41], v[172:175], v[196:199], v[38:41]
	v_mfma_f32_16x16x32_bf16 v[34:37], v[180:183], v[196:199], v[34:37]
	v_mfma_f32_16x16x32_bf16 v[22:25], v[172:175], v[204:207], v[22:25]
	v_mfma_f32_16x16x32_bf16 v[18:21], v[180:183], v[204:207], v[18:21]
	v_mfma_f32_16x16x32_bf16 v[6:9], v[172:175], v[212:215], v[6:9]
	v_mfma_f32_16x16x32_bf16 v[2:5], v[180:183], v[212:215], v[2:5]
	v_mfma_f32_16x16x32_bf16 v[54:57], v[176:179], v[192:195], v[54:57]
	v_mfma_f32_16x16x32_bf16 v[50:53], v[184:187], v[192:195], v[50:53]
	v_mfma_f32_16x16x32_bf16 v[38:41], v[176:179], v[200:203], v[38:41]
	v_mfma_f32_16x16x32_bf16 v[34:37], v[184:187], v[200:203], v[34:37]
	v_mfma_f32_16x16x32_bf16 v[22:25], v[176:179], v[208:211], v[22:25]
	v_mfma_f32_16x16x32_bf16 v[18:21], v[184:187], v[208:211], v[18:21]
	v_mfma_f32_16x16x32_bf16 v[6:9], v[176:179], v[216:219], v[6:9]
	v_mfma_f32_16x16x32_bf16 v[2:5], v[184:187], v[216:219], v[2:5]
	s_barrier
	s_add_i32 s59, s59, 2
	s_add_u32 s34, s34, 0x100
	s_addc_u32 s35, s35, 0
	s_add_u32 s57, s57, 0x100
	s_addc_u32 s58, s58, 0
	s_cmp_gt_u32 s59, 13
	s_cbranch_scc0 .LBB0_2153
	s_and_b64 vcc, exec, s[14:15]
	s_cbranch_vccz .LBB0_2156
	s_barrier

; #define PG8_STAGE(bufoff, gbase, voff) do { _Pragma("unroll") for (int _i = 0; _i < 2; ++_i) \
;         __builtin_amdgcn_global_load_lds((const unsigned*)((const char*)(gbase) + (voff)[_i]), (PG8_LAS unsigned*)(lds + (bufoff) + ldsw + _i * 8192), 16, 0, 0); } while (0)
; #define PG8_LDA(dst, b, h) do { _Pragma("unroll") for (int m = 0; m < 4; ++m) _Pragma("unroll") for (int k = 0; k < 2; ++k) dst[m][k] = *(const PG8_LAS bf16x8*)(lds + PG8_SA(b, h) + aoff + m * 2048 + k * 1024); } while (0)
; #define PG8_LDB(dst, b, h) do { _Pragma("unroll") for (int n = 0; n < 2; ++n) _Pragma("unroll") for (int k = 0; k < 2; ++k) dst[n][k] = *(const PG8_LAS bf16x8*)(lds + PG8_SB(b, h) + boff + n * 2048 + k * 1024); } while (0)
; #define PG8_MMA(ai, bj, At, Bt) do { __builtin_amdgcn_s_setprio(1); _Pragma("unroll") for (int m = 0; m < 4; ++m) _Pragma("unroll") for (int n = 0; n < 2; ++n) _Pragma("unroll") for (int k = 0; k < 2; ++k) \
;         acc[ai][bj][m][n] = __builtin_amdgcn_mfma_f32_16x16x32_bf16(Bt[n][k], At[m][k], acc[ai][bj][m][n], 0, 0, 0); __builtin_amdgcn_s_setprio(0); } while (0)
; #define PG8_WAIT_V(n) asm volatile("s_waitcnt vmcnt(" #n ")" ::: "memory")
; #define PG8_BAR __builtin_amdgcn_s_barrier()
; template <class Epi, class Sched, bool ALIGN_EPI = false, bool SP2 = false>
; __device__ __forceinline__ void gemm_phase(PG8_LAS unsigned char* lds, const Gemm g, const Sched& S, const Epi& E) {
;     ...
;         for (int t = 0; t < nt; t += 2) {
;             const bool last = (t == nt - 2);
;             const char* a1 = cA + (size_t)(t + 1) * kstep;
;             const char* a2 = last ? nA : cA + (size_t)(t + 2) * kstep; const char* b2 = last ? nB : cB + (size_t)(t + 2) * kstep;
;             const char* a3 = a2 + kstep; const char* b3 = b2 + kstep;
;             if (last && has_next) S.a_ready(nxt);
;             if constexpr (SP2) {
;             PG8_LDB(B0, 0, 0); PG8_LDB(B1, 0, 1); PG8_SCHED; PG8_LDA(At, 0, 0); PG8_STAGE(PG8_SA(1, 1), a1 + hstepA, voffA);
;             PG8_WAIT_V(8); PG8_WAIT_L(0); PG8_BAR; PG8_MMA(0, 0, At, B0); PG8_MMA(0, 1, At, B1); PG8_BAR; PG8_SCHED;
;             PG8_LDA(At, 0, 1); PG8_STAGE(PG8_SB(0, 0), b2, voffB); PG8_STAGE(PG8_SB(0, 1), b2 + hstepB, voffB); PG8_STAGE(PG8_SA(0, 0), a2, voffA);
;             PG8_WAIT_V(8); PG8_WAIT_L(0); PG8_BAR; PG8_MMA(1, 0, At, B0); PG8_MMA(1, 1, At, B1); PG8_BAR; PG8_SCHED;
.LBB0_2500:
	v_add_u32_e32 v24, s53, v22
	ds_read_b128 v[34:37], v24
	ds_read_b128 v[38:41], v24 offset:1024
	ds_read_b128 v[42:45], v24 offset:2048
	ds_read_b128 v[46:49], v24 offset:3072
	v_add_u32_e32 v24, s54, v22
	s_add_u32 s30, s0, s28
	ds_read_b128 v[50:53], v24
	ds_read_b128 v[54:57], v24 offset:1024
	ds_read_b128 v[66:69], v24 offset:2048
	ds_read_b128 v[70:73], v24 offset:3072
	s_addc_u32 s31, s1, s29
	s_add_u32 s30, s30, 0x100
	s_addc_u32 s31, s31, 0
	s_add_u32 s61, s56, s28
	s_addc_u32 s62, s57, s29
	s_cmpk_eq_i32 s28, 0x700
	s_cselect_b32 s35, s23, s31
	s_cselect_b32 s34, s58, s30
	s_cselect_b32 s31, s21, s62
	s_cselect_b32 s30, s59, s61
	v_lshl_add_u64 v[24:25], v[18:19], 0, s[28:29]
	s_add_i32 m0, s45, 0xc000
	ds_read_b128 v[162:165], v23
	ds_read_b128 v[166:169], v23 offset:1024
	ds_read_b128 v[194:197], v23 offset:2048
	ds_read_b128 v[198:201], v23 offset:3072
	ds_read_b128 v[202:205], v23 offset:4096
	ds_read_b128 v[206:209], v23 offset:5120
	ds_read_b128 v[210:213], v23 offset:6144
	ds_read_b128 v[216:219], v23 offset:7168
	global_load_lds_dwordx4 v[24:25], off
	v_lshl_add_u64 v[24:25], v[20:21], 0, s[28:29]
	s_add_i32 m0, s45, 0xe000
	s_nop 0
	global_load_lds_dwordx4 v[24:25], off
	s_waitcnt vmcnt(8)
	s_waitcnt lgkmcnt(0)
	s_barrier
	s_waitcnt lgkmcnt(0)
	v_mfma_f32_16x16x32_bf16 v[170:173], v[34:37], v[162:165], v[170:173]
	v_mfma_f32_16x16x32_bf16 v[174:177], v[42:45], v[162:165], v[174:177]
	v_mfma_f32_16x16x32_bf16 v[178:181], v[34:37], v[194:197], v[178:181]
	v_mfma_f32_16x16x32_bf16 v[182:185], v[42:45], v[194:197], v[182:185]
	v_mfma_f32_16x16x32_bf16 v[186:189], v[34:37], v[202:205], v[186:189]
	v_mfma_f32_16x16x32_bf16 v[190:193], v[42:45], v[202:205], v[190:193]
	v_mfma_f32_16x16x32_bf16 v[158:161], v[34:37], v[210:213], v[158:161]
	v_mfma_f32_16x16x32_bf16 v[154:157], v[42:45], v[210:213], v[154:157]
	v_mfma_f32_16x16x32_bf16 v[170:173], v[38:41], v[166:169], v[170:173]
	v_mfma_f32_16x16x32_bf16 v[174:177], v[46:49], v[166:169], v[174:177]
	v_mfma_f32_16x16x32_bf16 v[178:181], v[38:41], v[198:201], v[178:181]
	v_mfma_f32_16x16x32_bf16 v[182:185], v[46:49], v[198:201], v[182:185]
	v_mfma_f32_16x16x32_bf16 v[186:189], v[38:41], v[206:209], v[186:189]
	v_mfma_f32_16x16x32_bf16 v[190:193], v[46:49], v[206:209], v[190:193]
	v_mfma_f32_16x16x32_bf16 v[158:161], v[38:41], v[216:219], v[158:161]
	v_mfma_f32_16x16x32_bf16 v[154:157], v[46:49], v[216:219], v[154:157]
	v_mfma_f32_16x16x32_bf16 v[62:65], v[50:53], v[162:165], v[62:65]
	v_mfma_f32_16x16x32_bf16 v[58:61], v[66:69], v[162:165], v[58:61]
	v_mfma_f32_16x16x32_bf16 v[74:77], v[50:53], v[194:197], v[74:77]
	v_mfma_f32_16x16x32_bf16 v[78:81], v[66:69], v[194:197], v[78:81]
	v_mfma_f32_16x16x32_bf16 v[94:97], v[50:53], v[202:205], v[94:97]
	v_mfma_f32_16x16x32_bf16 v[98:101], v[66:69], v[202:205], v[98:101]
	v_mfma_f32_16x16x32_bf16 v[106:109], v[50:53], v[210:213], v[106:109]
	v_mfma_f32_16x16x32_bf16 v[110:113], v[66:69], v[210:213], v[110:113]
	v_mfma_f32_16x16x32_bf16 v[62:65], v[54:57], v[166:169], v[62:65]
	v_mfma_f32_16x16x32_bf16 v[58:61], v[70:73], v[166:169], v[58:61]
	v_mfma_f32_16x16x32_bf16 v[74:77], v[54:57], v[198:201], v[74:77]
	v_mfma_f32_16x16x32_bf16 v[78:81], v[70:73], v[198:201], v[78:81]
	v_mfma_f32_16x16x32_bf16 v[94:97], v[54:57], v[206:209], v[94:97]
	v_mfma_f32_16x16x32_bf16 v[98:101], v[70:73], v[206:209], v[98:101]
	v_mfma_f32_16x16x32_bf16 v[106:109], v[54:57], v[216:219], v[106:109]
	v_mfma_f32_16x16x32_bf16 v[110:113], v[70:73], v[216:219], v[110:113]
	s_barrier
	s_add_i32 s61, s53, s44
	s_add_u32 s98, s30, 0x80
	s_addc_u32 s99, s31, 0
	s_mov_b32 m0, s61
	ds_read_b128 v[162:165], v23 offset:16384
	ds_read_b128 v[166:169], v23 offset:17408
	ds_read_b128 v[194:197], v23 offset:18432
	ds_read_b128 v[198:201], v23 offset:19456
	ds_read_b128 v[202:205], v23 offset:20480
	ds_read_b128 v[206:209], v23 offset:21504
	ds_read_b128 v[210:213], v23 offset:22528
	ds_read_b128 v[216:219], v23 offset:23552
	global_load_lds_dwordx4 v4, s[30:31]
	s_add_i32 m0, s61, 0x2000
	s_add_u32 s62, s30, 0x40000
	s_addc_u32 s63, s31, 0
	s_add_i32 s61, s54, s44
	global_load_lds_dwordx4 v8, s[30:31]
	s_mov_b32 m0, s61
	s_add_u32 s100, s34, 0x80
	s_addc_u32 s101, s35, 0
	global_load_lds_dwordx4 v4, s[62:63]
	s_add_i32 m0, s61, 0x2000
	s_nop 0
	global_load_lds_dwordx4 v8, s[62:63]
	s_mov_b32 m0, s45
	s_nop 0
	global_load_lds_dwordx4 v2, s[34:35]
	s_mov_b32 m0, s46
	s_nop 0
	global_load_lds_dwordx4 v6, s[34:35]
	s_waitcnt vmcnt(8)
	s_waitcnt lgkmcnt(0)
	s_barrier
; #define PG8_STAGE(bufoff, gbase, voff) do { _Pragma("unroll") for (int _i = 0; _i < 2; ++_i) \
;         __builtin_amdgcn_global_load_lds((const unsigned*)((const char*)(gbase) + (voff)[_i]), (PG8_LAS unsigned*)(lds + (bufoff) + ldsw + _i * 8192), 16, 0, 0); } while (0)
; #define PG8_LDA(dst, b, h) do { _Pragma("unroll") for (int m = 0; m < 4; ++m) _Pragma("unroll") for (int k = 0; k < 2; ++k) dst[m][k] = *(const PG8_LAS bf16x8*)(lds + PG8_SA(b, h) + aoff + m * 2048 + k * 1024); } while (0)
; #define PG8_LDB(dst, b, h) do { _Pragma("unroll") for (int n = 0; n < 2; ++n) _Pragma("unroll") for (int k = 0; k < 2; ++k) dst[n][k] = *(const PG8_LAS bf16x8*)(lds + PG8_SB(b, h) + boff + n * 2048 + k * 1024); } while (0)
; #define PG8_MMA(ai, bj, At, Bt) do { __builtin_amdgcn_s_setprio(1); _Pragma("unroll") for (int m = 0; m < 4; ++m) _Pragma("unroll") for (int n = 0; n < 2; ++n) _Pragma("unroll") for (int k = 0; k < 2; ++k) \
;         acc[ai][bj][m][n] = __builtin_amdgcn_mfma_f32_16x16x32_bf16(Bt[n][k], At[m][k], acc[ai][bj][m][n], 0, 0, 0); __builtin_amdgcn_s_setprio(0); } while (0)
; #define PG8_WAIT_V(n) asm volatile("s_waitcnt vmcnt(" #n ")" ::: "memory")
; #define PG8_WAIT_L(n) asm volatile("s_waitcnt lgkmcnt(" #n ")" ::: "memory")
; #define PG8_BAR __builtin_amdgcn_s_barrier()
; #define PG8_SCHED __builtin_amdgcn_sched_barrier(0)
; template <class Epi, class Sched, bool ALIGN_EPI = false, bool SP2 = false>
; __device__ __forceinline__ void gemm_phase(PG8_LAS unsigned char* lds, const Gemm g, const Sched& S, const Epi& E) {
;     ...
;             PG8_WAIT_V(8); PG8_WAIT_L(0); PG8_BAR; PG8_MMA(1, 0, At, B0); PG8_MMA(1, 1, At, B1); PG8_BAR; PG8_SCHED;
;             PG8_LDB(B0, 1, 0); PG8_LDB(B1, 1, 1); PG8_SCHED; PG8_LDA(At, 1, 0); PG8_STAGE(PG8_SA(0, 1), a2 + hstepA, voffA);
;             PG8_WAIT_V(8); PG8_WAIT_L(0); PG8_BAR; PG8_MMA(0, 0, At, B0); PG8_MMA(0, 1, At, B1); PG8_BAR; PG8_SCHED;
	s_waitcnt lgkmcnt(0)
	v_mfma_f32_16x16x32_bf16 v[150:153], v[34:37], v[162:165], v[150:153]
	v_mfma_f32_16x16x32_bf16 v[146:149], v[42:45], v[162:165], v[146:149]
	v_mfma_f32_16x16x32_bf16 v[142:145], v[34:37], v[194:197], v[142:145]
	v_mfma_f32_16x16x32_bf16 v[138:141], v[42:45], v[194:197], v[138:141]
	v_mfma_f32_16x16x32_bf16 v[134:137], v[34:37], v[202:205], v[134:137]
	v_mfma_f32_16x16x32_bf16 v[130:133], v[42:45], v[202:205], v[130:133]
	v_mfma_f32_16x16x32_bf16 v[34:37], v[34:37], v[210:213], v[90:93]
	v_mfma_f32_16x16x32_bf16 v[150:153], v[38:41], v[166:169], v[150:153]
	v_mfma_f32_16x16x32_bf16 v[146:149], v[46:49], v[166:169], v[146:149]
	v_mfma_f32_16x16x32_bf16 v[142:145], v[38:41], v[198:201], v[142:145]
	v_mfma_f32_16x16x32_bf16 v[138:141], v[46:49], v[198:201], v[138:141]
	v_mfma_f32_16x16x32_bf16 v[134:137], v[38:41], v[206:209], v[134:137]
	v_mfma_f32_16x16x32_bf16 v[130:133], v[46:49], v[206:209], v[130:133]
	v_mfma_f32_16x16x32_bf16 v[34:37], v[38:41], v[216:219], v[34:37]
	v_mfma_f32_16x16x32_bf16 v[38:41], v[42:45], v[210:213], v[82:85]
	v_mfma_f32_16x16x32_bf16 v[38:41], v[46:49], v[216:219], v[38:41]
	v_mfma_f32_16x16x32_bf16 v[82:85], v[50:53], v[194:197], v[122:125]
	v_mfma_f32_16x16x32_bf16 v[122:125], v[54:57], v[198:201], v[82:85]
	v_mfma_f32_16x16x32_bf16 v[82:85], v[66:69], v[194:197], v[126:129]
	v_mfma_f32_16x16x32_bf16 v[126:129], v[70:73], v[198:201], v[82:85]
	v_mfma_f32_16x16x32_bf16 v[82:85], v[50:53], v[202:205], v[102:105]
	v_mfma_f32_16x16x32_bf16 v[102:105], v[54:57], v[206:209], v[82:85]
	v_mfma_f32_16x16x32_bf16 v[82:85], v[66:69], v[202:205], v[86:89]
	v_mfma_f32_16x16x32_bf16 v[30:33], v[50:53], v[210:213], v[30:33]
	v_mfma_f32_16x16x32_bf16 v[24:27], v[66:69], v[210:213], v[26:29]
	v_mfma_f32_16x16x32_bf16 v[42:45], v[50:53], v[162:165], v[114:117]
	v_mfma_f32_16x16x32_bf16 v[46:49], v[66:69], v[162:165], v[118:121]
	v_mfma_f32_16x16x32_bf16 v[86:89], v[70:73], v[206:209], v[82:85]
	v_mfma_f32_16x16x32_bf16 v[30:33], v[54:57], v[216:219], v[30:33]
	v_mfma_f32_16x16x32_bf16 v[24:27], v[70:73], v[216:219], v[24:27]
	v_mfma_f32_16x16x32_bf16 v[42:45], v[54:57], v[166:169], v[42:45]
	v_mfma_f32_16x16x32_bf16 v[46:49], v[70:73], v[166:169], v[46:49]
	s_barrier
	s_add_i32 s61, 0, 0x18000
	v_add_u32_e32 v28, s61, v22
	s_add_i32 s62, 0, 0x1c000
	ds_read_b128 v[50:53], v28
	ds_read_b128 v[54:57], v28 offset:1024
	ds_read_b128 v[66:69], v28 offset:2048
	ds_read_b128 v[70:73], v28 offset:3072
	v_add_u32_e32 v28, s62, v22
	ds_read_b128 v[162:165], v28
	ds_read_b128 v[166:169], v28 offset:1024
	ds_read_b128 v[194:197], v28 offset:2048
	ds_read_b128 v[198:201], v28 offset:3072
	s_add_u32 s34, s34, 0x40000
	s_addc_u32 s35, s35, 0
	s_mov_b32 m0, s48
	ds_read_b128 v[82:85], v23 offset:32768
	ds_read_b128 v[90:93], v23 offset:33792
	ds_read_b128 v[114:117], v23 offset:34816
	ds_read_b128 v[118:121], v23 offset:35840
	ds_read_b128 v[202:205], v23 offset:36864
	ds_read_b128 v[206:209], v23 offset:37888
	ds_read_b128 v[210:213], v23 offset:38912
	ds_read_b128 v[216:219], v23 offset:39936
	global_load_lds_dwordx4 v2, s[34:35]
	s_mov_b32 m0, s49
	s_nop 0
	global_load_lds_dwordx4 v6, s[34:35]
	s_waitcnt vmcnt(8)
	s_waitcnt lgkmcnt(0)
	s_barrier
	s_waitcnt lgkmcnt(0)
	v_mfma_f32_16x16x32_bf16 v[170:173], v[50:53], v[82:85], v[170:173]
	v_mfma_f32_16x16x32_bf16 v[174:177], v[66:69], v[82:85], v[174:177]
	v_mfma_f32_16x16x32_bf16 v[178:181], v[50:53], v[114:117], v[178:181]
	v_mfma_f32_16x16x32_bf16 v[182:185], v[66:69], v[114:117], v[182:185]
	v_mfma_f32_16x16x32_bf16 v[186:189], v[50:53], v[202:205], v[186:189]
	v_mfma_f32_16x16x32_bf16 v[190:193], v[66:69], v[202:205], v[190:193]
	v_mfma_f32_16x16x32_bf16 v[158:161], v[50:53], v[210:213], v[158:161]
	v_mfma_f32_16x16x32_bf16 v[154:157], v[66:69], v[210:213], v[154:157]
	v_mfma_f32_16x16x32_bf16 v[170:173], v[54:57], v[90:93], v[170:173]
	v_mfma_f32_16x16x32_bf16 v[174:177], v[70:73], v[90:93], v[174:177]
	v_mfma_f32_16x16x32_bf16 v[178:181], v[54:57], v[118:121], v[178:181]
	v_mfma_f32_16x16x32_bf16 v[182:185], v[70:73], v[118:121], v[182:185]
	v_mfma_f32_16x16x32_bf16 v[186:189], v[54:57], v[206:209], v[186:189]
	v_mfma_f32_16x16x32_bf16 v[190:193], v[70:73], v[206:209], v[190:193]
	v_mfma_f32_16x16x32_bf16 v[158:161], v[54:57], v[216:219], v[158:161]
	v_mfma_f32_16x16x32_bf16 v[154:157], v[70:73], v[216:219], v[154:157]
	v_mfma_f32_16x16x32_bf16 v[62:65], v[162:165], v[82:85], v[62:65]
	v_mfma_f32_16x16x32_bf16 v[58:61], v[194:197], v[82:85], v[58:61]
	v_mfma_f32_16x16x32_bf16 v[82:85], v[162:165], v[202:205], v[94:97]
	v_mfma_f32_16x16x32_bf16 v[94:97], v[166:169], v[206:209], v[82:85]
	v_mfma_f32_16x16x32_bf16 v[82:85], v[194:197], v[202:205], v[98:101]
	v_mfma_f32_16x16x32_bf16 v[98:101], v[198:201], v[206:209], v[82:85]
	v_mfma_f32_16x16x32_bf16 v[82:85], v[162:165], v[210:213], v[106:109]
	v_mfma_f32_16x16x32_bf16 v[74:77], v[162:165], v[114:117], v[74:77]
	v_mfma_f32_16x16x32_bf16 v[78:81], v[194:197], v[114:117], v[78:81]
	v_mfma_f32_16x16x32_bf16 v[106:109], v[166:169], v[216:219], v[82:85]
	v_mfma_f32_16x16x32_bf16 v[82:85], v[194:197], v[210:213], v[110:113]
	v_mfma_f32_16x16x32_bf16 v[62:65], v[166:169], v[90:93], v[62:65]
	v_mfma_f32_16x16x32_bf16 v[58:61], v[198:201], v[90:93], v[58:61]
	v_mfma_f32_16x16x32_bf16 v[74:77], v[166:169], v[118:121], v[74:77]
	v_mfma_f32_16x16x32_bf16 v[78:81], v[198:201], v[118:121], v[78:81]
	v_mfma_f32_16x16x32_bf16 v[110:113], v[198:201], v[216:219], v[82:85]
	s_barrier
; #define PG8_STAGE(bufoff, gbase, voff) do { _Pragma("unroll") for (int _i = 0; _i < 2; ++_i) \
;         __builtin_amdgcn_global_load_lds((const unsigned*)((const char*)(gbase) + (voff)[_i]), (PG8_LAS unsigned*)(lds + (bufoff) + ldsw + _i * 8192), 16, 0, 0); } while (0)
; #define PG8_LDA(dst, b, h) do { _Pragma("unroll") for (int m = 0; m < 4; ++m) _Pragma("unroll") for (int k = 0; k < 2; ++k) dst[m][k] = *(const PG8_LAS bf16x8*)(lds + PG8_SA(b, h) + aoff + m * 2048 + k * 1024); } while (0)
; #define PG8_MMA(ai, bj, At, Bt) do { __builtin_amdgcn_s_setprio(1); _Pragma("unroll") for (int m = 0; m < 4; ++m) _Pragma("unroll") for (int n = 0; n < 2; ++n) _Pragma("unroll") for (int k = 0; k < 2; ++k) \
;         acc[ai][bj][m][n] = __builtin_amdgcn_mfma_f32_16x16x32_bf16(Bt[n][k], At[m][k], acc[ai][bj][m][n], 0, 0, 0); __builtin_amdgcn_s_setprio(0); } while (0)
; #define PG8_WAIT_V(n) asm volatile("s_waitcnt vmcnt(" #n ")" ::: "memory")
; #define PG8_WAIT_L(n) asm volatile("s_waitcnt lgkmcnt(" #n ")" ::: "memory")
; #define PG8_BAR __builtin_amdgcn_s_barrier()
; #define PG8_SCHED __builtin_amdgcn_sched_barrier(0)
; template <class Epi, class Sched, bool ALIGN_EPI = false, bool SP2 = false>
; __device__ __forceinline__ void gemm_phase(PG8_LAS unsigned char* lds, const Gemm g, const Sched& S, const Epi& E) {
;     ...
;             PG8_LDA(At, 1, 1); PG8_STAGE(PG8_SB(1, 0), b3, voffB); PG8_STAGE(PG8_SB(1, 1), b3 + hstepB, voffB); PG8_STAGE(PG8_SA(1, 0), a3, voffA);
;             PG8_WAIT_V(8); PG8_WAIT_L(0); PG8_BAR; PG8_MMA(1, 0, At, B0); PG8_MMA(1, 1, At, B1); PG8_BAR; PG8_SCHED;
;     ...
; #pragma unroll
;         for (int a = 0; a < 2; ++a)
; #pragma unroll
;             for (int b = 0; b < 2; ++b)
; #pragma unroll
;                 for (int m = 0; m < 4; ++m)
; #pragma unroll
;                     for (int n = 0; n < 2; ++n) acc[a][b][m][n] = (f32x4){0.f, 0.f, 0.f, 0.f};
;         cur = nxt; cA = nA; cB = nB; ++ui;
	s_add_i32 s34, s61, s44
	s_mov_b32 m0, s34
	ds_read_b128 v[118:121], v23 offset:49152
	ds_read_b128 v[202:205], v23 offset:50176
	ds_read_b128 v[206:209], v23 offset:51200
	ds_read_b128 v[210:213], v23 offset:52224
	ds_read_b128 v[216:219], v23 offset:53248
	ds_read_b128 v[220:223], v23 offset:54272
	ds_read_b128 v[224:227], v23 offset:55296
	ds_read_b128 v[228:231], v23 offset:56320
	global_load_lds_dwordx4 v4, s[98:99]
	s_add_i32 m0, s34, 0x2000
	s_add_u32 s30, s30, 0x40080
	s_addc_u32 s31, s31, 0
	s_add_i32 s34, s62, s44
	global_load_lds_dwordx4 v8, s[98:99]
	s_mov_b32 m0, s34
	s_nop 0
	global_load_lds_dwordx4 v4, s[30:31]
	s_add_i32 m0, s34, 0x2000
	s_nop 0
	global_load_lds_dwordx4 v8, s[30:31]
	s_mov_b32 m0, s51
	s_nop 0
	global_load_lds_dwordx4 v2, s[100:101]
	s_mov_b32 m0, s52
	s_nop 0
	global_load_lds_dwordx4 v6, s[100:101]
	s_waitcnt vmcnt(8)
	s_waitcnt lgkmcnt(0)
	s_barrier
	s_waitcnt lgkmcnt(0)
	v_mfma_f32_16x16x32_bf16 v[82:85], v[50:53], v[118:121], v[150:153]
	v_mfma_f32_16x16x32_bf16 v[150:153], v[54:57], v[202:205], v[82:85]
	v_mfma_f32_16x16x32_bf16 v[82:85], v[66:69], v[118:121], v[146:149]
	v_mfma_f32_16x16x32_bf16 v[146:149], v[70:73], v[202:205], v[82:85]
	v_mfma_f32_16x16x32_bf16 v[82:85], v[50:53], v[206:209], v[142:145]
	v_mfma_f32_16x16x32_bf16 v[142:145], v[54:57], v[210:213], v[82:85]
	v_mfma_f32_16x16x32_bf16 v[82:85], v[66:69], v[206:209], v[138:141]
	v_mfma_f32_16x16x32_bf16 v[138:141], v[70:73], v[210:213], v[82:85]
	v_mfma_f32_16x16x32_bf16 v[82:85], v[50:53], v[216:219], v[134:137]
	v_mfma_f32_16x16x32_bf16 v[34:37], v[50:53], v[224:227], v[34:37]
	v_mfma_f32_16x16x32_bf16 v[134:137], v[54:57], v[220:223], v[82:85]
	v_mfma_f32_16x16x32_bf16 v[82:85], v[66:69], v[216:219], v[130:133]
	v_mfma_f32_16x16x32_bf16 v[90:93], v[54:57], v[228:231], v[34:37]
	v_mfma_f32_16x16x32_bf16 v[34:37], v[66:69], v[224:227], v[38:41]
	v_mfma_f32_16x16x32_bf16 v[130:133], v[70:73], v[220:223], v[82:85]
	v_mfma_f32_16x16x32_bf16 v[82:85], v[70:73], v[228:231], v[34:37]
	v_mfma_f32_16x16x32_bf16 v[34:37], v[162:165], v[118:121], v[42:45]
	v_mfma_f32_16x16x32_bf16 v[114:117], v[166:169], v[202:205], v[34:37]
	v_mfma_f32_16x16x32_bf16 v[34:37], v[194:197], v[118:121], v[46:49]
	v_mfma_f32_16x16x32_bf16 v[118:121], v[198:201], v[202:205], v[34:37]
	v_mfma_f32_16x16x32_bf16 v[34:37], v[162:165], v[206:209], v[122:125]
	v_mfma_f32_16x16x32_bf16 v[122:125], v[166:169], v[210:213], v[34:37]
	v_mfma_f32_16x16x32_bf16 v[34:37], v[194:197], v[206:209], v[126:129]
	v_mfma_f32_16x16x32_bf16 v[126:129], v[198:201], v[210:213], v[34:37]
	v_mfma_f32_16x16x32_bf16 v[34:37], v[162:165], v[216:219], v[102:105]
	v_mfma_f32_16x16x32_bf16 v[102:105], v[166:169], v[220:223], v[34:37]
	v_mfma_f32_16x16x32_bf16 v[34:37], v[194:197], v[216:219], v[86:89]
	v_mfma_f32_16x16x32_bf16 v[28:31], v[162:165], v[224:227], v[30:33]
	v_mfma_f32_16x16x32_bf16 v[24:27], v[194:197], v[224:227], v[24:27]
	v_mfma_f32_16x16x32_bf16 v[86:89], v[198:201], v[220:223], v[34:37]
	v_mfma_f32_16x16x32_bf16 v[30:33], v[166:169], v[228:231], v[28:31]
	v_mfma_f32_16x16x32_bf16 v[26:29], v[198:201], v[228:231], v[24:27]
	s_barrier
	s_add_i32 s60, s60, 2
	s_add_u32 s28, s28, 0x100
	s_addc_u32 s29, s29, 0
	s_cmp_gt_u32 s60, 13
	s_cbranch_scc0 .LBB0_2500
	s_add_u32 s28, s56, 0xffffff00
	s_addc_u32 s29, s57, -1
	s_andn2_b64 vcc, exec, s[4:5]
	s_cbranch_vccnz .LBB0_2491
	v_mov_b32_e32 v26, 0
	s_mov_b32 s16, s20
	s_mov_b32 s14, s22
	s_mov_b64 s[0:1], s[26:27]
	s_mov_b32 s50, s55
	v_mov_b32_e32 v27, v26
	v_mov_b32_e32 v28, v26
	v_mov_b32_e32 v29, v26
	v_mov_b32_e32 v30, v26
	v_mov_b32_e32 v31, v26
	v_mov_b32_e32 v32, v26
	v_mov_b32_e32 v33, v26
	v_mov_b32_e32 v86, v26
	v_mov_b32_e32 v87, v26
	v_mov_b32_e32 v88, v26
	v_mov_b32_e32 v89, v26
	v_mov_b32_e32 v102, v26
	v_mov_b32_e32 v103, v26
	v_mov_b32_e32 v104, v26
	v_mov_b32_e32 v105, v26
	v_mov_b32_e32 v126, v26
	v_mov_b32_e32 v127, v26
	v_mov_b32_e32 v128, v26
	v_mov_b32_e32 v129, v26
	v_mov_b32_e32 v122, v26
	v_mov_b32_e32 v123, v26
	v_mov_b32_e32 v124, v26
	v_mov_b32_e32 v125, v26
	v_mov_b32_e32 v118, v26
	v_mov_b32_e32 v119, v26
	v_mov_b32_e32 v120, v26
	v_mov_b32_e32 v121, v26
	v_mov_b32_e32 v114, v26
	v_mov_b32_e32 v115, v26
	v_mov_b32_e32 v116, v26
	v_mov_b32_e32 v117, v26
	v_mov_b32_e32 v82, v26
	v_mov_b32_e32 v83, v26
	v_mov_b32_e32 v84, v26
	v_mov_b32_e32 v85, v26
	v_mov_b32_e32 v90, v26
	v_mov_b32_e32 v91, v26
	v_mov_b32_e32 v92, v26
	v_mov_b32_e32 v93, v26
	v_mov_b32_e32 v130, v26
	v_mov_b32_e32 v131, v26
	v_mov_b32_e32 v132, v26
	v_mov_b32_e32 v133, v26
	v_mov_b32_e32 v134, v26
	v_mov_b32_e32 v135, v26
	v_mov_b32_e32 v136, v26
	v_mov_b32_e32 v137, v26
	v_mov_b32_e32 v138, v26
	v_mov_b32_e32 v139, v26
	v_mov_b32_e32 v140, v26
	v_mov_b32_e32 v141, v26
	v_mov_b32_e32 v142, v26
	v_mov_b32_e32 v143, v26
	v_mov_b32_e32 v144, v26
	v_mov_b32_e32 v145, v26
	v_mov_b32_e32 v146, v26
	v_mov_b32_e32 v147, v26
	v_mov_b32_e32 v148, v26
	v_mov_b32_e32 v149, v26
	v_mov_b32_e32 v150, v26
	v_mov_b32_e32 v151, v26
	v_mov_b32_e32 v152, v26
	v_mov_b32_e32 v153, v26
	v_mov_b32_e32 v110, v26
	v_mov_b32_e32 v111, v26
	v_mov_b32_e32 v112, v26
	v_mov_b32_e32 v113, v26
	v_mov_b32_e32 v106, v26
	v_mov_b32_e32 v107, v26
	v_mov_b32_e32 v108, v26
	v_mov_b32_e32 v109, v26
	v_mov_b32_e32 v98, v26
	v_mov_b32_e32 v99, v26
	v_mov_b32_e32 v100, v26
	v_mov_b32_e32 v101, v26
	v_mov_b32_e32 v94, v26
	v_mov_b32_e32 v95, v26
	v_mov_b32_e32 v96, v26
	v_mov_b32_e32 v97, v26
	v_mov_b32_e32 v78, v26
	v_mov_b32_e32 v79, v26
	v_mov_b32_e32 v80, v26
	v_mov_b32_e32 v81, v26
	v_mov_b32_e32 v74, v26
	v_mov_b32_e32 v75, v26
	v_mov_b32_e32 v76, v26
	v_mov_b32_e32 v77, v26
	v_mov_b32_e32 v58, v26
	v_mov_b32_e32 v59, v26
	v_mov_b32_e32 v60, v26
	v_mov_b32_e32 v61, v26
	v_mov_b32_e32 v62, v26
	v_mov_b32_e32 v63, v26
	v_mov_b32_e32 v64, v26
	v_mov_b32_e32 v65, v26
	v_mov_b32_e32 v154, v26
	v_mov_b32_e32 v155, v26
	v_mov_b32_e32 v156, v26
	v_mov_b32_e32 v157, v26
	v_mov_b32_e32 v158, v26
	v_mov_b32_e32 v159, v26
	v_mov_b32_e32 v160, v26
	v_mov_b32_e32 v161, v26
	v_mov_b32_e32 v190, v26
	v_mov_b32_e32 v191, v26
	v_mov_b32_e32 v192, v26
	v_mov_b32_e32 v193, v26
	v_mov_b32_e32 v186, v26
	v_mov_b32_e32 v187, v26
	v_mov_b32_e32 v188, v26
	v_mov_b32_e32 v189, v26
	v_mov_b32_e32 v182, v26
	v_mov_b32_e32 v183, v26
	v_mov_b32_e32 v184, v26
	v_mov_b32_e32 v185, v26
	v_mov_b32_e32 v178, v26
	v_mov_b32_e32 v179, v26
	v_mov_b32_e32 v180, v26
	v_mov_b32_e32 v181, v26
	v_mov_b32_e32 v174, v26
	v_mov_b32_e32 v175, v26
	v_mov_b32_e32 v176, v26
	v_mov_b32_e32 v177, v26
	v_mov_b32_e32 v170, v26
	v_mov_b32_e32 v171, v26
	v_mov_b32_e32 v172, v26
	v_mov_b32_e32 v173, v26
	s_andn2_b64 vcc, exec, s[2:3]
	s_cbranch_vccnz .LBB0_2492

; #define PG8_STAGE(bufoff, gbase, voff) do { _Pragma("unroll") for (int _i = 0; _i < 2; ++_i) \
;         __builtin_amdgcn_global_load_lds((const unsigned*)((const char*)(gbase) + (voff)[_i]), (PG8_LAS unsigned*)(lds + (bufoff) + ldsw + _i * 8192), 16, 0, 0); } while (0)
; #define PG8_LDA(dst, b, h) do { _Pragma("unroll") for (int m = 0; m < 4; ++m) _Pragma("unroll") for (int k = 0; k < 2; ++k) dst[m][k] = *(const PG8_LAS bf16x8*)(lds + PG8_SA(b, h) + aoff + m * 2048 + k * 1024); } while (0)
; #define PG8_LDB(dst, b, h) do { _Pragma("unroll") for (int n = 0; n < 2; ++n) _Pragma("unroll") for (int k = 0; k < 2; ++k) dst[n][k] = *(const PG8_LAS bf16x8*)(lds + PG8_SB(b, h) + boff + n * 2048 + k * 1024); } while (0)
; #define PG8_MMA(ai, bj, At, Bt) do { __builtin_amdgcn_s_setprio(1); _Pragma("unroll") for (int m = 0; m < 4; ++m) _Pragma("unroll") for (int n = 0; n < 2; ++n) _Pragma("unroll") for (int k = 0; k < 2; ++k) \
;         acc[ai][bj][m][n] = __builtin_amdgcn_mfma_f32_16x16x32_bf16(Bt[n][k], At[m][k], acc[ai][bj][m][n], 0, 0, 0); __builtin_amdgcn_s_setprio(0); } while (0)
; #define PG8_WAIT_V(n) asm volatile("s_waitcnt vmcnt(" #n ")" ::: "memory")
; #define PG8_BAR __builtin_amdgcn_s_barrier()
; template <class Epi, class Sched, bool ALIGN_EPI = false, bool SP2 = false>
; __device__ __forceinline__ void gemm_phase(PG8_LAS unsigned char* lds, const Gemm g, const Sched& S, const Epi& E) {
;     ...
;         for (int t = 0; t < nt; t += 2) {
;             const bool last = (t == nt - 2);
;             const char* a1 = cA + (size_t)(t + 1) * kstep;
;             const char* a2 = last ? nA : cA + (size_t)(t + 2) * kstep; const char* b2 = last ? nB : cB + (size_t)(t + 2) * kstep;
;             const char* a3 = a2 + kstep; const char* b3 = b2 + kstep;
;             if (last && has_next) S.a_ready(nxt);
;             if constexpr (SP2) {
;             PG8_LDB(B0, 0, 0); PG8_LDB(B1, 0, 1); PG8_SCHED; PG8_LDA(At, 0, 0); PG8_STAGE(PG8_SA(1, 1), a1 + hstepA, voffA);
;             PG8_WAIT_V(8); PG8_WAIT_L(0); PG8_BAR; PG8_MMA(0, 0, At, B0); PG8_MMA(0, 1, At, B1); PG8_BAR; PG8_SCHED;
;             PG8_LDA(At, 0, 1); PG8_STAGE(PG8_SB(0, 0), b2, voffB); PG8_STAGE(PG8_SB(0, 1), b2 + hstepB, voffB); PG8_STAGE(PG8_SA(0, 0), a2, voffA);
;             PG8_WAIT_V(8); PG8_WAIT_L(0); PG8_BAR; PG8_MMA(1, 0, At, B0); PG8_MMA(1, 1, At, B1); PG8_BAR; PG8_SCHED;
.LBB0_2613:
	ds_read_b128 v[130:133], v182
	ds_read_b128 v[134:137], v182 offset:1024
	ds_read_b128 v[154:157], v182 offset:2048
	ds_read_b128 v[158:161], v182 offset:3072
	ds_read_b128 v[162:165], v183
	ds_read_b128 v[166:169], v183 offset:1024
	ds_read_b128 v[170:173], v183 offset:2048
	ds_read_b128 v[186:189], v183 offset:3072
	s_add_u32 s44, s42, 0xfffc0080
	s_addc_u32 s45, s43, -1
	s_cmp_eq_u32 s70, 12
	s_cselect_b32 s47, s31, s45
	s_cselect_b32 s46, s39, s44
	s_cselect_b32 s45, s29, s69
	s_cselect_b32 s44, s67, s68
	s_add_i32 m0, s41, 0xc000
	ds_read_b128 v[190:193], v184
	ds_read_b128 v[194:197], v184 offset:1024
	ds_read_b128 v[198:201], v184 offset:2048
	ds_read_b128 v[202:205], v184 offset:3072
	ds_read_b128 v[206:209], v184 offset:4096
	ds_read_b128 v[210:213], v184 offset:5120
	ds_read_b128 v[214:217], v184 offset:6144
	ds_read_b128 v[218:221], v184 offset:7168
	global_load_lds_dwordx4 v146, s[42:43]
	s_add_i32 m0, s41, 0xe000
	s_nop 0
	global_load_lds_dwordx4 v148, s[42:43]
	s_waitcnt vmcnt(8)
	s_waitcnt lgkmcnt(0)
	s_barrier
	s_waitcnt lgkmcnt(0)
	v_mfma_f32_16x16x32_bf16 v[126:129], v[130:133], v[190:193], v[126:129]
	v_mfma_f32_16x16x32_bf16 v[94:97], v[154:157], v[190:193], v[94:97]
	v_mfma_f32_16x16x32_bf16 v[118:121], v[130:133], v[198:201], v[118:121]
	v_mfma_f32_16x16x32_bf16 v[86:89], v[154:157], v[198:201], v[86:89]
	v_mfma_f32_16x16x32_bf16 v[114:117], v[130:133], v[206:209], v[114:117]
	v_mfma_f32_16x16x32_bf16 v[82:85], v[154:157], v[206:209], v[82:85]
	v_mfma_f32_16x16x32_bf16 v[102:105], v[130:133], v[214:217], v[102:105]
	v_mfma_f32_16x16x32_bf16 v[70:73], v[154:157], v[214:217], v[70:73]
	v_mfma_f32_16x16x32_bf16 v[126:129], v[134:137], v[194:197], v[126:129]
	v_mfma_f32_16x16x32_bf16 v[94:97], v[158:161], v[194:197], v[94:97]
	v_mfma_f32_16x16x32_bf16 v[118:121], v[134:137], v[202:205], v[118:121]
	v_mfma_f32_16x16x32_bf16 v[86:89], v[158:161], v[202:205], v[86:89]
	v_mfma_f32_16x16x32_bf16 v[114:117], v[134:137], v[210:213], v[114:117]
	v_mfma_f32_16x16x32_bf16 v[82:85], v[158:161], v[210:213], v[82:85]
	v_mfma_f32_16x16x32_bf16 v[102:105], v[134:137], v[218:221], v[102:105]
	v_mfma_f32_16x16x32_bf16 v[70:73], v[158:161], v[218:221], v[70:73]
	v_mfma_f32_16x16x32_bf16 v[122:125], v[162:165], v[190:193], v[122:125]
	v_mfma_f32_16x16x32_bf16 v[90:93], v[170:173], v[190:193], v[90:93]
	v_mfma_f32_16x16x32_bf16 v[110:113], v[162:165], v[198:201], v[110:113]
	v_mfma_f32_16x16x32_bf16 v[78:81], v[170:173], v[198:201], v[78:81]
	v_mfma_f32_16x16x32_bf16 v[106:109], v[162:165], v[206:209], v[106:109]
	v_mfma_f32_16x16x32_bf16 v[74:77], v[170:173], v[206:209], v[74:77]
	v_mfma_f32_16x16x32_bf16 v[98:101], v[162:165], v[214:217], v[98:101]
	v_mfma_f32_16x16x32_bf16 v[66:69], v[170:173], v[214:217], v[66:69]
	v_mfma_f32_16x16x32_bf16 v[122:125], v[166:169], v[194:197], v[122:125]
	v_mfma_f32_16x16x32_bf16 v[90:93], v[186:189], v[194:197], v[90:93]
	v_mfma_f32_16x16x32_bf16 v[110:113], v[166:169], v[202:205], v[110:113]
	v_mfma_f32_16x16x32_bf16 v[78:81], v[186:189], v[202:205], v[78:81]
	v_mfma_f32_16x16x32_bf16 v[106:109], v[166:169], v[210:213], v[106:109]
	v_mfma_f32_16x16x32_bf16 v[74:77], v[186:189], v[210:213], v[74:77]
	v_mfma_f32_16x16x32_bf16 v[98:101], v[166:169], v[218:221], v[98:101]
	v_mfma_f32_16x16x32_bf16 v[66:69], v[186:189], v[218:221], v[66:69]
	s_barrier
	s_add_i32 s71, s64, s51
	s_add_u32 s98, s44, 0x80
	s_addc_u32 s99, s45, 0
	s_mov_b32 m0, s71
	ds_read_b128 v[190:193], v184 offset:16384
	ds_read_b128 v[194:197], v184 offset:17408
	ds_read_b128 v[198:201], v184 offset:18432
	ds_read_b128 v[202:205], v184 offset:19456
	ds_read_b128 v[206:209], v184 offset:20480
	ds_read_b128 v[210:213], v184 offset:21504
	ds_read_b128 v[214:217], v184 offset:22528
	ds_read_b128 v[218:221], v184 offset:23552
	global_load_lds_dwordx4 v140, s[44:45]
	s_add_i32 m0, s71, 0x2000
	s_add_u32 s72, s44, 0x40000
	s_addc_u32 s73, s45, 0
	s_add_i32 s71, s65, s51
	global_load_lds_dwordx4 v144, s[44:45]
	s_mov_b32 m0, s71
	v_lshl_add_u64 v[226:227], s[46:47], 0, v[142:143]
	global_load_lds_dwordx4 v140, s[72:73]
	s_add_i32 m0, s71, 0x2000
	s_nop 0
	global_load_lds_dwordx4 v144, s[72:73]
	s_add_u32 s100, s46, 0x80
	s_addc_u32 s101, s47, 0
	s_mov_b32 m0, s41
	s_nop 0
	global_load_lds_dwordx4 v138, s[46:47]
	s_mov_b32 m0, s52
	s_nop 0
	global_load_lds_dwordx4 v142, s[46:47]
	s_waitcnt vmcnt(8)
	s_waitcnt lgkmcnt(0)
	s_barrier
	s_waitcnt lgkmcnt(0)
	v_mfma_f32_16x16x32_bf16 v[62:65], v[130:133], v[190:193], v[62:65]
	v_mfma_f32_16x16x32_bf16 v[30:33], v[154:157], v[190:193], v[30:33]
	v_mfma_f32_16x16x32_bf16 v[54:57], v[130:133], v[198:201], v[54:57]
	v_mfma_f32_16x16x32_bf16 v[22:25], v[154:157], v[198:201], v[22:25]
	v_mfma_f32_16x16x32_bf16 v[50:53], v[130:133], v[206:209], v[50:53]
	v_mfma_f32_16x16x32_bf16 v[18:21], v[154:157], v[206:209], v[18:21]
	v_mfma_f32_16x16x32_bf16 v[38:41], v[130:133], v[214:217], v[38:41]
	v_mfma_f32_16x16x32_bf16 v[6:9], v[154:157], v[214:217], v[6:9]
	v_mfma_f32_16x16x32_bf16 v[62:65], v[134:137], v[194:197], v[62:65]
	v_mfma_f32_16x16x32_bf16 v[30:33], v[158:161], v[194:197], v[30:33]
	v_mfma_f32_16x16x32_bf16 v[54:57], v[134:137], v[202:205], v[54:57]
	v_mfma_f32_16x16x32_bf16 v[22:25], v[158:161], v[202:205], v[22:25]
	v_mfma_f32_16x16x32_bf16 v[50:53], v[134:137], v[210:213], v[50:53]
	v_mfma_f32_16x16x32_bf16 v[18:21], v[158:161], v[210:213], v[18:21]
	v_mfma_f32_16x16x32_bf16 v[38:41], v[134:137], v[218:221], v[38:41]
	v_mfma_f32_16x16x32_bf16 v[6:9], v[158:161], v[218:221], v[6:9]
	v_mfma_f32_16x16x32_bf16 v[58:61], v[162:165], v[190:193], v[58:61]
	v_mfma_f32_16x16x32_bf16 v[26:29], v[170:173], v[190:193], v[26:29]
	v_mfma_f32_16x16x32_bf16 v[46:49], v[162:165], v[198:201], v[46:49]
	v_mfma_f32_16x16x32_bf16 v[14:17], v[170:173], v[198:201], v[14:17]
	v_mfma_f32_16x16x32_bf16 v[42:45], v[162:165], v[206:209], v[42:45]
	v_mfma_f32_16x16x32_bf16 v[10:13], v[170:173], v[206:209], v[10:13]
	v_mfma_f32_16x16x32_bf16 v[34:37], v[162:165], v[214:217], v[34:37]
	v_mfma_f32_16x16x32_bf16 v[2:5], v[170:173], v[214:217], v[2:5]
	v_mfma_f32_16x16x32_bf16 v[58:61], v[166:169], v[194:197], v[58:61]
	v_mfma_f32_16x16x32_bf16 v[26:29], v[186:189], v[194:197], v[26:29]
	v_mfma_f32_16x16x32_bf16 v[46:49], v[166:169], v[202:205], v[46:49]
	v_mfma_f32_16x16x32_bf16 v[14:17], v[186:189], v[202:205], v[14:17]
	v_mfma_f32_16x16x32_bf16 v[42:45], v[166:169], v[210:213], v[42:45]
	v_mfma_f32_16x16x32_bf16 v[10:13], v[186:189], v[210:213], v[10:13]
	v_mfma_f32_16x16x32_bf16 v[34:37], v[166:169], v[218:221], v[34:37]
	v_mfma_f32_16x16x32_bf16 v[2:5], v[186:189], v[218:221], v[2:5]
	s_barrier
; #define PG8_STAGE(bufoff, gbase, voff) do { _Pragma("unroll") for (int _i = 0; _i < 2; ++_i) \
;         __builtin_amdgcn_global_load_lds((const unsigned*)((const char*)(gbase) + (voff)[_i]), (PG8_LAS unsigned*)(lds + (bufoff) + ldsw + _i * 8192), 16, 0, 0); } while (0)
; #define PG8_LDA(dst, b, h) do { _Pragma("unroll") for (int m = 0; m < 4; ++m) _Pragma("unroll") for (int k = 0; k < 2; ++k) dst[m][k] = *(const PG8_LAS bf16x8*)(lds + PG8_SA(b, h) + aoff + m * 2048 + k * 1024); } while (0)
; #define PG8_LDB(dst, b, h) do { _Pragma("unroll") for (int n = 0; n < 2; ++n) _Pragma("unroll") for (int k = 0; k < 2; ++k) dst[n][k] = *(const PG8_LAS bf16x8*)(lds + PG8_SB(b, h) + boff + n * 2048 + k * 1024); } while (0)
; #define PG8_MMA(ai, bj, At, Bt) do { __builtin_amdgcn_s_setprio(1); _Pragma("unroll") for (int m = 0; m < 4; ++m) _Pragma("unroll") for (int n = 0; n < 2; ++n) _Pragma("unroll") for (int k = 0; k < 2; ++k) \
;         acc[ai][bj][m][n] = __builtin_amdgcn_mfma_f32_16x16x32_bf16(Bt[n][k], At[m][k], acc[ai][bj][m][n], 0, 0, 0); __builtin_amdgcn_s_setprio(0); } while (0)
; #define PG8_WAIT_V(n) asm volatile("s_waitcnt vmcnt(" #n ")" ::: "memory")
; #define PG8_WAIT_L(n) asm volatile("s_waitcnt lgkmcnt(" #n ")" ::: "memory")
; #define PG8_BAR __builtin_amdgcn_s_barrier()
; #define PG8_SCHED __builtin_amdgcn_sched_barrier(0)
; template <class Epi, class Sched, bool ALIGN_EPI = false, bool SP2 = false>
; __device__ __forceinline__ void gemm_phase(PG8_LAS unsigned char* lds, const Gemm g, const Sched& S, const Epi& E) {
;     ...
;         for (int t = 0; t < nt; t += 2) {
;             const bool last = (t == nt - 2);
;     ...
;             PG8_LDB(B0, 1, 0); PG8_LDB(B1, 1, 1); PG8_SCHED; PG8_LDA(At, 1, 0); PG8_STAGE(PG8_SA(0, 1), a2 + hstepA, voffA);
;             PG8_WAIT_V(8); PG8_WAIT_L(0); PG8_BAR; PG8_MMA(0, 0, At, B0); PG8_MMA(0, 1, At, B1); PG8_BAR; PG8_SCHED;
;             PG8_LDA(At, 1, 1); PG8_STAGE(PG8_SB(1, 0), b3, voffB); PG8_STAGE(PG8_SB(1, 1), b3 + hstepB, voffB); PG8_STAGE(PG8_SA(1, 0), a3, voffA);
;             PG8_WAIT_V(8); PG8_WAIT_L(0); PG8_BAR; PG8_MMA(1, 0, At, B0); PG8_MMA(1, 1, At, B1); PG8_BAR; PG8_SCHED;
	s_add_i32 s71, 0, 0x18000
	s_add_i32 s72, 0, 0x1c000
	v_add_u32_e32 v158, s71, v176
	v_add_u32_e32 v185, s72, v176
	ds_read_b128 v[130:133], v158
	ds_read_b128 v[134:137], v158 offset:1024
	ds_read_b128 v[154:157], v158 offset:2048
	ds_read_b128 v[158:161], v158 offset:3072
	ds_read_b128 v[162:165], v185
	ds_read_b128 v[166:169], v185 offset:1024
	ds_read_b128 v[170:173], v185 offset:2048
	ds_read_b128 v[186:189], v185 offset:3072
	s_add_u32 s46, s46, 0x40000
	s_addc_u32 s47, s47, 0
	s_mov_b32 m0, s53
	ds_read_b128 v[190:193], v184 offset:32768
	ds_read_b128 v[194:197], v184 offset:33792
	ds_read_b128 v[198:201], v184 offset:34816
	ds_read_b128 v[202:205], v184 offset:35840
	ds_read_b128 v[206:209], v184 offset:36864
	ds_read_b128 v[210:213], v184 offset:37888
	ds_read_b128 v[214:217], v184 offset:38912
	ds_read_b128 v[218:221], v184 offset:39936
	global_load_lds_dwordx4 v138, s[46:47]
	s_mov_b32 m0, s54
	s_nop 0
	global_load_lds_dwordx4 v142, s[46:47]
	s_waitcnt vmcnt(8)
	s_waitcnt lgkmcnt(0)
	s_barrier
	s_waitcnt lgkmcnt(0)
	v_mfma_f32_16x16x32_bf16 v[126:129], v[130:133], v[190:193], v[126:129]
	v_mfma_f32_16x16x32_bf16 v[94:97], v[154:157], v[190:193], v[94:97]
	v_mfma_f32_16x16x32_bf16 v[118:121], v[130:133], v[198:201], v[118:121]
	v_mfma_f32_16x16x32_bf16 v[86:89], v[154:157], v[198:201], v[86:89]
	v_mfma_f32_16x16x32_bf16 v[114:117], v[130:133], v[206:209], v[114:117]
	v_mfma_f32_16x16x32_bf16 v[82:85], v[154:157], v[206:209], v[82:85]
	v_mfma_f32_16x16x32_bf16 v[102:105], v[130:133], v[214:217], v[102:105]
	v_mfma_f32_16x16x32_bf16 v[70:73], v[154:157], v[214:217], v[70:73]
	v_mfma_f32_16x16x32_bf16 v[126:129], v[134:137], v[194:197], v[126:129]
	v_mfma_f32_16x16x32_bf16 v[94:97], v[158:161], v[194:197], v[94:97]
	v_mfma_f32_16x16x32_bf16 v[118:121], v[134:137], v[202:205], v[118:121]
	v_mfma_f32_16x16x32_bf16 v[86:89], v[158:161], v[202:205], v[86:89]
	v_mfma_f32_16x16x32_bf16 v[114:117], v[134:137], v[210:213], v[114:117]
	v_mfma_f32_16x16x32_bf16 v[82:85], v[158:161], v[210:213], v[82:85]
	v_mfma_f32_16x16x32_bf16 v[102:105], v[134:137], v[218:221], v[102:105]
	v_mfma_f32_16x16x32_bf16 v[70:73], v[158:161], v[218:221], v[70:73]
	v_mfma_f32_16x16x32_bf16 v[122:125], v[162:165], v[190:193], v[122:125]
	v_mfma_f32_16x16x32_bf16 v[90:93], v[170:173], v[190:193], v[90:93]
	v_mfma_f32_16x16x32_bf16 v[110:113], v[162:165], v[198:201], v[110:113]
	v_mfma_f32_16x16x32_bf16 v[78:81], v[170:173], v[198:201], v[78:81]
	v_mfma_f32_16x16x32_bf16 v[106:109], v[162:165], v[206:209], v[106:109]
	v_mfma_f32_16x16x32_bf16 v[74:77], v[170:173], v[206:209], v[74:77]
	v_mfma_f32_16x16x32_bf16 v[98:101], v[162:165], v[214:217], v[98:101]
	v_mfma_f32_16x16x32_bf16 v[66:69], v[170:173], v[214:217], v[66:69]
	v_mfma_f32_16x16x32_bf16 v[122:125], v[166:169], v[194:197], v[122:125]
	v_mfma_f32_16x16x32_bf16 v[90:93], v[186:189], v[194:197], v[90:93]
	v_mfma_f32_16x16x32_bf16 v[110:113], v[166:169], v[202:205], v[110:113]
	v_mfma_f32_16x16x32_bf16 v[78:81], v[186:189], v[202:205], v[78:81]
	v_mfma_f32_16x16x32_bf16 v[106:109], v[166:169], v[210:213], v[106:109]
	v_mfma_f32_16x16x32_bf16 v[74:77], v[186:189], v[210:213], v[74:77]
	v_mfma_f32_16x16x32_bf16 v[98:101], v[166:169], v[218:221], v[98:101]
	v_mfma_f32_16x16x32_bf16 v[66:69], v[186:189], v[218:221], v[66:69]
	s_barrier
	s_add_i32 s46, s71, s51
	s_mov_b32 m0, s46
	ds_read_b128 v[190:193], v184 offset:49152
	ds_read_b128 v[194:197], v184 offset:50176
	ds_read_b128 v[198:201], v184 offset:51200
	ds_read_b128 v[202:205], v184 offset:52224
	ds_read_b128 v[206:209], v184 offset:53248
	ds_read_b128 v[210:213], v184 offset:54272
	ds_read_b128 v[214:217], v184 offset:55296
	ds_read_b128 v[218:221], v184 offset:56320
	global_load_lds_dwordx4 v140, s[98:99]
	s_add_i32 m0, s46, 0x2000
	s_add_u32 s44, s44, 0x40080
	s_addc_u32 s45, s45, 0
	s_add_i32 s46, s72, s51
	global_load_lds_dwordx4 v144, s[98:99]
	s_mov_b32 m0, s46
	s_nop 0
	global_load_lds_dwordx4 v140, s[44:45]
	s_add_i32 m0, s46, 0x2000
	s_nop 0
	global_load_lds_dwordx4 v144, s[44:45]
	s_mov_b32 m0, s59
	s_nop 0
	global_load_lds_dwordx4 v138, s[100:101]
	v_lshl_add_u64 v[174:175], v[226:227], 0, s[24:25]
	s_mov_b32 m0, s60
	s_nop 0
	global_load_lds_dwordx4 v142, s[100:101]
	s_waitcnt vmcnt(8)
	s_waitcnt lgkmcnt(0)
	s_barrier
	s_waitcnt lgkmcnt(0)
	v_mfma_f32_16x16x32_bf16 v[62:65], v[130:133], v[190:193], v[62:65]
	v_mfma_f32_16x16x32_bf16 v[30:33], v[154:157], v[190:193], v[30:33]
	v_mfma_f32_16x16x32_bf16 v[54:57], v[130:133], v[198:201], v[54:57]
	v_mfma_f32_16x16x32_bf16 v[22:25], v[154:157], v[198:201], v[22:25]
	v_mfma_f32_16x16x32_bf16 v[50:53], v[130:133], v[206:209], v[50:53]
	v_mfma_f32_16x16x32_bf16 v[18:21], v[154:157], v[206:209], v[18:21]
	v_mfma_f32_16x16x32_bf16 v[38:41], v[130:133], v[214:217], v[38:41]
	v_mfma_f32_16x16x32_bf16 v[6:9], v[154:157], v[214:217], v[6:9]
	v_mfma_f32_16x16x32_bf16 v[62:65], v[134:137], v[194:197], v[62:65]
	v_mfma_f32_16x16x32_bf16 v[30:33], v[158:161], v[194:197], v[30:33]
	v_mfma_f32_16x16x32_bf16 v[54:57], v[134:137], v[202:205], v[54:57]
	v_mfma_f32_16x16x32_bf16 v[22:25], v[158:161], v[202:205], v[22:25]
	v_mfma_f32_16x16x32_bf16 v[50:53], v[134:137], v[210:213], v[50:53]
	v_mfma_f32_16x16x32_bf16 v[18:21], v[158:161], v[210:213], v[18:21]
	v_mfma_f32_16x16x32_bf16 v[38:41], v[134:137], v[218:221], v[38:41]
	v_mfma_f32_16x16x32_bf16 v[6:9], v[158:161], v[218:221], v[6:9]
	v_mfma_f32_16x16x32_bf16 v[58:61], v[162:165], v[190:193], v[58:61]
	v_mfma_f32_16x16x32_bf16 v[26:29], v[170:173], v[190:193], v[26:29]
	v_mfma_f32_16x16x32_bf16 v[46:49], v[162:165], v[198:201], v[46:49]
	v_mfma_f32_16x16x32_bf16 v[14:17], v[170:173], v[198:201], v[14:17]
	v_mfma_f32_16x16x32_bf16 v[42:45], v[162:165], v[206:209], v[42:45]
	v_mfma_f32_16x16x32_bf16 v[10:13], v[170:173], v[206:209], v[10:13]
	v_mfma_f32_16x16x32_bf16 v[34:37], v[162:165], v[214:217], v[34:37]
	v_mfma_f32_16x16x32_bf16 v[2:5], v[170:173], v[214:217], v[2:5]
	v_mfma_f32_16x16x32_bf16 v[58:61], v[166:169], v[194:197], v[58:61]
	v_mfma_f32_16x16x32_bf16 v[26:29], v[186:189], v[194:197], v[26:29]
	v_mfma_f32_16x16x32_bf16 v[46:49], v[166:169], v[202:205], v[46:49]
	v_mfma_f32_16x16x32_bf16 v[14:17], v[186:189], v[202:205], v[14:17]
	v_mfma_f32_16x16x32_bf16 v[42:45], v[166:169], v[210:213], v[42:45]
	v_mfma_f32_16x16x32_bf16 v[10:13], v[186:189], v[210:213], v[10:13]
	v_mfma_f32_16x16x32_bf16 v[34:37], v[166:169], v[218:221], v[34:37]
	v_mfma_f32_16x16x32_bf16 v[2:5], v[186:189], v[218:221], v[2:5]
	s_barrier
	s_add_i32 s70, s70, 2
	s_add_u32 s42, s42, 0x100
	s_addc_u32 s43, s43, 0
	s_add_u32 s68, s68, 0x100
	s_addc_u32 s69, s69, 0
	s_cmp_gt_u32 s70, 13
	s_cbranch_scc0 .LBB0_2613
	s_and_b64 vcc, exec, s[26:27]
	s_cbranch_vccz .LBB0_2616
	s_barrier

; #define PG8_STAGE(bufoff, gbase, voff) do { _Pragma("unroll") for (int _i = 0; _i < 2; ++_i) \
;         __builtin_amdgcn_global_load_lds((const unsigned*)((const char*)(gbase) + (voff)[_i]), (PG8_LAS unsigned*)(lds + (bufoff) + ldsw + _i * 8192), 16, 0, 0); } while (0)
; #define PG8_LDA(dst, b, h) do { _Pragma("unroll") for (int m = 0; m < 4; ++m) _Pragma("unroll") for (int k = 0; k < 2; ++k) dst[m][k] = *(const PG8_LAS bf16x8*)(lds + PG8_SA(b, h) + aoff + m * 2048 + k * 1024); } while (0)
; #define PG8_LDB(dst, b, h) do { _Pragma("unroll") for (int n = 0; n < 2; ++n) _Pragma("unroll") for (int k = 0; k < 2; ++k) dst[n][k] = *(const PG8_LAS bf16x8*)(lds + PG8_SB(b, h) + boff + n * 2048 + k * 1024); } while (0)
; #define PG8_MMA(ai, bj, At, Bt) do { __builtin_amdgcn_s_setprio(1); _Pragma("unroll") for (int m = 0; m < 4; ++m) _Pragma("unroll") for (int n = 0; n < 2; ++n) _Pragma("unroll") for (int k = 0; k < 2; ++k) \
;         acc[ai][bj][m][n] = __builtin_amdgcn_mfma_f32_16x16x32_bf16(Bt[n][k], At[m][k], acc[ai][bj][m][n], 0, 0, 0); __builtin_amdgcn_s_setprio(0); } while (0)
; #define PG8_WAIT_V(n) asm volatile("s_waitcnt vmcnt(" #n ")" ::: "memory")
; #define PG8_BAR __builtin_amdgcn_s_barrier()
; template <class Epi, class Sched, bool ALIGN_EPI = false, bool SP2 = false>
; __device__ __forceinline__ void gemm_phase(PG8_LAS unsigned char* lds, const Gemm g, const Sched& S, const Epi& E) {
;     ...
;         for (int t = 0; t < nt; t += 2) {
;             const bool last = (t == nt - 2);
;             const char* a1 = cA + (size_t)(t + 1) * kstep;
;             const char* a2 = last ? nA : cA + (size_t)(t + 2) * kstep; const char* b2 = last ? nB : cB + (size_t)(t + 2) * kstep;
;             const char* a3 = a2 + kstep; const char* b3 = b2 + kstep;
;             if (last && has_next) S.a_ready(nxt);
;             if constexpr (SP2) {
;             PG8_LDB(B0, 0, 0); PG8_LDB(B1, 0, 1); PG8_SCHED; PG8_LDA(At, 0, 0); PG8_STAGE(PG8_SA(1, 1), a1 + hstepA, voffA);
;             PG8_WAIT_V(8); PG8_WAIT_L(0); PG8_BAR; PG8_MMA(0, 0, At, B0); PG8_MMA(0, 1, At, B1); PG8_BAR; PG8_SCHED;
;             PG8_LDA(At, 0, 1); PG8_STAGE(PG8_SB(0, 0), b2, voffB); PG8_STAGE(PG8_SB(0, 1), b2 + hstepB, voffB); PG8_STAGE(PG8_SA(0, 0), a2, voffA);
;             PG8_WAIT_V(8); PG8_WAIT_L(0); PG8_BAR; PG8_MMA(1, 0, At, B0); PG8_MMA(1, 1, At, B1); PG8_BAR; PG8_SCHED;
.LBB0_2807:
	v_add_u32_e32 v68, s49, v58
	ds_read_b128 v[60:63], v68
	ds_read_b128 v[64:67], v68 offset:1024
	ds_read_b128 v[162:165], v68 offset:2048
	ds_read_b128 v[166:169], v68 offset:3072
	v_add_u32_e32 v68, s50, v58
	s_add_u32 s22, s14, s20
	ds_read_b128 v[170:173], v68
	ds_read_b128 v[174:177], v68 offset:1024
	ds_read_b128 v[178:181], v68 offset:2048
	ds_read_b128 v[184:187], v68 offset:3072
	s_addc_u32 s23, s15, s21
	s_add_u32 s22, s22, 0x100
	s_addc_u32 s23, s23, 0
	s_add_u32 s57, s54, s20
	s_addc_u32 s58, s55, s21
	s_cmpk_eq_i32 s20, 0x1500
	s_cselect_b32 s25, s19, s23
	s_cselect_b32 s24, s18, s22
	s_cselect_b32 s23, s1, s58
	s_cselect_b32 s22, s0, s57
	v_lshl_add_u64 v[68:69], v[54:55], 0, s[20:21]
	s_add_i32 m0, s41, 0xc000
	ds_read_b128 v[188:191], v59
	ds_read_b128 v[192:195], v59 offset:1024
	ds_read_b128 v[196:199], v59 offset:2048
	ds_read_b128 v[200:203], v59 offset:3072
	ds_read_b128 v[204:207], v59 offset:4096
	ds_read_b128 v[208:211], v59 offset:5120
	ds_read_b128 v[212:215], v59 offset:6144
	ds_read_b128 v[216:219], v59 offset:7168
	global_load_lds_dwordx4 v[68:69], off
	v_lshl_add_u64 v[68:69], v[56:57], 0, s[20:21]
	s_add_i32 m0, s41, 0xe000
	s_nop 0
	global_load_lds_dwordx4 v[68:69], off
	s_waitcnt vmcnt(8)
	s_waitcnt lgkmcnt(0)
	s_barrier
	s_waitcnt lgkmcnt(0)
	v_mfma_f32_16x16x32_bf16 v[158:161], v[60:63], v[188:191], v[158:161]
	v_mfma_f32_16x16x32_bf16 v[146:149], v[162:165], v[188:191], v[146:149]
	v_mfma_f32_16x16x32_bf16 v[150:153], v[60:63], v[196:199], v[150:153]
	v_mfma_f32_16x16x32_bf16 v[154:157], v[162:165], v[196:199], v[154:157]
	v_mfma_f32_16x16x32_bf16 v[142:145], v[60:63], v[204:207], v[142:145]
	v_mfma_f32_16x16x32_bf16 v[138:141], v[162:165], v[204:207], v[138:141]
	v_mfma_f32_16x16x32_bf16 v[134:137], v[60:63], v[212:215], v[134:137]
	v_mfma_f32_16x16x32_bf16 v[130:133], v[162:165], v[212:215], v[130:133]
	v_mfma_f32_16x16x32_bf16 v[158:161], v[64:67], v[192:195], v[158:161]
	v_mfma_f32_16x16x32_bf16 v[146:149], v[166:169], v[192:195], v[146:149]
	v_mfma_f32_16x16x32_bf16 v[150:153], v[64:67], v[200:203], v[150:153]
	v_mfma_f32_16x16x32_bf16 v[154:157], v[166:169], v[200:203], v[154:157]
	v_mfma_f32_16x16x32_bf16 v[142:145], v[64:67], v[208:211], v[142:145]
	v_mfma_f32_16x16x32_bf16 v[138:141], v[166:169], v[208:211], v[138:141]
	v_mfma_f32_16x16x32_bf16 v[134:137], v[64:67], v[216:219], v[134:137]
	v_mfma_f32_16x16x32_bf16 v[130:133], v[166:169], v[216:219], v[130:133]
	v_mfma_f32_16x16x32_bf16 v[78:81], v[170:173], v[188:191], v[78:81]
	v_mfma_f32_16x16x32_bf16 v[74:77], v[178:181], v[188:191], v[74:77]
	v_mfma_f32_16x16x32_bf16 v[86:89], v[170:173], v[196:199], v[86:89]
	v_mfma_f32_16x16x32_bf16 v[90:93], v[178:181], v[196:199], v[90:93]
	v_mfma_f32_16x16x32_bf16 v[118:121], v[170:173], v[204:207], v[118:121]
	v_mfma_f32_16x16x32_bf16 v[114:117], v[178:181], v[204:207], v[114:117]
	v_mfma_f32_16x16x32_bf16 v[122:125], v[170:173], v[212:215], v[122:125]
	v_mfma_f32_16x16x32_bf16 v[126:129], v[178:181], v[212:215], v[126:129]
	v_mfma_f32_16x16x32_bf16 v[78:81], v[174:177], v[192:195], v[78:81]
	v_mfma_f32_16x16x32_bf16 v[74:77], v[184:187], v[192:195], v[74:77]
	v_mfma_f32_16x16x32_bf16 v[86:89], v[174:177], v[200:203], v[86:89]
	v_mfma_f32_16x16x32_bf16 v[90:93], v[184:187], v[200:203], v[90:93]
	v_mfma_f32_16x16x32_bf16 v[118:121], v[174:177], v[208:211], v[118:121]
	v_mfma_f32_16x16x32_bf16 v[114:117], v[184:187], v[208:211], v[114:117]
	v_mfma_f32_16x16x32_bf16 v[122:125], v[174:177], v[216:219], v[122:125]
	v_mfma_f32_16x16x32_bf16 v[126:129], v[184:187], v[216:219], v[126:129]
	s_barrier
	s_add_i32 s57, s49, s40
	s_add_u32 s98, s22, 0x80
	s_addc_u32 s99, s23, 0
	s_mov_b32 m0, s57
	ds_read_b128 v[188:191], v59 offset:16384
	ds_read_b128 v[192:195], v59 offset:17408
	ds_read_b128 v[196:199], v59 offset:18432
	ds_read_b128 v[200:203], v59 offset:19456
	ds_read_b128 v[204:207], v59 offset:20480
	ds_read_b128 v[208:211], v59 offset:21504
	ds_read_b128 v[212:215], v59 offset:22528
	ds_read_b128 v[216:219], v59 offset:23552
	global_load_lds_dwordx4 v8, s[22:23]
	s_add_i32 m0, s57, 0x2000
	s_add_u32 s58, s22, 0xb0000
	s_addc_u32 s59, s23, 0
	s_add_i32 s57, s50, s40
	global_load_lds_dwordx4 v12, s[22:23]
	s_mov_b32 m0, s57
	s_add_u32 s100, s24, 0x80
	s_addc_u32 s101, s25, 0
	global_load_lds_dwordx4 v8, s[58:59]
	s_add_i32 m0, s57, 0x2000
	s_nop 0
	global_load_lds_dwordx4 v12, s[58:59]
	s_mov_b32 m0, s41
	s_nop 0
	global_load_lds_dwordx4 v6, s[24:25]
	s_mov_b32 m0, s42
	s_nop 0
	global_load_lds_dwordx4 v10, s[24:25]
	s_waitcnt vmcnt(8)
	s_waitcnt lgkmcnt(0)
	s_barrier
; #define PG8_STAGE(bufoff, gbase, voff) do { _Pragma("unroll") for (int _i = 0; _i < 2; ++_i) \
;         __builtin_amdgcn_global_load_lds((const unsigned*)((const char*)(gbase) + (voff)[_i]), (PG8_LAS unsigned*)(lds + (bufoff) + ldsw + _i * 8192), 16, 0, 0); } while (0)
; #define PG8_LDA(dst, b, h) do { _Pragma("unroll") for (int m = 0; m < 4; ++m) _Pragma("unroll") for (int k = 0; k < 2; ++k) dst[m][k] = *(const PG8_LAS bf16x8*)(lds + PG8_SA(b, h) + aoff + m * 2048 + k * 1024); } while (0)
; #define PG8_LDB(dst, b, h) do { _Pragma("unroll") for (int n = 0; n < 2; ++n) _Pragma("unroll") for (int k = 0; k < 2; ++k) dst[n][k] = *(const PG8_LAS bf16x8*)(lds + PG8_SB(b, h) + boff + n * 2048 + k * 1024); } while (0)
; #define PG8_MMA(ai, bj, At, Bt) do { __builtin_amdgcn_s_setprio(1); _Pragma("unroll") for (int m = 0; m < 4; ++m) _Pragma("unroll") for (int n = 0; n < 2; ++n) _Pragma("unroll") for (int k = 0; k < 2; ++k) \
;         acc[ai][bj][m][n] = __builtin_amdgcn_mfma_f32_16x16x32_bf16(Bt[n][k], At[m][k], acc[ai][bj][m][n], 0, 0, 0); __builtin_amdgcn_s_setprio(0); } while (0)
; #define PG8_WAIT_V(n) asm volatile("s_waitcnt vmcnt(" #n ")" ::: "memory")
; #define PG8_WAIT_L(n) asm volatile("s_waitcnt lgkmcnt(" #n ")" ::: "memory")
; #define PG8_BAR __builtin_amdgcn_s_barrier()
; #define PG8_SCHED __builtin_amdgcn_sched_barrier(0)
; template <class Epi, class Sched, bool ALIGN_EPI = false, bool SP2 = false>
; __device__ __forceinline__ void gemm_phase(PG8_LAS unsigned char* lds, const Gemm g, const Sched& S, const Epi& E) {
;     ...
;             PG8_WAIT_V(8); PG8_WAIT_L(0); PG8_BAR; PG8_MMA(1, 0, At, B0); PG8_MMA(1, 1, At, B1); PG8_BAR; PG8_SCHED;
;             PG8_LDB(B0, 1, 0); PG8_LDB(B1, 1, 1); PG8_SCHED; PG8_LDA(At, 1, 0); PG8_STAGE(PG8_SA(0, 1), a2 + hstepA, voffA);
;             PG8_WAIT_V(8); PG8_WAIT_L(0); PG8_BAR; PG8_MMA(0, 0, At, B0); PG8_MMA(0, 1, At, B1); PG8_BAR; PG8_SCHED;
	s_waitcnt lgkmcnt(0)
	v_mfma_f32_16x16x32_bf16 v[110:113], v[60:63], v[188:191], v[110:113]
	v_mfma_f32_16x16x32_bf16 v[106:109], v[162:165], v[188:191], v[106:109]
	v_mfma_f32_16x16x32_bf16 v[102:105], v[60:63], v[196:199], v[102:105]
	v_mfma_f32_16x16x32_bf16 v[98:101], v[162:165], v[196:199], v[98:101]
	v_mfma_f32_16x16x32_bf16 v[46:49], v[60:63], v[204:207], v[46:49]
	v_mfma_f32_16x16x32_bf16 v[42:45], v[162:165], v[204:207], v[42:45]
	v_mfma_f32_16x16x32_bf16 v[38:41], v[60:63], v[212:215], v[38:41]
	v_mfma_f32_16x16x32_bf16 v[34:37], v[162:165], v[212:215], v[34:37]
	v_mfma_f32_16x16x32_bf16 v[110:113], v[64:67], v[192:195], v[110:113]
	v_mfma_f32_16x16x32_bf16 v[106:109], v[166:169], v[192:195], v[106:109]
	v_mfma_f32_16x16x32_bf16 v[102:105], v[64:67], v[200:203], v[102:105]
	v_mfma_f32_16x16x32_bf16 v[98:101], v[166:169], v[200:203], v[98:101]
	v_mfma_f32_16x16x32_bf16 v[46:49], v[64:67], v[208:211], v[46:49]
	v_mfma_f32_16x16x32_bf16 v[42:45], v[166:169], v[208:211], v[42:45]
	v_mfma_f32_16x16x32_bf16 v[38:41], v[64:67], v[216:219], v[38:41]
	v_mfma_f32_16x16x32_bf16 v[34:37], v[166:169], v[216:219], v[34:37]
	v_mfma_f32_16x16x32_bf16 v[68:71], v[170:173], v[196:199], v[70:73]
	v_mfma_f32_16x16x32_bf16 v[50:53], v[178:181], v[196:199], v[50:53]
	v_mfma_f32_16x16x32_bf16 v[30:33], v[170:173], v[204:207], v[30:33]
	v_mfma_f32_16x16x32_bf16 v[26:29], v[178:181], v[204:207], v[26:29]
	v_mfma_f32_16x16x32_bf16 v[22:25], v[170:173], v[212:215], v[22:25]
	v_mfma_f32_16x16x32_bf16 v[2:5], v[178:181], v[212:215], v[2:5]
	v_mfma_f32_16x16x32_bf16 v[60:63], v[170:173], v[188:191], v[94:97]
	v_mfma_f32_16x16x32_bf16 v[64:67], v[178:181], v[188:191], v[82:85]
	v_mfma_f32_16x16x32_bf16 v[68:71], v[174:177], v[200:203], v[68:71]
	v_mfma_f32_16x16x32_bf16 v[50:53], v[184:187], v[200:203], v[50:53]
	v_mfma_f32_16x16x32_bf16 v[30:33], v[174:177], v[208:211], v[30:33]
	v_mfma_f32_16x16x32_bf16 v[26:29], v[184:187], v[208:211], v[26:29]
	v_mfma_f32_16x16x32_bf16 v[22:25], v[174:177], v[216:219], v[22:25]
	v_mfma_f32_16x16x32_bf16 v[2:5], v[184:187], v[216:219], v[2:5]
	v_mfma_f32_16x16x32_bf16 v[60:63], v[174:177], v[192:195], v[60:63]
	v_mfma_f32_16x16x32_bf16 v[64:67], v[184:187], v[192:195], v[64:67]
	s_barrier
	s_add_i32 s57, 0, 0x18000
	v_add_u32_e32 v72, s57, v58
	s_add_i32 s58, 0, 0x1c000
	ds_read_b128 v[82:85], v72
	ds_read_b128 v[94:97], v72 offset:1024
	ds_read_b128 v[162:165], v72 offset:2048
	ds_read_b128 v[166:169], v72 offset:3072
	v_add_u32_e32 v72, s58, v58
	ds_read_b128 v[170:173], v72
	ds_read_b128 v[174:177], v72 offset:1024
	ds_read_b128 v[178:181], v72 offset:2048
	ds_read_b128 v[184:187], v72 offset:3072
	s_add_u32 s24, s24, 0xb0000
	s_addc_u32 s25, s25, 0
	s_mov_b32 m0, s44
	ds_read_b128 v[188:191], v59 offset:32768
	ds_read_b128 v[192:195], v59 offset:33792
	ds_read_b128 v[196:199], v59 offset:34816
	ds_read_b128 v[200:203], v59 offset:35840
	ds_read_b128 v[204:207], v59 offset:36864
	ds_read_b128 v[208:211], v59 offset:37888
	ds_read_b128 v[212:215], v59 offset:38912
	ds_read_b128 v[216:219], v59 offset:39936
	global_load_lds_dwordx4 v6, s[24:25]
	s_mov_b32 m0, s45
	s_nop 0
	global_load_lds_dwordx4 v10, s[24:25]
	s_waitcnt vmcnt(8)
	s_waitcnt lgkmcnt(0)
	s_barrier
	s_waitcnt lgkmcnt(0)
	v_mfma_f32_16x16x32_bf16 v[158:161], v[82:85], v[188:191], v[158:161]
	v_mfma_f32_16x16x32_bf16 v[146:149], v[162:165], v[188:191], v[146:149]
	v_mfma_f32_16x16x32_bf16 v[150:153], v[82:85], v[196:199], v[150:153]
	v_mfma_f32_16x16x32_bf16 v[154:157], v[162:165], v[196:199], v[154:157]
	v_mfma_f32_16x16x32_bf16 v[142:145], v[82:85], v[204:207], v[142:145]
	v_mfma_f32_16x16x32_bf16 v[138:141], v[162:165], v[204:207], v[138:141]
	v_mfma_f32_16x16x32_bf16 v[134:137], v[82:85], v[212:215], v[134:137]
	v_mfma_f32_16x16x32_bf16 v[130:133], v[162:165], v[212:215], v[130:133]
	v_mfma_f32_16x16x32_bf16 v[158:161], v[94:97], v[192:195], v[158:161]
	v_mfma_f32_16x16x32_bf16 v[146:149], v[166:169], v[192:195], v[146:149]
	v_mfma_f32_16x16x32_bf16 v[150:153], v[94:97], v[200:203], v[150:153]
	v_mfma_f32_16x16x32_bf16 v[154:157], v[166:169], v[200:203], v[154:157]
	v_mfma_f32_16x16x32_bf16 v[142:145], v[94:97], v[208:211], v[142:145]
	v_mfma_f32_16x16x32_bf16 v[138:141], v[166:169], v[208:211], v[138:141]
	v_mfma_f32_16x16x32_bf16 v[134:137], v[94:97], v[216:219], v[134:137]
	v_mfma_f32_16x16x32_bf16 v[130:133], v[166:169], v[216:219], v[130:133]
	v_mfma_f32_16x16x32_bf16 v[78:81], v[170:173], v[188:191], v[78:81]
	v_mfma_f32_16x16x32_bf16 v[72:75], v[178:181], v[188:191], v[74:77]
	v_mfma_f32_16x16x32_bf16 v[86:89], v[170:173], v[196:199], v[86:89]
	v_mfma_f32_16x16x32_bf16 v[90:93], v[178:181], v[196:199], v[90:93]
	v_mfma_f32_16x16x32_bf16 v[118:121], v[170:173], v[204:207], v[118:121]
	v_mfma_f32_16x16x32_bf16 v[114:117], v[178:181], v[204:207], v[114:117]
	v_mfma_f32_16x16x32_bf16 v[122:125], v[170:173], v[212:215], v[122:125]
	v_mfma_f32_16x16x32_bf16 v[126:129], v[178:181], v[212:215], v[126:129]
	v_mfma_f32_16x16x32_bf16 v[78:81], v[174:177], v[192:195], v[78:81]
	v_mfma_f32_16x16x32_bf16 v[74:77], v[184:187], v[192:195], v[72:75]
	v_mfma_f32_16x16x32_bf16 v[86:89], v[174:177], v[200:203], v[86:89]
	v_mfma_f32_16x16x32_bf16 v[90:93], v[184:187], v[200:203], v[90:93]
	v_mfma_f32_16x16x32_bf16 v[118:121], v[174:177], v[208:211], v[118:121]
	v_mfma_f32_16x16x32_bf16 v[114:117], v[184:187], v[208:211], v[114:117]
	v_mfma_f32_16x16x32_bf16 v[122:125], v[174:177], v[216:219], v[122:125]
	v_mfma_f32_16x16x32_bf16 v[126:129], v[184:187], v[216:219], v[126:129]
	s_barrier
; #define PG8_STAGE(bufoff, gbase, voff) do { _Pragma("unroll") for (int _i = 0; _i < 2; ++_i) \
;         __builtin_amdgcn_global_load_lds((const unsigned*)((const char*)(gbase) + (voff)[_i]), (PG8_LAS unsigned*)(lds + (bufoff) + ldsw + _i * 8192), 16, 0, 0); } while (0)
; #define PG8_LDA(dst, b, h) do { _Pragma("unroll") for (int m = 0; m < 4; ++m) _Pragma("unroll") for (int k = 0; k < 2; ++k) dst[m][k] = *(const PG8_LAS bf16x8*)(lds + PG8_SA(b, h) + aoff + m * 2048 + k * 1024); } while (0)
; #define PG8_MMA(ai, bj, At, Bt) do { __builtin_amdgcn_s_setprio(1); _Pragma("unroll") for (int m = 0; m < 4; ++m) _Pragma("unroll") for (int n = 0; n < 2; ++n) _Pragma("unroll") for (int k = 0; k < 2; ++k) \
;         acc[ai][bj][m][n] = __builtin_amdgcn_mfma_f32_16x16x32_bf16(Bt[n][k], At[m][k], acc[ai][bj][m][n], 0, 0, 0); __builtin_amdgcn_s_setprio(0); } while (0)
; #define PG8_WAIT_V(n) asm volatile("s_waitcnt vmcnt(" #n ")" ::: "memory")
; #define PG8_WAIT_L(n) asm volatile("s_waitcnt lgkmcnt(" #n ")" ::: "memory")
; #define PG8_BAR __builtin_amdgcn_s_barrier()
; #define PG8_SCHED __builtin_amdgcn_sched_barrier(0)
; template <class Epi, class Sched, bool ALIGN_EPI = false, bool SP2 = false>
; __device__ __forceinline__ void gemm_phase(PG8_LAS unsigned char* lds, const Gemm g, const Sched& S, const Epi& E) {
;     ...
;             PG8_LDA(At, 1, 1); PG8_STAGE(PG8_SB(1, 0), b3, voffB); PG8_STAGE(PG8_SB(1, 1), b3 + hstepB, voffB); PG8_STAGE(PG8_SA(1, 0), a3, voffA);
;             PG8_WAIT_V(8); PG8_WAIT_L(0); PG8_BAR; PG8_MMA(1, 0, At, B0); PG8_MMA(1, 1, At, B1); PG8_BAR; PG8_SCHED;
;     ...
; #pragma unroll
;         for (int a = 0; a < 2; ++a)
; #pragma unroll
;             for (int b = 0; b < 2; ++b)
; #pragma unroll
;                 for (int m = 0; m < 4; ++m)
; #pragma unroll
;                     for (int n = 0; n < 2; ++n) acc[a][b][m][n] = (f32x4){0.f, 0.f, 0.f, 0.f};
;         cur = nxt; cA = nA; cB = nB; ++ui;
	s_add_i32 s24, s57, s40
	s_mov_b32 m0, s24
	ds_read_b128 v[188:191], v59 offset:49152
	ds_read_b128 v[192:195], v59 offset:50176
	ds_read_b128 v[196:199], v59 offset:51200
	ds_read_b128 v[200:203], v59 offset:52224
	ds_read_b128 v[204:207], v59 offset:53248
	ds_read_b128 v[208:211], v59 offset:54272
	ds_read_b128 v[212:215], v59 offset:55296
	ds_read_b128 v[216:219], v59 offset:56320
	global_load_lds_dwordx4 v8, s[98:99]
	s_add_i32 m0, s24, 0x2000
	s_add_u32 s22, s22, 0xb0080
	s_addc_u32 s23, s23, 0
	s_add_i32 s24, s58, s40
	global_load_lds_dwordx4 v12, s[98:99]
	s_mov_b32 m0, s24
	s_nop 0
	global_load_lds_dwordx4 v8, s[22:23]
	s_add_i32 m0, s24, 0x2000
	s_nop 0
	global_load_lds_dwordx4 v12, s[22:23]
	s_mov_b32 m0, s47
	s_nop 0
	global_load_lds_dwordx4 v6, s[100:101]
	s_mov_b32 m0, s48
	s_nop 0
	global_load_lds_dwordx4 v10, s[100:101]
	s_waitcnt vmcnt(8)
	s_waitcnt lgkmcnt(0)
	s_barrier
	s_waitcnt lgkmcnt(0)
	v_mfma_f32_16x16x32_bf16 v[110:113], v[82:85], v[188:191], v[110:113]
	v_mfma_f32_16x16x32_bf16 v[106:109], v[162:165], v[188:191], v[106:109]
	v_mfma_f32_16x16x32_bf16 v[102:105], v[82:85], v[196:199], v[102:105]
	v_mfma_f32_16x16x32_bf16 v[98:101], v[162:165], v[196:199], v[98:101]
	v_mfma_f32_16x16x32_bf16 v[46:49], v[82:85], v[204:207], v[46:49]
	v_mfma_f32_16x16x32_bf16 v[42:45], v[162:165], v[204:207], v[42:45]
	v_mfma_f32_16x16x32_bf16 v[38:41], v[82:85], v[212:215], v[38:41]
	v_mfma_f32_16x16x32_bf16 v[34:37], v[162:165], v[212:215], v[34:37]
	v_mfma_f32_16x16x32_bf16 v[110:113], v[94:97], v[192:195], v[110:113]
	v_mfma_f32_16x16x32_bf16 v[106:109], v[166:169], v[192:195], v[106:109]
	v_mfma_f32_16x16x32_bf16 v[102:105], v[94:97], v[200:203], v[102:105]
	v_mfma_f32_16x16x32_bf16 v[98:101], v[166:169], v[200:203], v[98:101]
	v_mfma_f32_16x16x32_bf16 v[46:49], v[94:97], v[208:211], v[46:49]
	v_mfma_f32_16x16x32_bf16 v[42:45], v[166:169], v[208:211], v[42:45]
	v_mfma_f32_16x16x32_bf16 v[38:41], v[94:97], v[216:219], v[38:41]
	v_mfma_f32_16x16x32_bf16 v[34:37], v[166:169], v[216:219], v[34:37]
	v_mfma_f32_16x16x32_bf16 v[60:63], v[170:173], v[188:191], v[60:63]
	v_mfma_f32_16x16x32_bf16 v[94:97], v[174:177], v[192:195], v[60:63]
	v_mfma_f32_16x16x32_bf16 v[60:63], v[178:181], v[188:191], v[64:67]
	v_mfma_f32_16x16x32_bf16 v[82:85], v[184:187], v[192:195], v[60:63]
	v_mfma_f32_16x16x32_bf16 v[60:63], v[170:173], v[196:199], v[68:71]
	v_mfma_f32_16x16x32_bf16 v[50:53], v[178:181], v[196:199], v[50:53]
	v_mfma_f32_16x16x32_bf16 v[30:33], v[170:173], v[204:207], v[30:33]
	v_mfma_f32_16x16x32_bf16 v[26:29], v[178:181], v[204:207], v[26:29]
	v_mfma_f32_16x16x32_bf16 v[22:25], v[170:173], v[212:215], v[22:25]
	v_mfma_f32_16x16x32_bf16 v[2:5], v[178:181], v[212:215], v[2:5]
	v_mfma_f32_16x16x32_bf16 v[70:73], v[174:177], v[200:203], v[60:63]
	v_mfma_f32_16x16x32_bf16 v[50:53], v[184:187], v[200:203], v[50:53]
	v_mfma_f32_16x16x32_bf16 v[30:33], v[174:177], v[208:211], v[30:33]
	v_mfma_f32_16x16x32_bf16 v[26:29], v[184:187], v[208:211], v[26:29]
	v_mfma_f32_16x16x32_bf16 v[22:25], v[174:177], v[216:219], v[22:25]
	v_mfma_f32_16x16x32_bf16 v[2:5], v[184:187], v[216:219], v[2:5]
	s_barrier
	s_add_i32 s56, s56, 2
	s_add_u32 s20, s20, 0x100
	s_addc_u32 s21, s21, 0
	s_cmp_gt_u32 s56, 41
	s_cbranch_scc0 .LBB0_2807
	s_add_u32 s20, s54, 0xffffff00
	s_addc_u32 s21, s55, -1
	s_and_b64 vcc, exec, s[4:5]
	s_cbranch_vccnz .LBB0_2794
	v_mov_b32_e32 v2, 0
	s_mov_b32 s12, s51
	s_mov_b32 s27, s52
	s_mov_b64 s[14:15], s[18:19]
	s_mov_b32 s46, s53
	v_mov_b32_e32 v3, v2
	v_mov_b32_e32 v4, v2
	v_mov_b32_e32 v5, v2
	v_mov_b32_e32 v22, v2
	v_mov_b32_e32 v23, v2
	v_mov_b32_e32 v24, v2
	v_mov_b32_e32 v25, v2
	v_mov_b32_e32 v26, v2
	v_mov_b32_e32 v27, v2
	v_mov_b32_e32 v28, v2
	v_mov_b32_e32 v29, v2
	v_mov_b32_e32 v30, v2
	v_mov_b32_e32 v31, v2
	v_mov_b32_e32 v32, v2
	v_mov_b32_e32 v33, v2
	v_mov_b32_e32 v50, v2
	v_mov_b32_e32 v51, v2
	v_mov_b32_e32 v52, v2
	v_mov_b32_e32 v53, v2
	v_mov_b32_e32 v70, v2
	v_mov_b32_e32 v71, v2
	v_mov_b32_e32 v72, v2
	v_mov_b32_e32 v73, v2
	v_mov_b32_e32 v82, v2
	v_mov_b32_e32 v83, v2
	v_mov_b32_e32 v84, v2
	v_mov_b32_e32 v85, v2
	v_mov_b32_e32 v94, v2
	v_mov_b32_e32 v95, v2
	v_mov_b32_e32 v96, v2
	v_mov_b32_e32 v97, v2
	v_mov_b32_e32 v34, v2
	v_mov_b32_e32 v35, v2
	v_mov_b32_e32 v36, v2
	v_mov_b32_e32 v37, v2
	v_mov_b32_e32 v38, v2
	v_mov_b32_e32 v39, v2
	v_mov_b32_e32 v40, v2
	v_mov_b32_e32 v41, v2
	v_mov_b32_e32 v42, v2
	v_mov_b32_e32 v43, v2
	v_mov_b32_e32 v44, v2
	v_mov_b32_e32 v45, v2
	v_mov_b32_e32 v46, v2
	v_mov_b32_e32 v47, v2
	v_mov_b32_e32 v48, v2
	v_mov_b32_e32 v49, v2
	v_mov_b32_e32 v98, v2
	v_mov_b32_e32 v99, v2
	v_mov_b32_e32 v100, v2
	v_mov_b32_e32 v101, v2
	v_mov_b32_e32 v102, v2
	v_mov_b32_e32 v103, v2
	v_mov_b32_e32 v104, v2
	v_mov_b32_e32 v105, v2
	v_mov_b32_e32 v106, v2
	v_mov_b32_e32 v107, v2
	v_mov_b32_e32 v108, v2
	v_mov_b32_e32 v109, v2
	v_mov_b32_e32 v110, v2
	v_mov_b32_e32 v111, v2
	v_mov_b32_e32 v112, v2
	v_mov_b32_e32 v113, v2
	v_mov_b32_e32 v126, v2
	v_mov_b32_e32 v127, v2
	v_mov_b32_e32 v128, v2
	v_mov_b32_e32 v129, v2
	v_mov_b32_e32 v122, v2
	v_mov_b32_e32 v123, v2
	v_mov_b32_e32 v124, v2
	v_mov_b32_e32 v125, v2
	v_mov_b32_e32 v114, v2
	v_mov_b32_e32 v115, v2
	v_mov_b32_e32 v116, v2
	v_mov_b32_e32 v117, v2
	v_mov_b32_e32 v118, v2
	v_mov_b32_e32 v119, v2
	v_mov_b32_e32 v120, v2
	v_mov_b32_e32 v121, v2
	v_mov_b32_e32 v90, v2
	v_mov_b32_e32 v91, v2
	v_mov_b32_e32 v92, v2
	v_mov_b32_e32 v93, v2
	v_mov_b32_e32 v86, v2
	v_mov_b32_e32 v87, v2
	v_mov_b32_e32 v88, v2
	v_mov_b32_e32 v89, v2
	v_mov_b32_e32 v74, v2
	v_mov_b32_e32 v75, v2
	v_mov_b32_e32 v76, v2
	v_mov_b32_e32 v77, v2
	v_mov_b32_e32 v78, v2
	v_mov_b32_e32 v79, v2
	v_mov_b32_e32 v80, v2
	v_mov_b32_e32 v81, v2
	v_mov_b32_e32 v130, v2
	v_mov_b32_e32 v131, v2
	v_mov_b32_e32 v132, v2
	v_mov_b32_e32 v133, v2
	v_mov_b32_e32 v134, v2
	v_mov_b32_e32 v135, v2
	v_mov_b32_e32 v136, v2
	v_mov_b32_e32 v137, v2
	v_mov_b32_e32 v138, v2
	v_mov_b32_e32 v139, v2
	v_mov_b32_e32 v140, v2
	v_mov_b32_e32 v141, v2
	v_mov_b32_e32 v142, v2
	v_mov_b32_e32 v143, v2
	v_mov_b32_e32 v144, v2
	v_mov_b32_e32 v145, v2
	v_mov_b32_e32 v154, v2
	v_mov_b32_e32 v155, v2
	v_mov_b32_e32 v156, v2
	v_mov_b32_e32 v157, v2
	v_mov_b32_e32 v150, v2
	v_mov_b32_e32 v151, v2
	v_mov_b32_e32 v152, v2
	v_mov_b32_e32 v153, v2
	v_mov_b32_e32 v146, v2
	v_mov_b32_e32 v147, v2
	v_mov_b32_e32 v148, v2
	v_mov_b32_e32 v149, v2
	v_mov_b32_e32 v158, v2
	v_mov_b32_e32 v159, v2
	v_mov_b32_e32 v160, v2
	v_mov_b32_e32 v161, v2
	s_andn2_b64 vcc, exec, s[2:3]
	s_cbranch_vccnz .LBB0_2795
